# compress unit GEMM1: each of the 8 waves walks the K dimension from a different start (8 rotated copies of the unrolled loop) to spread W1 reads over L2 channels
# baseline (speedup 1.0000x reference)
.LBB0_270:
	s_or_b64 exec, exec, s[22:23]
	s_and_b64 s[18:19], s[20:21], exec
	s_mov_b32 s14, 0x5b00000
	s_cselect_b32 s16, s14, 0x5c00000
	v_mov_b32_e32 v6, 0
	v_lshl_add_u64 v[10:11], v[130:131], 0, s[16:17]
	s_mov_b64 s[22:23], 0
	v_mov_b32_e32 v0, v230
	v_mov_b32_e32 v16, v228
	v_mov_b32_e32 v7, v6
	v_mov_b32_e32 v8, v6
	v_mov_b32_e32 v9, v6
	v_mov_b32_e32 v2, v6
	v_mov_b32_e32 v3, v6
	v_mov_b32_e32 v4, v6
	v_mov_b32_e32 v5, v6
	s_waitcnt lgkmcnt(0)
	s_barrier
	v_and_b32_e32 v12, 0x70, v228
	v_add_u32_e32 v13, 16, v228
	v_and_b32_e32 v13, 0x70, v13
	v_xad_u32 v114, v128, v12, v230
	v_xad_u32 v115, v129, v12, v230
	v_xad_u32 v116, v128, v13, v230
	v_xad_u32 v117, v129, v13, v230
	s_mov_b64 s[22:23], 0x10000
	v_lshl_add_u64 v[14:15], v[10:11], 0, s[22:23]
	v_readfirstlane_b32 s22, v146
	s_lshr_b32 s22, s22, 6
	s_cmp_ge_u32 s22, 7
	s_cbranch_scc1 .Lcmp_rot7
	s_cmp_ge_u32 s22, 6
	s_cbranch_scc1 .Lcmp_rot6
	s_cmp_ge_u32 s22, 5
	s_cbranch_scc1 .Lcmp_rot5
	s_cmp_ge_u32 s22, 4
	s_cbranch_scc1 .Lcmp_rot4
	s_cmp_ge_u32 s22, 3
	s_cbranch_scc1 .Lcmp_rot3
	s_cmp_ge_u32 s22, 2
	s_cbranch_scc1 .Lcmp_rot2
	s_cmp_ge_u32 s22, 1
	s_cbranch_scc1 .Lcmp_rot1
	ds_read_b128 v[18:21], v114
	ds_read_b128 v[22:25], v115
	ds_read_b128 v[26:29], v114 offset:128
	ds_read_b128 v[30:33], v115 offset:128
	global_load_dwordx4 v[34:37], v[10:11], off
	global_load_dwordx4 v[38:41], v[14:15], off
	global_load_dwordx4 v[42:45], v[10:11], off offset:64
	global_load_dwordx4 v[46:49], v[14:15], off offset:64
	global_load_dwordx4 v[50:53], v[10:11], off offset:128
	global_load_dwordx4 v[54:57], v[14:15], off offset:128
	global_load_dwordx4 v[58:61], v[10:11], off offset:192
	global_load_dwordx4 v[62:65], v[14:15], off offset:192
	ds_read_b128 v[66:69], v114 offset:256
	ds_read_b128 v[70:73], v115 offset:256
	ds_read_b128 v[74:77], v114 offset:384
	ds_read_b128 v[78:81], v115 offset:384
	global_load_dwordx4 v[82:85], v[10:11], off offset:256
	global_load_dwordx4 v[86:89], v[14:15], off offset:256
	global_load_dwordx4 v[90:93], v[10:11], off offset:320
	global_load_dwordx4 v[94:97], v[14:15], off offset:320
	global_load_dwordx4 v[98:101], v[10:11], off offset:384
	global_load_dwordx4 v[102:105], v[14:15], off offset:384
	global_load_dwordx4 v[106:109], v[10:11], off offset:448
	global_load_dwordx4 v[110:113], v[14:15], off offset:448
	s_waitcnt vmcnt(14) lgkmcnt(7)
	v_mfma_f32_16x16x32_bf16 v[6:9], v[18:21], v[34:37], v[6:9]
	v_mfma_f32_16x16x32_bf16 v[2:5], v[18:21], v[38:41], v[2:5]
	s_waitcnt vmcnt(12) lgkmcnt(6)
	v_mfma_f32_16x16x32_bf16 v[6:9], v[22:25], v[42:45], v[6:9]
	v_mfma_f32_16x16x32_bf16 v[2:5], v[22:25], v[46:49], v[2:5]
	s_waitcnt vmcnt(10) lgkmcnt(5)
	v_mfma_f32_16x16x32_bf16 v[6:9], v[26:29], v[50:53], v[6:9]
	v_mfma_f32_16x16x32_bf16 v[2:5], v[26:29], v[54:57], v[2:5]
	s_waitcnt vmcnt(8) lgkmcnt(4)
	v_mfma_f32_16x16x32_bf16 v[6:9], v[30:33], v[58:61], v[6:9]
	v_mfma_f32_16x16x32_bf16 v[2:5], v[30:33], v[62:65], v[2:5]
	ds_read_b128 v[18:21], v114 offset:512
	ds_read_b128 v[22:25], v115 offset:512
	ds_read_b128 v[26:29], v114 offset:640
	ds_read_b128 v[30:33], v115 offset:640
	global_load_dwordx4 v[34:37], v[10:11], off offset:512
	global_load_dwordx4 v[38:41], v[14:15], off offset:512
	global_load_dwordx4 v[42:45], v[10:11], off offset:576
	global_load_dwordx4 v[46:49], v[14:15], off offset:576
	global_load_dwordx4 v[50:53], v[10:11], off offset:640
	global_load_dwordx4 v[54:57], v[14:15], off offset:640
	global_load_dwordx4 v[58:61], v[10:11], off offset:704
	global_load_dwordx4 v[62:65], v[14:15], off offset:704
	s_waitcnt vmcnt(14) lgkmcnt(7)
	v_mfma_f32_16x16x32_bf16 v[6:9], v[66:69], v[82:85], v[6:9]
	v_mfma_f32_16x16x32_bf16 v[2:5], v[66:69], v[86:89], v[2:5]
	s_waitcnt vmcnt(12) lgkmcnt(6)
	v_mfma_f32_16x16x32_bf16 v[6:9], v[70:73], v[90:93], v[6:9]
	v_mfma_f32_16x16x32_bf16 v[2:5], v[70:73], v[94:97], v[2:5]
	s_waitcnt vmcnt(10) lgkmcnt(5)
	v_mfma_f32_16x16x32_bf16 v[6:9], v[74:77], v[98:101], v[6:9]
	v_mfma_f32_16x16x32_bf16 v[2:5], v[74:77], v[102:105], v[2:5]
	s_waitcnt vmcnt(8) lgkmcnt(4)
	v_mfma_f32_16x16x32_bf16 v[6:9], v[78:81], v[106:109], v[6:9]
	v_mfma_f32_16x16x32_bf16 v[2:5], v[78:81], v[110:113], v[2:5]
	ds_read_b128 v[66:69], v114 offset:768
	ds_read_b128 v[70:73], v115 offset:768
	ds_read_b128 v[74:77], v114 offset:896
	ds_read_b128 v[78:81], v115 offset:896
	global_load_dwordx4 v[82:85], v[10:11], off offset:768
	global_load_dwordx4 v[86:89], v[14:15], off offset:768
	global_load_dwordx4 v[90:93], v[10:11], off offset:832
	global_load_dwordx4 v[94:97], v[14:15], off offset:832
	global_load_dwordx4 v[98:101], v[10:11], off offset:896
	global_load_dwordx4 v[102:105], v[14:15], off offset:896
	global_load_dwordx4 v[106:109], v[10:11], off offset:960
	global_load_dwordx4 v[110:113], v[14:15], off offset:960
	s_waitcnt vmcnt(14) lgkmcnt(7)
	v_mfma_f32_16x16x32_bf16 v[6:9], v[18:21], v[34:37], v[6:9]
	v_mfma_f32_16x16x32_bf16 v[2:5], v[18:21], v[38:41], v[2:5]
	s_waitcnt vmcnt(12) lgkmcnt(6)
	v_mfma_f32_16x16x32_bf16 v[6:9], v[22:25], v[42:45], v[6:9]
	v_mfma_f32_16x16x32_bf16 v[2:5], v[22:25], v[46:49], v[2:5]
	s_waitcnt vmcnt(10) lgkmcnt(5)
	v_mfma_f32_16x16x32_bf16 v[6:9], v[26:29], v[50:53], v[6:9]
	v_mfma_f32_16x16x32_bf16 v[2:5], v[26:29], v[54:57], v[2:5]
	s_waitcnt vmcnt(8) lgkmcnt(4)
	v_mfma_f32_16x16x32_bf16 v[6:9], v[30:33], v[58:61], v[6:9]
	v_mfma_f32_16x16x32_bf16 v[2:5], v[30:33], v[62:65], v[2:5]
	ds_read_b128 v[18:21], v114 offset:1024
	ds_read_b128 v[22:25], v115 offset:1024
	ds_read_b128 v[26:29], v114 offset:1152
	ds_read_b128 v[30:33], v115 offset:1152
	global_load_dwordx4 v[34:37], v[10:11], off offset:1024
	global_load_dwordx4 v[38:41], v[14:15], off offset:1024
	global_load_dwordx4 v[42:45], v[10:11], off offset:1088
	global_load_dwordx4 v[46:49], v[14:15], off offset:1088
	global_load_dwordx4 v[50:53], v[10:11], off offset:1152
	global_load_dwordx4 v[54:57], v[14:15], off offset:1152
	global_load_dwordx4 v[58:61], v[10:11], off offset:1216
	global_load_dwordx4 v[62:65], v[14:15], off offset:1216
	s_waitcnt vmcnt(14) lgkmcnt(7)
	v_mfma_f32_16x16x32_bf16 v[6:9], v[66:69], v[82:85], v[6:9]
	v_mfma_f32_16x16x32_bf16 v[2:5], v[66:69], v[86:89], v[2:5]
	s_waitcnt vmcnt(12) lgkmcnt(6)
	v_mfma_f32_16x16x32_bf16 v[6:9], v[70:73], v[90:93], v[6:9]
	v_mfma_f32_16x16x32_bf16 v[2:5], v[70:73], v[94:97], v[2:5]
	s_waitcnt vmcnt(10) lgkmcnt(5)
	v_mfma_f32_16x16x32_bf16 v[6:9], v[74:77], v[98:101], v[6:9]
	v_mfma_f32_16x16x32_bf16 v[2:5], v[74:77], v[102:105], v[2:5]
	s_waitcnt vmcnt(8) lgkmcnt(4)
	v_mfma_f32_16x16x32_bf16 v[6:9], v[78:81], v[106:109], v[6:9]
	v_mfma_f32_16x16x32_bf16 v[2:5], v[78:81], v[110:113], v[2:5]
	ds_read_b128 v[66:69], v114 offset:1280
	ds_read_b128 v[70:73], v115 offset:1280
	ds_read_b128 v[74:77], v114 offset:1408
	ds_read_b128 v[78:81], v115 offset:1408
	global_load_dwordx4 v[82:85], v[10:11], off offset:1280
	global_load_dwordx4 v[86:89], v[14:15], off offset:1280
	global_load_dwordx4 v[90:93], v[10:11], off offset:1344
	global_load_dwordx4 v[94:97], v[14:15], off offset:1344
	global_load_dwordx4 v[98:101], v[10:11], off offset:1408
	global_load_dwordx4 v[102:105], v[14:15], off offset:1408
	global_load_dwordx4 v[106:109], v[10:11], off offset:1472
	global_load_dwordx4 v[110:113], v[14:15], off offset:1472
	s_waitcnt vmcnt(14) lgkmcnt(7)
	v_mfma_f32_16x16x32_bf16 v[6:9], v[18:21], v[34:37], v[6:9]
	v_mfma_f32_16x16x32_bf16 v[2:5], v[18:21], v[38:41], v[2:5]
	s_waitcnt vmcnt(12) lgkmcnt(6)
	v_mfma_f32_16x16x32_bf16 v[6:9], v[22:25], v[42:45], v[6:9]
	v_mfma_f32_16x16x32_bf16 v[2:5], v[22:25], v[46:49], v[2:5]
	s_waitcnt vmcnt(10) lgkmcnt(5)
	v_mfma_f32_16x16x32_bf16 v[6:9], v[26:29], v[50:53], v[6:9]
	v_mfma_f32_16x16x32_bf16 v[2:5], v[26:29], v[54:57], v[2:5]
	s_waitcnt vmcnt(8) lgkmcnt(4)
	v_mfma_f32_16x16x32_bf16 v[6:9], v[30:33], v[58:61], v[6:9]
	v_mfma_f32_16x16x32_bf16 v[2:5], v[30:33], v[62:65], v[2:5]
	ds_read_b128 v[18:21], v114 offset:1536
	ds_read_b128 v[22:25], v115 offset:1536
	ds_read_b128 v[26:29], v114 offset:1664
	ds_read_b128 v[30:33], v115 offset:1664
	global_load_dwordx4 v[34:37], v[10:11], off offset:1536
	global_load_dwordx4 v[38:41], v[14:15], off offset:1536
	global_load_dwordx4 v[42:45], v[10:11], off offset:1600
	global_load_dwordx4 v[46:49], v[14:15], off offset:1600
	global_load_dwordx4 v[50:53], v[10:11], off offset:1664
	global_load_dwordx4 v[54:57], v[14:15], off offset:1664
	global_load_dwordx4 v[58:61], v[10:11], off offset:1728
	global_load_dwordx4 v[62:65], v[14:15], off offset:1728
	s_waitcnt vmcnt(14) lgkmcnt(7)
	v_mfma_f32_16x16x32_bf16 v[6:9], v[66:69], v[82:85], v[6:9]
	v_mfma_f32_16x16x32_bf16 v[2:5], v[66:69], v[86:89], v[2:5]
	s_waitcnt vmcnt(12) lgkmcnt(6)
	v_mfma_f32_16x16x32_bf16 v[6:9], v[70:73], v[90:93], v[6:9]
	v_mfma_f32_16x16x32_bf16 v[2:5], v[70:73], v[94:97], v[2:5]
	s_waitcnt vmcnt(10) lgkmcnt(5)
	v_mfma_f32_16x16x32_bf16 v[6:9], v[74:77], v[98:101], v[6:9]
	v_mfma_f32_16x16x32_bf16 v[2:5], v[74:77], v[102:105], v[2:5]
	s_waitcnt vmcnt(8) lgkmcnt(4)
	v_mfma_f32_16x16x32_bf16 v[6:9], v[78:81], v[106:109], v[6:9]
	v_mfma_f32_16x16x32_bf16 v[2:5], v[78:81], v[110:113], v[2:5]
	ds_read_b128 v[66:69], v114 offset:1792
	ds_read_b128 v[70:73], v115 offset:1792
	ds_read_b128 v[74:77], v114 offset:1920
	ds_read_b128 v[78:81], v115 offset:1920
	global_load_dwordx4 v[82:85], v[10:11], off offset:1792
	global_load_dwordx4 v[86:89], v[14:15], off offset:1792
	global_load_dwordx4 v[90:93], v[10:11], off offset:1856
	global_load_dwordx4 v[94:97], v[14:15], off offset:1856
	global_load_dwordx4 v[98:101], v[10:11], off offset:1920
	global_load_dwordx4 v[102:105], v[14:15], off offset:1920
	global_load_dwordx4 v[106:109], v[10:11], off offset:1984
	global_load_dwordx4 v[110:113], v[14:15], off offset:1984
	s_waitcnt vmcnt(14) lgkmcnt(7)
	v_mfma_f32_16x16x32_bf16 v[6:9], v[18:21], v[34:37], v[6:9]
	v_mfma_f32_16x16x32_bf16 v[2:5], v[18:21], v[38:41], v[2:5]
	s_waitcnt vmcnt(12) lgkmcnt(6)
	v_mfma_f32_16x16x32_bf16 v[6:9], v[22:25], v[42:45], v[6:9]
	v_mfma_f32_16x16x32_bf16 v[2:5], v[22:25], v[46:49], v[2:5]
	s_waitcnt vmcnt(10) lgkmcnt(5)
	v_mfma_f32_16x16x32_bf16 v[6:9], v[26:29], v[50:53], v[6:9]
	v_mfma_f32_16x16x32_bf16 v[2:5], v[26:29], v[54:57], v[2:5]
	s_waitcnt vmcnt(8) lgkmcnt(4)
	v_mfma_f32_16x16x32_bf16 v[6:9], v[30:33], v[58:61], v[6:9]
	v_mfma_f32_16x16x32_bf16 v[2:5], v[30:33], v[62:65], v[2:5]
	ds_read_b128 v[18:21], v116 offset:2048
	ds_read_b128 v[22:25], v117 offset:2048
	ds_read_b128 v[26:29], v116 offset:2176
	ds_read_b128 v[30:33], v117 offset:2176
	global_load_dwordx4 v[34:37], v[10:11], off offset:2048
	global_load_dwordx4 v[38:41], v[14:15], off offset:2048
	global_load_dwordx4 v[42:45], v[10:11], off offset:2112
	global_load_dwordx4 v[46:49], v[14:15], off offset:2112
	global_load_dwordx4 v[50:53], v[10:11], off offset:2176
	global_load_dwordx4 v[54:57], v[14:15], off offset:2176
	global_load_dwordx4 v[58:61], v[10:11], off offset:2240
	global_load_dwordx4 v[62:65], v[14:15], off offset:2240
	s_waitcnt vmcnt(14) lgkmcnt(7)
	v_mfma_f32_16x16x32_bf16 v[6:9], v[66:69], v[82:85], v[6:9]
	v_mfma_f32_16x16x32_bf16 v[2:5], v[66:69], v[86:89], v[2:5]
	s_waitcnt vmcnt(12) lgkmcnt(6)
	v_mfma_f32_16x16x32_bf16 v[6:9], v[70:73], v[90:93], v[6:9]
	v_mfma_f32_16x16x32_bf16 v[2:5], v[70:73], v[94:97], v[2:5]
	s_waitcnt vmcnt(10) lgkmcnt(5)
	v_mfma_f32_16x16x32_bf16 v[6:9], v[74:77], v[98:101], v[6:9]
	v_mfma_f32_16x16x32_bf16 v[2:5], v[74:77], v[102:105], v[2:5]
	s_waitcnt vmcnt(8) lgkmcnt(4)
	v_mfma_f32_16x16x32_bf16 v[6:9], v[78:81], v[106:109], v[6:9]
	v_mfma_f32_16x16x32_bf16 v[2:5], v[78:81], v[110:113], v[2:5]
	ds_read_b128 v[66:69], v116 offset:2304
	ds_read_b128 v[70:73], v117 offset:2304
	ds_read_b128 v[74:77], v116 offset:2432
	ds_read_b128 v[78:81], v117 offset:2432
	global_load_dwordx4 v[82:85], v[10:11], off offset:2304
	global_load_dwordx4 v[86:89], v[14:15], off offset:2304
	global_load_dwordx4 v[90:93], v[10:11], off offset:2368
	global_load_dwordx4 v[94:97], v[14:15], off offset:2368
	global_load_dwordx4 v[98:101], v[10:11], off offset:2432
	global_load_dwordx4 v[102:105], v[14:15], off offset:2432
	global_load_dwordx4 v[106:109], v[10:11], off offset:2496
	global_load_dwordx4 v[110:113], v[14:15], off offset:2496
	s_waitcnt vmcnt(14) lgkmcnt(7)
	v_mfma_f32_16x16x32_bf16 v[6:9], v[18:21], v[34:37], v[6:9]
	v_mfma_f32_16x16x32_bf16 v[2:5], v[18:21], v[38:41], v[2:5]
	s_waitcnt vmcnt(12) lgkmcnt(6)
	v_mfma_f32_16x16x32_bf16 v[6:9], v[22:25], v[42:45], v[6:9]
	v_mfma_f32_16x16x32_bf16 v[2:5], v[22:25], v[46:49], v[2:5]
	s_waitcnt vmcnt(10) lgkmcnt(5)
	v_mfma_f32_16x16x32_bf16 v[6:9], v[26:29], v[50:53], v[6:9]
	v_mfma_f32_16x16x32_bf16 v[2:5], v[26:29], v[54:57], v[2:5]
	s_waitcnt vmcnt(8) lgkmcnt(4)
	v_mfma_f32_16x16x32_bf16 v[6:9], v[30:33], v[58:61], v[6:9]
	v_mfma_f32_16x16x32_bf16 v[2:5], v[30:33], v[62:65], v[2:5]
	ds_read_b128 v[18:21], v116 offset:2560
	ds_read_b128 v[22:25], v117 offset:2560
	ds_read_b128 v[26:29], v116 offset:2688
	ds_read_b128 v[30:33], v117 offset:2688
	global_load_dwordx4 v[34:37], v[10:11], off offset:2560
	global_load_dwordx4 v[38:41], v[14:15], off offset:2560
	global_load_dwordx4 v[42:45], v[10:11], off offset:2624
	global_load_dwordx4 v[46:49], v[14:15], off offset:2624
	global_load_dwordx4 v[50:53], v[10:11], off offset:2688
	global_load_dwordx4 v[54:57], v[14:15], off offset:2688
	global_load_dwordx4 v[58:61], v[10:11], off offset:2752
	global_load_dwordx4 v[62:65], v[14:15], off offset:2752
	s_waitcnt vmcnt(14) lgkmcnt(7)
	v_mfma_f32_16x16x32_bf16 v[6:9], v[66:69], v[82:85], v[6:9]
	v_mfma_f32_16x16x32_bf16 v[2:5], v[66:69], v[86:89], v[2:5]
	s_waitcnt vmcnt(12) lgkmcnt(6)
	v_mfma_f32_16x16x32_bf16 v[6:9], v[70:73], v[90:93], v[6:9]
	v_mfma_f32_16x16x32_bf16 v[2:5], v[70:73], v[94:97], v[2:5]
	s_waitcnt vmcnt(10) lgkmcnt(5)
	v_mfma_f32_16x16x32_bf16 v[6:9], v[74:77], v[98:101], v[6:9]
	v_mfma_f32_16x16x32_bf16 v[2:5], v[74:77], v[102:105], v[2:5]
	s_waitcnt vmcnt(8) lgkmcnt(4)
	v_mfma_f32_16x16x32_bf16 v[6:9], v[78:81], v[106:109], v[6:9]
	v_mfma_f32_16x16x32_bf16 v[2:5], v[78:81], v[110:113], v[2:5]
	ds_read_b128 v[66:69], v116 offset:2816
	ds_read_b128 v[70:73], v117 offset:2816
	ds_read_b128 v[74:77], v116 offset:2944
	ds_read_b128 v[78:81], v117 offset:2944
	global_load_dwordx4 v[82:85], v[10:11], off offset:2816
	global_load_dwordx4 v[86:89], v[14:15], off offset:2816
	global_load_dwordx4 v[90:93], v[10:11], off offset:2880
	global_load_dwordx4 v[94:97], v[14:15], off offset:2880
	global_load_dwordx4 v[98:101], v[10:11], off offset:2944
	global_load_dwordx4 v[102:105], v[14:15], off offset:2944
	global_load_dwordx4 v[106:109], v[10:11], off offset:3008
	global_load_dwordx4 v[110:113], v[14:15], off offset:3008
	s_waitcnt vmcnt(14) lgkmcnt(7)
	v_mfma_f32_16x16x32_bf16 v[6:9], v[18:21], v[34:37], v[6:9]
	v_mfma_f32_16x16x32_bf16 v[2:5], v[18:21], v[38:41], v[2:5]
	s_waitcnt vmcnt(12) lgkmcnt(6)
	v_mfma_f32_16x16x32_bf16 v[6:9], v[22:25], v[42:45], v[6:9]
	v_mfma_f32_16x16x32_bf16 v[2:5], v[22:25], v[46:49], v[2:5]
	s_waitcnt vmcnt(10) lgkmcnt(5)
	v_mfma_f32_16x16x32_bf16 v[6:9], v[26:29], v[50:53], v[6:9]
	v_mfma_f32_16x16x32_bf16 v[2:5], v[26:29], v[54:57], v[2:5]
	s_waitcnt vmcnt(8) lgkmcnt(4)
	v_mfma_f32_16x16x32_bf16 v[6:9], v[30:33], v[58:61], v[6:9]
	v_mfma_f32_16x16x32_bf16 v[2:5], v[30:33], v[62:65], v[2:5]
	ds_read_b128 v[18:21], v116 offset:3072
	ds_read_b128 v[22:25], v117 offset:3072
	ds_read_b128 v[26:29], v116 offset:3200
	ds_read_b128 v[30:33], v117 offset:3200
	global_load_dwordx4 v[34:37], v[10:11], off offset:3072
	global_load_dwordx4 v[38:41], v[14:15], off offset:3072
	global_load_dwordx4 v[42:45], v[10:11], off offset:3136
	global_load_dwordx4 v[46:49], v[14:15], off offset:3136
	global_load_dwordx4 v[50:53], v[10:11], off offset:3200
	global_load_dwordx4 v[54:57], v[14:15], off offset:3200
	global_load_dwordx4 v[58:61], v[10:11], off offset:3264
	global_load_dwordx4 v[62:65], v[14:15], off offset:3264
	s_waitcnt vmcnt(14) lgkmcnt(7)
	v_mfma_f32_16x16x32_bf16 v[6:9], v[66:69], v[82:85], v[6:9]
	v_mfma_f32_16x16x32_bf16 v[2:5], v[66:69], v[86:89], v[2:5]
	s_waitcnt vmcnt(12) lgkmcnt(6)
	v_mfma_f32_16x16x32_bf16 v[6:9], v[70:73], v[90:93], v[6:9]
	v_mfma_f32_16x16x32_bf16 v[2:5], v[70:73], v[94:97], v[2:5]
	s_waitcnt vmcnt(10) lgkmcnt(5)
	v_mfma_f32_16x16x32_bf16 v[6:9], v[74:77], v[98:101], v[6:9]
	v_mfma_f32_16x16x32_bf16 v[2:5], v[74:77], v[102:105], v[2:5]
	s_waitcnt vmcnt(8) lgkmcnt(4)
	v_mfma_f32_16x16x32_bf16 v[6:9], v[78:81], v[106:109], v[6:9]
	v_mfma_f32_16x16x32_bf16 v[2:5], v[78:81], v[110:113], v[2:5]
	ds_read_b128 v[66:69], v116 offset:3328
	ds_read_b128 v[70:73], v117 offset:3328
	ds_read_b128 v[74:77], v116 offset:3456
	ds_read_b128 v[78:81], v117 offset:3456
	global_load_dwordx4 v[82:85], v[10:11], off offset:3328
	global_load_dwordx4 v[86:89], v[14:15], off offset:3328
	global_load_dwordx4 v[90:93], v[10:11], off offset:3392
	global_load_dwordx4 v[94:97], v[14:15], off offset:3392
	global_load_dwordx4 v[98:101], v[10:11], off offset:3456
	global_load_dwordx4 v[102:105], v[14:15], off offset:3456
	global_load_dwordx4 v[106:109], v[10:11], off offset:3520
	global_load_dwordx4 v[110:113], v[14:15], off offset:3520
	s_waitcnt vmcnt(14) lgkmcnt(7)
	v_mfma_f32_16x16x32_bf16 v[6:9], v[18:21], v[34:37], v[6:9]
	v_mfma_f32_16x16x32_bf16 v[2:5], v[18:21], v[38:41], v[2:5]
	s_waitcnt vmcnt(12) lgkmcnt(6)
	v_mfma_f32_16x16x32_bf16 v[6:9], v[22:25], v[42:45], v[6:9]
	v_mfma_f32_16x16x32_bf16 v[2:5], v[22:25], v[46:49], v[2:5]
	s_waitcnt vmcnt(10) lgkmcnt(5)
	v_mfma_f32_16x16x32_bf16 v[6:9], v[26:29], v[50:53], v[6:9]
	v_mfma_f32_16x16x32_bf16 v[2:5], v[26:29], v[54:57], v[2:5]
	s_waitcnt vmcnt(8) lgkmcnt(4)
	v_mfma_f32_16x16x32_bf16 v[6:9], v[30:33], v[58:61], v[6:9]
	v_mfma_f32_16x16x32_bf16 v[2:5], v[30:33], v[62:65], v[2:5]
	ds_read_b128 v[18:21], v116 offset:3584
	ds_read_b128 v[22:25], v117 offset:3584
	ds_read_b128 v[26:29], v116 offset:3712
	ds_read_b128 v[30:33], v117 offset:3712
	global_load_dwordx4 v[34:37], v[10:11], off offset:3584
	global_load_dwordx4 v[38:41], v[14:15], off offset:3584
	global_load_dwordx4 v[42:45], v[10:11], off offset:3648
	global_load_dwordx4 v[46:49], v[14:15], off offset:3648
	global_load_dwordx4 v[50:53], v[10:11], off offset:3712
	global_load_dwordx4 v[54:57], v[14:15], off offset:3712
	global_load_dwordx4 v[58:61], v[10:11], off offset:3776
	global_load_dwordx4 v[62:65], v[14:15], off offset:3776
	s_waitcnt vmcnt(14) lgkmcnt(7)
	v_mfma_f32_16x16x32_bf16 v[6:9], v[66:69], v[82:85], v[6:9]
	v_mfma_f32_16x16x32_bf16 v[2:5], v[66:69], v[86:89], v[2:5]
	s_waitcnt vmcnt(12) lgkmcnt(6)
	v_mfma_f32_16x16x32_bf16 v[6:9], v[70:73], v[90:93], v[6:9]
	v_mfma_f32_16x16x32_bf16 v[2:5], v[70:73], v[94:97], v[2:5]
	s_waitcnt vmcnt(10) lgkmcnt(5)
	v_mfma_f32_16x16x32_bf16 v[6:9], v[74:77], v[98:101], v[6:9]
	v_mfma_f32_16x16x32_bf16 v[2:5], v[74:77], v[102:105], v[2:5]
	s_waitcnt vmcnt(8) lgkmcnt(4)
	v_mfma_f32_16x16x32_bf16 v[6:9], v[78:81], v[106:109], v[6:9]
	v_mfma_f32_16x16x32_bf16 v[2:5], v[78:81], v[110:113], v[2:5]
	ds_read_b128 v[66:69], v116 offset:3840
	ds_read_b128 v[70:73], v117 offset:3840
	ds_read_b128 v[74:77], v116 offset:3968
	ds_read_b128 v[78:81], v117 offset:3968
	global_load_dwordx4 v[82:85], v[10:11], off offset:3840
	global_load_dwordx4 v[86:89], v[14:15], off offset:3840
	global_load_dwordx4 v[90:93], v[10:11], off offset:3904
	global_load_dwordx4 v[94:97], v[14:15], off offset:3904
	global_load_dwordx4 v[98:101], v[10:11], off offset:3968
	global_load_dwordx4 v[102:105], v[14:15], off offset:3968
	global_load_dwordx4 v[106:109], v[10:11], off offset:4032
	global_load_dwordx4 v[110:113], v[14:15], off offset:4032
	s_waitcnt vmcnt(14) lgkmcnt(7)
	v_mfma_f32_16x16x32_bf16 v[6:9], v[18:21], v[34:37], v[6:9]
	v_mfma_f32_16x16x32_bf16 v[2:5], v[18:21], v[38:41], v[2:5]
	s_waitcnt vmcnt(12) lgkmcnt(6)
	v_mfma_f32_16x16x32_bf16 v[6:9], v[22:25], v[42:45], v[6:9]
	v_mfma_f32_16x16x32_bf16 v[2:5], v[22:25], v[46:49], v[2:5]
	s_waitcnt vmcnt(10) lgkmcnt(5)
	v_mfma_f32_16x16x32_bf16 v[6:9], v[26:29], v[50:53], v[6:9]
	v_mfma_f32_16x16x32_bf16 v[2:5], v[26:29], v[54:57], v[2:5]
	s_waitcnt vmcnt(8) lgkmcnt(4)
	v_mfma_f32_16x16x32_bf16 v[6:9], v[30:33], v[58:61], v[6:9]
	v_mfma_f32_16x16x32_bf16 v[2:5], v[30:33], v[62:65], v[2:5]
	s_waitcnt vmcnt(6) lgkmcnt(3)
	v_mfma_f32_16x16x32_bf16 v[6:9], v[66:69], v[82:85], v[6:9]
	v_mfma_f32_16x16x32_bf16 v[2:5], v[66:69], v[86:89], v[2:5]
	s_waitcnt vmcnt(4) lgkmcnt(2)
	v_mfma_f32_16x16x32_bf16 v[6:9], v[70:73], v[90:93], v[6:9]
	v_mfma_f32_16x16x32_bf16 v[2:5], v[70:73], v[94:97], v[2:5]
	s_waitcnt vmcnt(2) lgkmcnt(1)
	v_mfma_f32_16x16x32_bf16 v[6:9], v[74:77], v[98:101], v[6:9]
	v_mfma_f32_16x16x32_bf16 v[2:5], v[74:77], v[102:105], v[2:5]
	s_waitcnt vmcnt(0) lgkmcnt(0)
	v_mfma_f32_16x16x32_bf16 v[6:9], v[78:81], v[106:109], v[6:9]
	v_mfma_f32_16x16x32_bf16 v[2:5], v[78:81], v[110:113], v[2:5]
	s_branch .Lcmp_done
.Lcmp_rot1:
	ds_read_b128 v[18:21], v114 offset:512
	ds_read_b128 v[22:25], v115 offset:512
	ds_read_b128 v[26:29], v114 offset:640
	ds_read_b128 v[30:33], v115 offset:640
	global_load_dwordx4 v[34:37], v[10:11], off offset:512
	global_load_dwordx4 v[38:41], v[14:15], off offset:512
	global_load_dwordx4 v[42:45], v[10:11], off offset:576
	global_load_dwordx4 v[46:49], v[14:15], off offset:576
	global_load_dwordx4 v[50:53], v[10:11], off offset:640
	global_load_dwordx4 v[54:57], v[14:15], off offset:640
	global_load_dwordx4 v[58:61], v[10:11], off offset:704
	global_load_dwordx4 v[62:65], v[14:15], off offset:704
	ds_read_b128 v[66:69], v114 offset:768
	ds_read_b128 v[70:73], v115 offset:768
	ds_read_b128 v[74:77], v114 offset:896
	ds_read_b128 v[78:81], v115 offset:896
	global_load_dwordx4 v[82:85], v[10:11], off offset:768
	global_load_dwordx4 v[86:89], v[14:15], off offset:768
	global_load_dwordx4 v[90:93], v[10:11], off offset:832
	global_load_dwordx4 v[94:97], v[14:15], off offset:832
	global_load_dwordx4 v[98:101], v[10:11], off offset:896
	global_load_dwordx4 v[102:105], v[14:15], off offset:896
	global_load_dwordx4 v[106:109], v[10:11], off offset:960
	global_load_dwordx4 v[110:113], v[14:15], off offset:960
	s_waitcnt vmcnt(14) lgkmcnt(7)
	v_mfma_f32_16x16x32_bf16 v[6:9], v[18:21], v[34:37], v[6:9]
	v_mfma_f32_16x16x32_bf16 v[2:5], v[18:21], v[38:41], v[2:5]
	s_waitcnt vmcnt(12) lgkmcnt(6)
	v_mfma_f32_16x16x32_bf16 v[6:9], v[22:25], v[42:45], v[6:9]
	v_mfma_f32_16x16x32_bf16 v[2:5], v[22:25], v[46:49], v[2:5]
	s_waitcnt vmcnt(10) lgkmcnt(5)
	v_mfma_f32_16x16x32_bf16 v[6:9], v[26:29], v[50:53], v[6:9]
	v_mfma_f32_16x16x32_bf16 v[2:5], v[26:29], v[54:57], v[2:5]
	s_waitcnt vmcnt(8) lgkmcnt(4)
	v_mfma_f32_16x16x32_bf16 v[6:9], v[30:33], v[58:61], v[6:9]
	v_mfma_f32_16x16x32_bf16 v[2:5], v[30:33], v[62:65], v[2:5]
	ds_read_b128 v[18:21], v114 offset:1024
	ds_read_b128 v[22:25], v115 offset:1024
	ds_read_b128 v[26:29], v114 offset:1152
	ds_read_b128 v[30:33], v115 offset:1152
	global_load_dwordx4 v[34:37], v[10:11], off offset:1024
	global_load_dwordx4 v[38:41], v[14:15], off offset:1024
	global_load_dwordx4 v[42:45], v[10:11], off offset:1088
	global_load_dwordx4 v[46:49], v[14:15], off offset:1088
	global_load_dwordx4 v[50:53], v[10:11], off offset:1152
	global_load_dwordx4 v[54:57], v[14:15], off offset:1152
	global_load_dwordx4 v[58:61], v[10:11], off offset:1216
	global_load_dwordx4 v[62:65], v[14:15], off offset:1216
	s_waitcnt vmcnt(14) lgkmcnt(7)
	v_mfma_f32_16x16x32_bf16 v[6:9], v[66:69], v[82:85], v[6:9]
	v_mfma_f32_16x16x32_bf16 v[2:5], v[66:69], v[86:89], v[2:5]
	s_waitcnt vmcnt(12) lgkmcnt(6)
	v_mfma_f32_16x16x32_bf16 v[6:9], v[70:73], v[90:93], v[6:9]
	v_mfma_f32_16x16x32_bf16 v[2:5], v[70:73], v[94:97], v[2:5]
	s_waitcnt vmcnt(10) lgkmcnt(5)
	v_mfma_f32_16x16x32_bf16 v[6:9], v[74:77], v[98:101], v[6:9]
	v_mfma_f32_16x16x32_bf16 v[2:5], v[74:77], v[102:105], v[2:5]
	s_waitcnt vmcnt(8) lgkmcnt(4)
	v_mfma_f32_16x16x32_bf16 v[6:9], v[78:81], v[106:109], v[6:9]
	v_mfma_f32_16x16x32_bf16 v[2:5], v[78:81], v[110:113], v[2:5]
	ds_read_b128 v[66:69], v114 offset:1280
	ds_read_b128 v[70:73], v115 offset:1280
	ds_read_b128 v[74:77], v114 offset:1408
	ds_read_b128 v[78:81], v115 offset:1408
	global_load_dwordx4 v[82:85], v[10:11], off offset:1280
	global_load_dwordx4 v[86:89], v[14:15], off offset:1280
	global_load_dwordx4 v[90:93], v[10:11], off offset:1344
	global_load_dwordx4 v[94:97], v[14:15], off offset:1344
	global_load_dwordx4 v[98:101], v[10:11], off offset:1408
	global_load_dwordx4 v[102:105], v[14:15], off offset:1408
	global_load_dwordx4 v[106:109], v[10:11], off offset:1472
	global_load_dwordx4 v[110:113], v[14:15], off offset:1472
	s_waitcnt vmcnt(14) lgkmcnt(7)
	v_mfma_f32_16x16x32_bf16 v[6:9], v[18:21], v[34:37], v[6:9]
	v_mfma_f32_16x16x32_bf16 v[2:5], v[18:21], v[38:41], v[2:5]
	s_waitcnt vmcnt(12) lgkmcnt(6)
	v_mfma_f32_16x16x32_bf16 v[6:9], v[22:25], v[42:45], v[6:9]
	v_mfma_f32_16x16x32_bf16 v[2:5], v[22:25], v[46:49], v[2:5]
	s_waitcnt vmcnt(10) lgkmcnt(5)
	v_mfma_f32_16x16x32_bf16 v[6:9], v[26:29], v[50:53], v[6:9]
	v_mfma_f32_16x16x32_bf16 v[2:5], v[26:29], v[54:57], v[2:5]
	s_waitcnt vmcnt(8) lgkmcnt(4)
	v_mfma_f32_16x16x32_bf16 v[6:9], v[30:33], v[58:61], v[6:9]
	v_mfma_f32_16x16x32_bf16 v[2:5], v[30:33], v[62:65], v[2:5]
	ds_read_b128 v[18:21], v114 offset:1536
	ds_read_b128 v[22:25], v115 offset:1536
	ds_read_b128 v[26:29], v114 offset:1664
	ds_read_b128 v[30:33], v115 offset:1664
	global_load_dwordx4 v[34:37], v[10:11], off offset:1536
	global_load_dwordx4 v[38:41], v[14:15], off offset:1536
	global_load_dwordx4 v[42:45], v[10:11], off offset:1600
	global_load_dwordx4 v[46:49], v[14:15], off offset:1600
	global_load_dwordx4 v[50:53], v[10:11], off offset:1664
	global_load_dwordx4 v[54:57], v[14:15], off offset:1664
	global_load_dwordx4 v[58:61], v[10:11], off offset:1728
	global_load_dwordx4 v[62:65], v[14:15], off offset:1728
	s_waitcnt vmcnt(14) lgkmcnt(7)
	v_mfma_f32_16x16x32_bf16 v[6:9], v[66:69], v[82:85], v[6:9]
	v_mfma_f32_16x16x32_bf16 v[2:5], v[66:69], v[86:89], v[2:5]
	s_waitcnt vmcnt(12) lgkmcnt(6)
	v_mfma_f32_16x16x32_bf16 v[6:9], v[70:73], v[90:93], v[6:9]
	v_mfma_f32_16x16x32_bf16 v[2:5], v[70:73], v[94:97], v[2:5]
	s_waitcnt vmcnt(10) lgkmcnt(5)
	v_mfma_f32_16x16x32_bf16 v[6:9], v[74:77], v[98:101], v[6:9]
	v_mfma_f32_16x16x32_bf16 v[2:5], v[74:77], v[102:105], v[2:5]
	s_waitcnt vmcnt(8) lgkmcnt(4)
	v_mfma_f32_16x16x32_bf16 v[6:9], v[78:81], v[106:109], v[6:9]
	v_mfma_f32_16x16x32_bf16 v[2:5], v[78:81], v[110:113], v[2:5]
	ds_read_b128 v[66:69], v114 offset:1792
	ds_read_b128 v[70:73], v115 offset:1792
	ds_read_b128 v[74:77], v114 offset:1920
	ds_read_b128 v[78:81], v115 offset:1920
	global_load_dwordx4 v[82:85], v[10:11], off offset:1792
	global_load_dwordx4 v[86:89], v[14:15], off offset:1792
	global_load_dwordx4 v[90:93], v[10:11], off offset:1856
	global_load_dwordx4 v[94:97], v[14:15], off offset:1856
	global_load_dwordx4 v[98:101], v[10:11], off offset:1920
	global_load_dwordx4 v[102:105], v[14:15], off offset:1920
	global_load_dwordx4 v[106:109], v[10:11], off offset:1984
	global_load_dwordx4 v[110:113], v[14:15], off offset:1984
	s_waitcnt vmcnt(14) lgkmcnt(7)
	v_mfma_f32_16x16x32_bf16 v[6:9], v[18:21], v[34:37], v[6:9]
	v_mfma_f32_16x16x32_bf16 v[2:5], v[18:21], v[38:41], v[2:5]
	s_waitcnt vmcnt(12) lgkmcnt(6)
	v_mfma_f32_16x16x32_bf16 v[6:9], v[22:25], v[42:45], v[6:9]
	v_mfma_f32_16x16x32_bf16 v[2:5], v[22:25], v[46:49], v[2:5]
	s_waitcnt vmcnt(10) lgkmcnt(5)
	v_mfma_f32_16x16x32_bf16 v[6:9], v[26:29], v[50:53], v[6:9]
	v_mfma_f32_16x16x32_bf16 v[2:5], v[26:29], v[54:57], v[2:5]
	s_waitcnt vmcnt(8) lgkmcnt(4)
	v_mfma_f32_16x16x32_bf16 v[6:9], v[30:33], v[58:61], v[6:9]
	v_mfma_f32_16x16x32_bf16 v[2:5], v[30:33], v[62:65], v[2:5]
	ds_read_b128 v[18:21], v116 offset:2048
	ds_read_b128 v[22:25], v117 offset:2048
	ds_read_b128 v[26:29], v116 offset:2176
	ds_read_b128 v[30:33], v117 offset:2176
	global_load_dwordx4 v[34:37], v[10:11], off offset:2048
	global_load_dwordx4 v[38:41], v[14:15], off offset:2048
	global_load_dwordx4 v[42:45], v[10:11], off offset:2112
	global_load_dwordx4 v[46:49], v[14:15], off offset:2112
	global_load_dwordx4 v[50:53], v[10:11], off offset:2176
	global_load_dwordx4 v[54:57], v[14:15], off offset:2176
	global_load_dwordx4 v[58:61], v[10:11], off offset:2240
	global_load_dwordx4 v[62:65], v[14:15], off offset:2240
	s_waitcnt vmcnt(14) lgkmcnt(7)
	v_mfma_f32_16x16x32_bf16 v[6:9], v[66:69], v[82:85], v[6:9]
	v_mfma_f32_16x16x32_bf16 v[2:5], v[66:69], v[86:89], v[2:5]
	s_waitcnt vmcnt(12) lgkmcnt(6)
	v_mfma_f32_16x16x32_bf16 v[6:9], v[70:73], v[90:93], v[6:9]
	v_mfma_f32_16x16x32_bf16 v[2:5], v[70:73], v[94:97], v[2:5]
	s_waitcnt vmcnt(10) lgkmcnt(5)
	v_mfma_f32_16x16x32_bf16 v[6:9], v[74:77], v[98:101], v[6:9]
	v_mfma_f32_16x16x32_bf16 v[2:5], v[74:77], v[102:105], v[2:5]
	s_waitcnt vmcnt(8) lgkmcnt(4)
	v_mfma_f32_16x16x32_bf16 v[6:9], v[78:81], v[106:109], v[6:9]
	v_mfma_f32_16x16x32_bf16 v[2:5], v[78:81], v[110:113], v[2:5]
	ds_read_b128 v[66:69], v116 offset:2304
	ds_read_b128 v[70:73], v117 offset:2304
	ds_read_b128 v[74:77], v116 offset:2432
	ds_read_b128 v[78:81], v117 offset:2432
	global_load_dwordx4 v[82:85], v[10:11], off offset:2304
	global_load_dwordx4 v[86:89], v[14:15], off offset:2304
	global_load_dwordx4 v[90:93], v[10:11], off offset:2368
	global_load_dwordx4 v[94:97], v[14:15], off offset:2368
	global_load_dwordx4 v[98:101], v[10:11], off offset:2432
	global_load_dwordx4 v[102:105], v[14:15], off offset:2432
	global_load_dwordx4 v[106:109], v[10:11], off offset:2496
	global_load_dwordx4 v[110:113], v[14:15], off offset:2496
	s_waitcnt vmcnt(14) lgkmcnt(7)
	v_mfma_f32_16x16x32_bf16 v[6:9], v[18:21], v[34:37], v[6:9]
	v_mfma_f32_16x16x32_bf16 v[2:5], v[18:21], v[38:41], v[2:5]
	s_waitcnt vmcnt(12) lgkmcnt(6)
	v_mfma_f32_16x16x32_bf16 v[6:9], v[22:25], v[42:45], v[6:9]
	v_mfma_f32_16x16x32_bf16 v[2:5], v[22:25], v[46:49], v[2:5]
	s_waitcnt vmcnt(10) lgkmcnt(5)
	v_mfma_f32_16x16x32_bf16 v[6:9], v[26:29], v[50:53], v[6:9]
	v_mfma_f32_16x16x32_bf16 v[2:5], v[26:29], v[54:57], v[2:5]
	s_waitcnt vmcnt(8) lgkmcnt(4)
	v_mfma_f32_16x16x32_bf16 v[6:9], v[30:33], v[58:61], v[6:9]
	v_mfma_f32_16x16x32_bf16 v[2:5], v[30:33], v[62:65], v[2:5]
	ds_read_b128 v[18:21], v116 offset:2560
	ds_read_b128 v[22:25], v117 offset:2560
	ds_read_b128 v[26:29], v116 offset:2688
	ds_read_b128 v[30:33], v117 offset:2688
	global_load_dwordx4 v[34:37], v[10:11], off offset:2560
	global_load_dwordx4 v[38:41], v[14:15], off offset:2560
	global_load_dwordx4 v[42:45], v[10:11], off offset:2624
	global_load_dwordx4 v[46:49], v[14:15], off offset:2624
	global_load_dwordx4 v[50:53], v[10:11], off offset:2688
	global_load_dwordx4 v[54:57], v[14:15], off offset:2688
	global_load_dwordx4 v[58:61], v[10:11], off offset:2752
	global_load_dwordx4 v[62:65], v[14:15], off offset:2752
	s_waitcnt vmcnt(14) lgkmcnt(7)
	v_mfma_f32_16x16x32_bf16 v[6:9], v[66:69], v[82:85], v[6:9]
	v_mfma_f32_16x16x32_bf16 v[2:5], v[66:69], v[86:89], v[2:5]
	s_waitcnt vmcnt(12) lgkmcnt(6)
	v_mfma_f32_16x16x32_bf16 v[6:9], v[70:73], v[90:93], v[6:9]
	v_mfma_f32_16x16x32_bf16 v[2:5], v[70:73], v[94:97], v[2:5]
	s_waitcnt vmcnt(10) lgkmcnt(5)
	v_mfma_f32_16x16x32_bf16 v[6:9], v[74:77], v[98:101], v[6:9]
	v_mfma_f32_16x16x32_bf16 v[2:5], v[74:77], v[102:105], v[2:5]
	s_waitcnt vmcnt(8) lgkmcnt(4)
	v_mfma_f32_16x16x32_bf16 v[6:9], v[78:81], v[106:109], v[6:9]
	v_mfma_f32_16x16x32_bf16 v[2:5], v[78:81], v[110:113], v[2:5]
	ds_read_b128 v[66:69], v116 offset:2816
	ds_read_b128 v[70:73], v117 offset:2816
	ds_read_b128 v[74:77], v116 offset:2944
	ds_read_b128 v[78:81], v117 offset:2944
	global_load_dwordx4 v[82:85], v[10:11], off offset:2816
	global_load_dwordx4 v[86:89], v[14:15], off offset:2816
	global_load_dwordx4 v[90:93], v[10:11], off offset:2880
	global_load_dwordx4 v[94:97], v[14:15], off offset:2880
	global_load_dwordx4 v[98:101], v[10:11], off offset:2944
	global_load_dwordx4 v[102:105], v[14:15], off offset:2944
	global_load_dwordx4 v[106:109], v[10:11], off offset:3008
	global_load_dwordx4 v[110:113], v[14:15], off offset:3008
	s_waitcnt vmcnt(14) lgkmcnt(7)
	v_mfma_f32_16x16x32_bf16 v[6:9], v[18:21], v[34:37], v[6:9]
	v_mfma_f32_16x16x32_bf16 v[2:5], v[18:21], v[38:41], v[2:5]
	s_waitcnt vmcnt(12) lgkmcnt(6)
	v_mfma_f32_16x16x32_bf16 v[6:9], v[22:25], v[42:45], v[6:9]
	v_mfma_f32_16x16x32_bf16 v[2:5], v[22:25], v[46:49], v[2:5]
	s_waitcnt vmcnt(10) lgkmcnt(5)
	v_mfma_f32_16x16x32_bf16 v[6:9], v[26:29], v[50:53], v[6:9]
	v_mfma_f32_16x16x32_bf16 v[2:5], v[26:29], v[54:57], v[2:5]
	s_waitcnt vmcnt(8) lgkmcnt(4)
	v_mfma_f32_16x16x32_bf16 v[6:9], v[30:33], v[58:61], v[6:9]
	v_mfma_f32_16x16x32_bf16 v[2:5], v[30:33], v[62:65], v[2:5]
	ds_read_b128 v[18:21], v116 offset:3072
	ds_read_b128 v[22:25], v117 offset:3072
	ds_read_b128 v[26:29], v116 offset:3200
	ds_read_b128 v[30:33], v117 offset:3200
	global_load_dwordx4 v[34:37], v[10:11], off offset:3072
	global_load_dwordx4 v[38:41], v[14:15], off offset:3072
	global_load_dwordx4 v[42:45], v[10:11], off offset:3136
	global_load_dwordx4 v[46:49], v[14:15], off offset:3136
	global_load_dwordx4 v[50:53], v[10:11], off offset:3200
	global_load_dwordx4 v[54:57], v[14:15], off offset:3200
	global_load_dwordx4 v[58:61], v[10:11], off offset:3264
	global_load_dwordx4 v[62:65], v[14:15], off offset:3264
	s_waitcnt vmcnt(14) lgkmcnt(7)
	v_mfma_f32_16x16x32_bf16 v[6:9], v[66:69], v[82:85], v[6:9]
	v_mfma_f32_16x16x32_bf16 v[2:5], v[66:69], v[86:89], v[2:5]
	s_waitcnt vmcnt(12) lgkmcnt(6)
	v_mfma_f32_16x16x32_bf16 v[6:9], v[70:73], v[90:93], v[6:9]
	v_mfma_f32_16x16x32_bf16 v[2:5], v[70:73], v[94:97], v[2:5]
	s_waitcnt vmcnt(10) lgkmcnt(5)
	v_mfma_f32_16x16x32_bf16 v[6:9], v[74:77], v[98:101], v[6:9]
	v_mfma_f32_16x16x32_bf16 v[2:5], v[74:77], v[102:105], v[2:5]
	s_waitcnt vmcnt(8) lgkmcnt(4)
	v_mfma_f32_16x16x32_bf16 v[6:9], v[78:81], v[106:109], v[6:9]
	v_mfma_f32_16x16x32_bf16 v[2:5], v[78:81], v[110:113], v[2:5]
	ds_read_b128 v[66:69], v116 offset:3328
	ds_read_b128 v[70:73], v117 offset:3328
	ds_read_b128 v[74:77], v116 offset:3456
	ds_read_b128 v[78:81], v117 offset:3456
	global_load_dwordx4 v[82:85], v[10:11], off offset:3328
	global_load_dwordx4 v[86:89], v[14:15], off offset:3328
	global_load_dwordx4 v[90:93], v[10:11], off offset:3392
	global_load_dwordx4 v[94:97], v[14:15], off offset:3392
	global_load_dwordx4 v[98:101], v[10:11], off offset:3456
	global_load_dwordx4 v[102:105], v[14:15], off offset:3456
	global_load_dwordx4 v[106:109], v[10:11], off offset:3520
	global_load_dwordx4 v[110:113], v[14:15], off offset:3520
	s_waitcnt vmcnt(14) lgkmcnt(7)
	v_mfma_f32_16x16x32_bf16 v[6:9], v[18:21], v[34:37], v[6:9]
	v_mfma_f32_16x16x32_bf16 v[2:5], v[18:21], v[38:41], v[2:5]
	s_waitcnt vmcnt(12) lgkmcnt(6)
	v_mfma_f32_16x16x32_bf16 v[6:9], v[22:25], v[42:45], v[6:9]
	v_mfma_f32_16x16x32_bf16 v[2:5], v[22:25], v[46:49], v[2:5]
	s_waitcnt vmcnt(10) lgkmcnt(5)
	v_mfma_f32_16x16x32_bf16 v[6:9], v[26:29], v[50:53], v[6:9]
	v_mfma_f32_16x16x32_bf16 v[2:5], v[26:29], v[54:57], v[2:5]
	s_waitcnt vmcnt(8) lgkmcnt(4)
	v_mfma_f32_16x16x32_bf16 v[6:9], v[30:33], v[58:61], v[6:9]
	v_mfma_f32_16x16x32_bf16 v[2:5], v[30:33], v[62:65], v[2:5]
	ds_read_b128 v[18:21], v116 offset:3584
	ds_read_b128 v[22:25], v117 offset:3584
	ds_read_b128 v[26:29], v116 offset:3712
	ds_read_b128 v[30:33], v117 offset:3712
	global_load_dwordx4 v[34:37], v[10:11], off offset:3584
	global_load_dwordx4 v[38:41], v[14:15], off offset:3584
	global_load_dwordx4 v[42:45], v[10:11], off offset:3648
	global_load_dwordx4 v[46:49], v[14:15], off offset:3648
	global_load_dwordx4 v[50:53], v[10:11], off offset:3712
	global_load_dwordx4 v[54:57], v[14:15], off offset:3712
	global_load_dwordx4 v[58:61], v[10:11], off offset:3776
	global_load_dwordx4 v[62:65], v[14:15], off offset:3776
	s_waitcnt vmcnt(14) lgkmcnt(7)
	v_mfma_f32_16x16x32_bf16 v[6:9], v[66:69], v[82:85], v[6:9]
	v_mfma_f32_16x16x32_bf16 v[2:5], v[66:69], v[86:89], v[2:5]
	s_waitcnt vmcnt(12) lgkmcnt(6)
	v_mfma_f32_16x16x32_bf16 v[6:9], v[70:73], v[90:93], v[6:9]
	v_mfma_f32_16x16x32_bf16 v[2:5], v[70:73], v[94:97], v[2:5]
	s_waitcnt vmcnt(10) lgkmcnt(5)
	v_mfma_f32_16x16x32_bf16 v[6:9], v[74:77], v[98:101], v[6:9]
	v_mfma_f32_16x16x32_bf16 v[2:5], v[74:77], v[102:105], v[2:5]
	s_waitcnt vmcnt(8) lgkmcnt(4)
	v_mfma_f32_16x16x32_bf16 v[6:9], v[78:81], v[106:109], v[6:9]
	v_mfma_f32_16x16x32_bf16 v[2:5], v[78:81], v[110:113], v[2:5]
	ds_read_b128 v[66:69], v116 offset:3840
	ds_read_b128 v[70:73], v117 offset:3840
	ds_read_b128 v[74:77], v116 offset:3968
	ds_read_b128 v[78:81], v117 offset:3968
	global_load_dwordx4 v[82:85], v[10:11], off offset:3840
	global_load_dwordx4 v[86:89], v[14:15], off offset:3840
	global_load_dwordx4 v[90:93], v[10:11], off offset:3904
	global_load_dwordx4 v[94:97], v[14:15], off offset:3904
	global_load_dwordx4 v[98:101], v[10:11], off offset:3968
	global_load_dwordx4 v[102:105], v[14:15], off offset:3968
	global_load_dwordx4 v[106:109], v[10:11], off offset:4032
	global_load_dwordx4 v[110:113], v[14:15], off offset:4032
	s_waitcnt vmcnt(14) lgkmcnt(7)
	v_mfma_f32_16x16x32_bf16 v[6:9], v[18:21], v[34:37], v[6:9]
	v_mfma_f32_16x16x32_bf16 v[2:5], v[18:21], v[38:41], v[2:5]
	s_waitcnt vmcnt(12) lgkmcnt(6)
	v_mfma_f32_16x16x32_bf16 v[6:9], v[22:25], v[42:45], v[6:9]
	v_mfma_f32_16x16x32_bf16 v[2:5], v[22:25], v[46:49], v[2:5]
	s_waitcnt vmcnt(10) lgkmcnt(5)
	v_mfma_f32_16x16x32_bf16 v[6:9], v[26:29], v[50:53], v[6:9]
	v_mfma_f32_16x16x32_bf16 v[2:5], v[26:29], v[54:57], v[2:5]
	s_waitcnt vmcnt(8) lgkmcnt(4)
	v_mfma_f32_16x16x32_bf16 v[6:9], v[30:33], v[58:61], v[6:9]
	v_mfma_f32_16x16x32_bf16 v[2:5], v[30:33], v[62:65], v[2:5]
	ds_read_b128 v[18:21], v114
	ds_read_b128 v[22:25], v115
	ds_read_b128 v[26:29], v114 offset:128
	ds_read_b128 v[30:33], v115 offset:128
	global_load_dwordx4 v[34:37], v[10:11], off
	global_load_dwordx4 v[38:41], v[14:15], off
	global_load_dwordx4 v[42:45], v[10:11], off offset:64
	global_load_dwordx4 v[46:49], v[14:15], off offset:64
	global_load_dwordx4 v[50:53], v[10:11], off offset:128
	global_load_dwordx4 v[54:57], v[14:15], off offset:128
	global_load_dwordx4 v[58:61], v[10:11], off offset:192
	global_load_dwordx4 v[62:65], v[14:15], off offset:192
	s_waitcnt vmcnt(14) lgkmcnt(7)
	v_mfma_f32_16x16x32_bf16 v[6:9], v[66:69], v[82:85], v[6:9]
	v_mfma_f32_16x16x32_bf16 v[2:5], v[66:69], v[86:89], v[2:5]
	s_waitcnt vmcnt(12) lgkmcnt(6)
	v_mfma_f32_16x16x32_bf16 v[6:9], v[70:73], v[90:93], v[6:9]
	v_mfma_f32_16x16x32_bf16 v[2:5], v[70:73], v[94:97], v[2:5]
	s_waitcnt vmcnt(10) lgkmcnt(5)
	v_mfma_f32_16x16x32_bf16 v[6:9], v[74:77], v[98:101], v[6:9]
	v_mfma_f32_16x16x32_bf16 v[2:5], v[74:77], v[102:105], v[2:5]
	s_waitcnt vmcnt(8) lgkmcnt(4)
	v_mfma_f32_16x16x32_bf16 v[6:9], v[78:81], v[106:109], v[6:9]
	v_mfma_f32_16x16x32_bf16 v[2:5], v[78:81], v[110:113], v[2:5]
	ds_read_b128 v[66:69], v114 offset:256
	ds_read_b128 v[70:73], v115 offset:256
	ds_read_b128 v[74:77], v114 offset:384
	ds_read_b128 v[78:81], v115 offset:384
	global_load_dwordx4 v[82:85], v[10:11], off offset:256
	global_load_dwordx4 v[86:89], v[14:15], off offset:256
	global_load_dwordx4 v[90:93], v[10:11], off offset:320
	global_load_dwordx4 v[94:97], v[14:15], off offset:320
	global_load_dwordx4 v[98:101], v[10:11], off offset:384
	global_load_dwordx4 v[102:105], v[14:15], off offset:384
	global_load_dwordx4 v[106:109], v[10:11], off offset:448
	global_load_dwordx4 v[110:113], v[14:15], off offset:448
	s_waitcnt vmcnt(14) lgkmcnt(7)
	v_mfma_f32_16x16x32_bf16 v[6:9], v[18:21], v[34:37], v[6:9]
	v_mfma_f32_16x16x32_bf16 v[2:5], v[18:21], v[38:41], v[2:5]
	s_waitcnt vmcnt(12) lgkmcnt(6)
	v_mfma_f32_16x16x32_bf16 v[6:9], v[22:25], v[42:45], v[6:9]
	v_mfma_f32_16x16x32_bf16 v[2:5], v[22:25], v[46:49], v[2:5]
	s_waitcnt vmcnt(10) lgkmcnt(5)
	v_mfma_f32_16x16x32_bf16 v[6:9], v[26:29], v[50:53], v[6:9]
	v_mfma_f32_16x16x32_bf16 v[2:5], v[26:29], v[54:57], v[2:5]
	s_waitcnt vmcnt(8) lgkmcnt(4)
	v_mfma_f32_16x16x32_bf16 v[6:9], v[30:33], v[58:61], v[6:9]
	v_mfma_f32_16x16x32_bf16 v[2:5], v[30:33], v[62:65], v[2:5]
	s_waitcnt vmcnt(6) lgkmcnt(3)
	v_mfma_f32_16x16x32_bf16 v[6:9], v[66:69], v[82:85], v[6:9]
	v_mfma_f32_16x16x32_bf16 v[2:5], v[66:69], v[86:89], v[2:5]
	s_waitcnt vmcnt(4) lgkmcnt(2)
	v_mfma_f32_16x16x32_bf16 v[6:9], v[70:73], v[90:93], v[6:9]
	v_mfma_f32_16x16x32_bf16 v[2:5], v[70:73], v[94:97], v[2:5]
	s_waitcnt vmcnt(2) lgkmcnt(1)
	v_mfma_f32_16x16x32_bf16 v[6:9], v[74:77], v[98:101], v[6:9]
	v_mfma_f32_16x16x32_bf16 v[2:5], v[74:77], v[102:105], v[2:5]
	s_waitcnt vmcnt(0) lgkmcnt(0)
	v_mfma_f32_16x16x32_bf16 v[6:9], v[78:81], v[106:109], v[6:9]
	v_mfma_f32_16x16x32_bf16 v[2:5], v[78:81], v[110:113], v[2:5]
	s_branch .Lcmp_done
.Lcmp_rot2:
	ds_read_b128 v[18:21], v114 offset:1024
	ds_read_b128 v[22:25], v115 offset:1024
	ds_read_b128 v[26:29], v114 offset:1152
	ds_read_b128 v[30:33], v115 offset:1152
	global_load_dwordx4 v[34:37], v[10:11], off offset:1024
	global_load_dwordx4 v[38:41], v[14:15], off offset:1024
	global_load_dwordx4 v[42:45], v[10:11], off offset:1088
	global_load_dwordx4 v[46:49], v[14:15], off offset:1088
	global_load_dwordx4 v[50:53], v[10:11], off offset:1152
	global_load_dwordx4 v[54:57], v[14:15], off offset:1152
	global_load_dwordx4 v[58:61], v[10:11], off offset:1216
	global_load_dwordx4 v[62:65], v[14:15], off offset:1216
	ds_read_b128 v[66:69], v114 offset:1280
	ds_read_b128 v[70:73], v115 offset:1280
	ds_read_b128 v[74:77], v114 offset:1408
	ds_read_b128 v[78:81], v115 offset:1408
	global_load_dwordx4 v[82:85], v[10:11], off offset:1280
	global_load_dwordx4 v[86:89], v[14:15], off offset:1280
	global_load_dwordx4 v[90:93], v[10:11], off offset:1344
	global_load_dwordx4 v[94:97], v[14:15], off offset:1344
	global_load_dwordx4 v[98:101], v[10:11], off offset:1408
	global_load_dwordx4 v[102:105], v[14:15], off offset:1408
	global_load_dwordx4 v[106:109], v[10:11], off offset:1472
	global_load_dwordx4 v[110:113], v[14:15], off offset:1472
	s_waitcnt vmcnt(14) lgkmcnt(7)
	v_mfma_f32_16x16x32_bf16 v[6:9], v[18:21], v[34:37], v[6:9]
	v_mfma_f32_16x16x32_bf16 v[2:5], v[18:21], v[38:41], v[2:5]
	s_waitcnt vmcnt(12) lgkmcnt(6)
	v_mfma_f32_16x16x32_bf16 v[6:9], v[22:25], v[42:45], v[6:9]
	v_mfma_f32_16x16x32_bf16 v[2:5], v[22:25], v[46:49], v[2:5]
	s_waitcnt vmcnt(10) lgkmcnt(5)
	v_mfma_f32_16x16x32_bf16 v[6:9], v[26:29], v[50:53], v[6:9]
	v_mfma_f32_16x16x32_bf16 v[2:5], v[26:29], v[54:57], v[2:5]
	s_waitcnt vmcnt(8) lgkmcnt(4)
	v_mfma_f32_16x16x32_bf16 v[6:9], v[30:33], v[58:61], v[6:9]
	v_mfma_f32_16x16x32_bf16 v[2:5], v[30:33], v[62:65], v[2:5]
	ds_read_b128 v[18:21], v114 offset:1536
	ds_read_b128 v[22:25], v115 offset:1536
	ds_read_b128 v[26:29], v114 offset:1664
	ds_read_b128 v[30:33], v115 offset:1664
	global_load_dwordx4 v[34:37], v[10:11], off offset:1536
	global_load_dwordx4 v[38:41], v[14:15], off offset:1536
	global_load_dwordx4 v[42:45], v[10:11], off offset:1600
	global_load_dwordx4 v[46:49], v[14:15], off offset:1600
	global_load_dwordx4 v[50:53], v[10:11], off offset:1664
	global_load_dwordx4 v[54:57], v[14:15], off offset:1664
	global_load_dwordx4 v[58:61], v[10:11], off offset:1728
	global_load_dwordx4 v[62:65], v[14:15], off offset:1728
	s_waitcnt vmcnt(14) lgkmcnt(7)
	v_mfma_f32_16x16x32_bf16 v[6:9], v[66:69], v[82:85], v[6:9]
	v_mfma_f32_16x16x32_bf16 v[2:5], v[66:69], v[86:89], v[2:5]
	s_waitcnt vmcnt(12) lgkmcnt(6)
	v_mfma_f32_16x16x32_bf16 v[6:9], v[70:73], v[90:93], v[6:9]
	v_mfma_f32_16x16x32_bf16 v[2:5], v[70:73], v[94:97], v[2:5]
	s_waitcnt vmcnt(10) lgkmcnt(5)
	v_mfma_f32_16x16x32_bf16 v[6:9], v[74:77], v[98:101], v[6:9]
	v_mfma_f32_16x16x32_bf16 v[2:5], v[74:77], v[102:105], v[2:5]
	s_waitcnt vmcnt(8) lgkmcnt(4)
	v_mfma_f32_16x16x32_bf16 v[6:9], v[78:81], v[106:109], v[6:9]
	v_mfma_f32_16x16x32_bf16 v[2:5], v[78:81], v[110:113], v[2:5]
	ds_read_b128 v[66:69], v114 offset:1792
	ds_read_b128 v[70:73], v115 offset:1792
	ds_read_b128 v[74:77], v114 offset:1920
	ds_read_b128 v[78:81], v115 offset:1920
	global_load_dwordx4 v[82:85], v[10:11], off offset:1792
	global_load_dwordx4 v[86:89], v[14:15], off offset:1792
	global_load_dwordx4 v[90:93], v[10:11], off offset:1856
	global_load_dwordx4 v[94:97], v[14:15], off offset:1856
	global_load_dwordx4 v[98:101], v[10:11], off offset:1920
	global_load_dwordx4 v[102:105], v[14:15], off offset:1920
	global_load_dwordx4 v[106:109], v[10:11], off offset:1984
	global_load_dwordx4 v[110:113], v[14:15], off offset:1984
	s_waitcnt vmcnt(14) lgkmcnt(7)
	v_mfma_f32_16x16x32_bf16 v[6:9], v[18:21], v[34:37], v[6:9]
	v_mfma_f32_16x16x32_bf16 v[2:5], v[18:21], v[38:41], v[2:5]
	s_waitcnt vmcnt(12) lgkmcnt(6)
	v_mfma_f32_16x16x32_bf16 v[6:9], v[22:25], v[42:45], v[6:9]
	v_mfma_f32_16x16x32_bf16 v[2:5], v[22:25], v[46:49], v[2:5]
	s_waitcnt vmcnt(10) lgkmcnt(5)
	v_mfma_f32_16x16x32_bf16 v[6:9], v[26:29], v[50:53], v[6:9]
	v_mfma_f32_16x16x32_bf16 v[2:5], v[26:29], v[54:57], v[2:5]
	s_waitcnt vmcnt(8) lgkmcnt(4)
	v_mfma_f32_16x16x32_bf16 v[6:9], v[30:33], v[58:61], v[6:9]
	v_mfma_f32_16x16x32_bf16 v[2:5], v[30:33], v[62:65], v[2:5]
	ds_read_b128 v[18:21], v116 offset:2048
	ds_read_b128 v[22:25], v117 offset:2048
	ds_read_b128 v[26:29], v116 offset:2176
	ds_read_b128 v[30:33], v117 offset:2176
	global_load_dwordx4 v[34:37], v[10:11], off offset:2048
	global_load_dwordx4 v[38:41], v[14:15], off offset:2048
	global_load_dwordx4 v[42:45], v[10:11], off offset:2112
	global_load_dwordx4 v[46:49], v[14:15], off offset:2112
	global_load_dwordx4 v[50:53], v[10:11], off offset:2176
	global_load_dwordx4 v[54:57], v[14:15], off offset:2176
	global_load_dwordx4 v[58:61], v[10:11], off offset:2240
	global_load_dwordx4 v[62:65], v[14:15], off offset:2240
	s_waitcnt vmcnt(14) lgkmcnt(7)
	v_mfma_f32_16x16x32_bf16 v[6:9], v[66:69], v[82:85], v[6:9]
	v_mfma_f32_16x16x32_bf16 v[2:5], v[66:69], v[86:89], v[2:5]
	s_waitcnt vmcnt(12) lgkmcnt(6)
	v_mfma_f32_16x16x32_bf16 v[6:9], v[70:73], v[90:93], v[6:9]
	v_mfma_f32_16x16x32_bf16 v[2:5], v[70:73], v[94:97], v[2:5]
	s_waitcnt vmcnt(10) lgkmcnt(5)
	v_mfma_f32_16x16x32_bf16 v[6:9], v[74:77], v[98:101], v[6:9]
	v_mfma_f32_16x16x32_bf16 v[2:5], v[74:77], v[102:105], v[2:5]
	s_waitcnt vmcnt(8) lgkmcnt(4)
	v_mfma_f32_16x16x32_bf16 v[6:9], v[78:81], v[106:109], v[6:9]
	v_mfma_f32_16x16x32_bf16 v[2:5], v[78:81], v[110:113], v[2:5]
	ds_read_b128 v[66:69], v116 offset:2304
	ds_read_b128 v[70:73], v117 offset:2304
	ds_read_b128 v[74:77], v116 offset:2432
	ds_read_b128 v[78:81], v117 offset:2432
	global_load_dwordx4 v[82:85], v[10:11], off offset:2304
	global_load_dwordx4 v[86:89], v[14:15], off offset:2304
	global_load_dwordx4 v[90:93], v[10:11], off offset:2368
	global_load_dwordx4 v[94:97], v[14:15], off offset:2368
	global_load_dwordx4 v[98:101], v[10:11], off offset:2432
	global_load_dwordx4 v[102:105], v[14:15], off offset:2432
	global_load_dwordx4 v[106:109], v[10:11], off offset:2496
	global_load_dwordx4 v[110:113], v[14:15], off offset:2496
	s_waitcnt vmcnt(14) lgkmcnt(7)
	v_mfma_f32_16x16x32_bf16 v[6:9], v[18:21], v[34:37], v[6:9]
	v_mfma_f32_16x16x32_bf16 v[2:5], v[18:21], v[38:41], v[2:5]
	s_waitcnt vmcnt(12) lgkmcnt(6)
	v_mfma_f32_16x16x32_bf16 v[6:9], v[22:25], v[42:45], v[6:9]
	v_mfma_f32_16x16x32_bf16 v[2:5], v[22:25], v[46:49], v[2:5]
	s_waitcnt vmcnt(10) lgkmcnt(5)
	v_mfma_f32_16x16x32_bf16 v[6:9], v[26:29], v[50:53], v[6:9]
	v_mfma_f32_16x16x32_bf16 v[2:5], v[26:29], v[54:57], v[2:5]
	s_waitcnt vmcnt(8) lgkmcnt(4)
	v_mfma_f32_16x16x32_bf16 v[6:9], v[30:33], v[58:61], v[6:9]
	v_mfma_f32_16x16x32_bf16 v[2:5], v[30:33], v[62:65], v[2:5]
	ds_read_b128 v[18:21], v116 offset:2560
	ds_read_b128 v[22:25], v117 offset:2560
	ds_read_b128 v[26:29], v116 offset:2688
	ds_read_b128 v[30:33], v117 offset:2688
	global_load_dwordx4 v[34:37], v[10:11], off offset:2560
	global_load_dwordx4 v[38:41], v[14:15], off offset:2560
	global_load_dwordx4 v[42:45], v[10:11], off offset:2624
	global_load_dwordx4 v[46:49], v[14:15], off offset:2624
	global_load_dwordx4 v[50:53], v[10:11], off offset:2688
	global_load_dwordx4 v[54:57], v[14:15], off offset:2688
	global_load_dwordx4 v[58:61], v[10:11], off offset:2752
	global_load_dwordx4 v[62:65], v[14:15], off offset:2752
	s_waitcnt vmcnt(14) lgkmcnt(7)
	v_mfma_f32_16x16x32_bf16 v[6:9], v[66:69], v[82:85], v[6:9]
	v_mfma_f32_16x16x32_bf16 v[2:5], v[66:69], v[86:89], v[2:5]
	s_waitcnt vmcnt(12) lgkmcnt(6)
	v_mfma_f32_16x16x32_bf16 v[6:9], v[70:73], v[90:93], v[6:9]
	v_mfma_f32_16x16x32_bf16 v[2:5], v[70:73], v[94:97], v[2:5]
	s_waitcnt vmcnt(10) lgkmcnt(5)
	v_mfma_f32_16x16x32_bf16 v[6:9], v[74:77], v[98:101], v[6:9]
	v_mfma_f32_16x16x32_bf16 v[2:5], v[74:77], v[102:105], v[2:5]
	s_waitcnt vmcnt(8) lgkmcnt(4)
	v_mfma_f32_16x16x32_bf16 v[6:9], v[78:81], v[106:109], v[6:9]
	v_mfma_f32_16x16x32_bf16 v[2:5], v[78:81], v[110:113], v[2:5]
	ds_read_b128 v[66:69], v116 offset:2816
	ds_read_b128 v[70:73], v117 offset:2816
	ds_read_b128 v[74:77], v116 offset:2944
	ds_read_b128 v[78:81], v117 offset:2944
	global_load_dwordx4 v[82:85], v[10:11], off offset:2816
	global_load_dwordx4 v[86:89], v[14:15], off offset:2816
	global_load_dwordx4 v[90:93], v[10:11], off offset:2880
	global_load_dwordx4 v[94:97], v[14:15], off offset:2880
	global_load_dwordx4 v[98:101], v[10:11], off offset:2944
	global_load_dwordx4 v[102:105], v[14:15], off offset:2944
	global_load_dwordx4 v[106:109], v[10:11], off offset:3008
	global_load_dwordx4 v[110:113], v[14:15], off offset:3008
	s_waitcnt vmcnt(14) lgkmcnt(7)
	v_mfma_f32_16x16x32_bf16 v[6:9], v[18:21], v[34:37], v[6:9]
	v_mfma_f32_16x16x32_bf16 v[2:5], v[18:21], v[38:41], v[2:5]
	s_waitcnt vmcnt(12) lgkmcnt(6)
	v_mfma_f32_16x16x32_bf16 v[6:9], v[22:25], v[42:45], v[6:9]
	v_mfma_f32_16x16x32_bf16 v[2:5], v[22:25], v[46:49], v[2:5]
	s_waitcnt vmcnt(10) lgkmcnt(5)
	v_mfma_f32_16x16x32_bf16 v[6:9], v[26:29], v[50:53], v[6:9]
	v_mfma_f32_16x16x32_bf16 v[2:5], v[26:29], v[54:57], v[2:5]
	s_waitcnt vmcnt(8) lgkmcnt(4)
	v_mfma_f32_16x16x32_bf16 v[6:9], v[30:33], v[58:61], v[6:9]
	v_mfma_f32_16x16x32_bf16 v[2:5], v[30:33], v[62:65], v[2:5]
	ds_read_b128 v[18:21], v116 offset:3072
	ds_read_b128 v[22:25], v117 offset:3072
	ds_read_b128 v[26:29], v116 offset:3200
	ds_read_b128 v[30:33], v117 offset:3200
	global_load_dwordx4 v[34:37], v[10:11], off offset:3072
	global_load_dwordx4 v[38:41], v[14:15], off offset:3072
	global_load_dwordx4 v[42:45], v[10:11], off offset:3136
	global_load_dwordx4 v[46:49], v[14:15], off offset:3136
	global_load_dwordx4 v[50:53], v[10:11], off offset:3200
	global_load_dwordx4 v[54:57], v[14:15], off offset:3200
	global_load_dwordx4 v[58:61], v[10:11], off offset:3264
	global_load_dwordx4 v[62:65], v[14:15], off offset:3264
	s_waitcnt vmcnt(14) lgkmcnt(7)
	v_mfma_f32_16x16x32_bf16 v[6:9], v[66:69], v[82:85], v[6:9]
	v_mfma_f32_16x16x32_bf16 v[2:5], v[66:69], v[86:89], v[2:5]
	s_waitcnt vmcnt(12) lgkmcnt(6)
	v_mfma_f32_16x16x32_bf16 v[6:9], v[70:73], v[90:93], v[6:9]
	v_mfma_f32_16x16x32_bf16 v[2:5], v[70:73], v[94:97], v[2:5]
	s_waitcnt vmcnt(10) lgkmcnt(5)
	v_mfma_f32_16x16x32_bf16 v[6:9], v[74:77], v[98:101], v[6:9]
	v_mfma_f32_16x16x32_bf16 v[2:5], v[74:77], v[102:105], v[2:5]
	s_waitcnt vmcnt(8) lgkmcnt(4)
	v_mfma_f32_16x16x32_bf16 v[6:9], v[78:81], v[106:109], v[6:9]
	v_mfma_f32_16x16x32_bf16 v[2:5], v[78:81], v[110:113], v[2:5]
	ds_read_b128 v[66:69], v116 offset:3328
	ds_read_b128 v[70:73], v117 offset:3328
	ds_read_b128 v[74:77], v116 offset:3456
	ds_read_b128 v[78:81], v117 offset:3456
	global_load_dwordx4 v[82:85], v[10:11], off offset:3328
	global_load_dwordx4 v[86:89], v[14:15], off offset:3328
	global_load_dwordx4 v[90:93], v[10:11], off offset:3392
	global_load_dwordx4 v[94:97], v[14:15], off offset:3392
	global_load_dwordx4 v[98:101], v[10:11], off offset:3456
	global_load_dwordx4 v[102:105], v[14:15], off offset:3456
	global_load_dwordx4 v[106:109], v[10:11], off offset:3520
	global_load_dwordx4 v[110:113], v[14:15], off offset:3520
	s_waitcnt vmcnt(14) lgkmcnt(7)
	v_mfma_f32_16x16x32_bf16 v[6:9], v[18:21], v[34:37], v[6:9]
	v_mfma_f32_16x16x32_bf16 v[2:5], v[18:21], v[38:41], v[2:5]
	s_waitcnt vmcnt(12) lgkmcnt(6)
	v_mfma_f32_16x16x32_bf16 v[6:9], v[22:25], v[42:45], v[6:9]
	v_mfma_f32_16x16x32_bf16 v[2:5], v[22:25], v[46:49], v[2:5]
	s_waitcnt vmcnt(10) lgkmcnt(5)
	v_mfma_f32_16x16x32_bf16 v[6:9], v[26:29], v[50:53], v[6:9]
	v_mfma_f32_16x16x32_bf16 v[2:5], v[26:29], v[54:57], v[2:5]
	s_waitcnt vmcnt(8) lgkmcnt(4)
	v_mfma_f32_16x16x32_bf16 v[6:9], v[30:33], v[58:61], v[6:9]
	v_mfma_f32_16x16x32_bf16 v[2:5], v[30:33], v[62:65], v[2:5]
	ds_read_b128 v[18:21], v116 offset:3584
	ds_read_b128 v[22:25], v117 offset:3584
	ds_read_b128 v[26:29], v116 offset:3712
	ds_read_b128 v[30:33], v117 offset:3712
	global_load_dwordx4 v[34:37], v[10:11], off offset:3584
	global_load_dwordx4 v[38:41], v[14:15], off offset:3584
	global_load_dwordx4 v[42:45], v[10:11], off offset:3648
	global_load_dwordx4 v[46:49], v[14:15], off offset:3648
	global_load_dwordx4 v[50:53], v[10:11], off offset:3712
	global_load_dwordx4 v[54:57], v[14:15], off offset:3712
	global_load_dwordx4 v[58:61], v[10:11], off offset:3776
	global_load_dwordx4 v[62:65], v[14:15], off offset:3776
	s_waitcnt vmcnt(14) lgkmcnt(7)
	v_mfma_f32_16x16x32_bf16 v[6:9], v[66:69], v[82:85], v[6:9]
	v_mfma_f32_16x16x32_bf16 v[2:5], v[66:69], v[86:89], v[2:5]
	s_waitcnt vmcnt(12) lgkmcnt(6)
	v_mfma_f32_16x16x32_bf16 v[6:9], v[70:73], v[90:93], v[6:9]
	v_mfma_f32_16x16x32_bf16 v[2:5], v[70:73], v[94:97], v[2:5]
	s_waitcnt vmcnt(10) lgkmcnt(5)
	v_mfma_f32_16x16x32_bf16 v[6:9], v[74:77], v[98:101], v[6:9]
	v_mfma_f32_16x16x32_bf16 v[2:5], v[74:77], v[102:105], v[2:5]
	s_waitcnt vmcnt(8) lgkmcnt(4)
	v_mfma_f32_16x16x32_bf16 v[6:9], v[78:81], v[106:109], v[6:9]
	v_mfma_f32_16x16x32_bf16 v[2:5], v[78:81], v[110:113], v[2:5]
	ds_read_b128 v[66:69], v116 offset:3840
	ds_read_b128 v[70:73], v117 offset:3840
	ds_read_b128 v[74:77], v116 offset:3968
	ds_read_b128 v[78:81], v117 offset:3968
	global_load_dwordx4 v[82:85], v[10:11], off offset:3840
	global_load_dwordx4 v[86:89], v[14:15], off offset:3840
	global_load_dwordx4 v[90:93], v[10:11], off offset:3904
	global_load_dwordx4 v[94:97], v[14:15], off offset:3904
	global_load_dwordx4 v[98:101], v[10:11], off offset:3968
	global_load_dwordx4 v[102:105], v[14:15], off offset:3968
	global_load_dwordx4 v[106:109], v[10:11], off offset:4032
	global_load_dwordx4 v[110:113], v[14:15], off offset:4032
	s_waitcnt vmcnt(14) lgkmcnt(7)
	v_mfma_f32_16x16x32_bf16 v[6:9], v[18:21], v[34:37], v[6:9]
	v_mfma_f32_16x16x32_bf16 v[2:5], v[18:21], v[38:41], v[2:5]
	s_waitcnt vmcnt(12) lgkmcnt(6)
	v_mfma_f32_16x16x32_bf16 v[6:9], v[22:25], v[42:45], v[6:9]
	v_mfma_f32_16x16x32_bf16 v[2:5], v[22:25], v[46:49], v[2:5]
	s_waitcnt vmcnt(10) lgkmcnt(5)
	v_mfma_f32_16x16x32_bf16 v[6:9], v[26:29], v[50:53], v[6:9]
	v_mfma_f32_16x16x32_bf16 v[2:5], v[26:29], v[54:57], v[2:5]
	s_waitcnt vmcnt(8) lgkmcnt(4)
	v_mfma_f32_16x16x32_bf16 v[6:9], v[30:33], v[58:61], v[6:9]
	v_mfma_f32_16x16x32_bf16 v[2:5], v[30:33], v[62:65], v[2:5]
	ds_read_b128 v[18:21], v114
	ds_read_b128 v[22:25], v115
	ds_read_b128 v[26:29], v114 offset:128
	ds_read_b128 v[30:33], v115 offset:128
	global_load_dwordx4 v[34:37], v[10:11], off
	global_load_dwordx4 v[38:41], v[14:15], off
	global_load_dwordx4 v[42:45], v[10:11], off offset:64
	global_load_dwordx4 v[46:49], v[14:15], off offset:64
	global_load_dwordx4 v[50:53], v[10:11], off offset:128
	global_load_dwordx4 v[54:57], v[14:15], off offset:128
	global_load_dwordx4 v[58:61], v[10:11], off offset:192
	global_load_dwordx4 v[62:65], v[14:15], off offset:192
	s_waitcnt vmcnt(14) lgkmcnt(7)
	v_mfma_f32_16x16x32_bf16 v[6:9], v[66:69], v[82:85], v[6:9]
	v_mfma_f32_16x16x32_bf16 v[2:5], v[66:69], v[86:89], v[2:5]
	s_waitcnt vmcnt(12) lgkmcnt(6)
	v_mfma_f32_16x16x32_bf16 v[6:9], v[70:73], v[90:93], v[6:9]
	v_mfma_f32_16x16x32_bf16 v[2:5], v[70:73], v[94:97], v[2:5]
	s_waitcnt vmcnt(10) lgkmcnt(5)
	v_mfma_f32_16x16x32_bf16 v[6:9], v[74:77], v[98:101], v[6:9]
	v_mfma_f32_16x16x32_bf16 v[2:5], v[74:77], v[102:105], v[2:5]
	s_waitcnt vmcnt(8) lgkmcnt(4)
	v_mfma_f32_16x16x32_bf16 v[6:9], v[78:81], v[106:109], v[6:9]
	v_mfma_f32_16x16x32_bf16 v[2:5], v[78:81], v[110:113], v[2:5]
	ds_read_b128 v[66:69], v114 offset:256
	ds_read_b128 v[70:73], v115 offset:256
	ds_read_b128 v[74:77], v114 offset:384
	ds_read_b128 v[78:81], v115 offset:384
	global_load_dwordx4 v[82:85], v[10:11], off offset:256
	global_load_dwordx4 v[86:89], v[14:15], off offset:256
	global_load_dwordx4 v[90:93], v[10:11], off offset:320
	global_load_dwordx4 v[94:97], v[14:15], off offset:320
	global_load_dwordx4 v[98:101], v[10:11], off offset:384
	global_load_dwordx4 v[102:105], v[14:15], off offset:384
	global_load_dwordx4 v[106:109], v[10:11], off offset:448
	global_load_dwordx4 v[110:113], v[14:15], off offset:448
	s_waitcnt vmcnt(14) lgkmcnt(7)
	v_mfma_f32_16x16x32_bf16 v[6:9], v[18:21], v[34:37], v[6:9]
	v_mfma_f32_16x16x32_bf16 v[2:5], v[18:21], v[38:41], v[2:5]
	s_waitcnt vmcnt(12) lgkmcnt(6)
	v_mfma_f32_16x16x32_bf16 v[6:9], v[22:25], v[42:45], v[6:9]
	v_mfma_f32_16x16x32_bf16 v[2:5], v[22:25], v[46:49], v[2:5]
	s_waitcnt vmcnt(10) lgkmcnt(5)
	v_mfma_f32_16x16x32_bf16 v[6:9], v[26:29], v[50:53], v[6:9]
	v_mfma_f32_16x16x32_bf16 v[2:5], v[26:29], v[54:57], v[2:5]
	s_waitcnt vmcnt(8) lgkmcnt(4)
	v_mfma_f32_16x16x32_bf16 v[6:9], v[30:33], v[58:61], v[6:9]
	v_mfma_f32_16x16x32_bf16 v[2:5], v[30:33], v[62:65], v[2:5]
	ds_read_b128 v[18:21], v114 offset:512
	ds_read_b128 v[22:25], v115 offset:512
	ds_read_b128 v[26:29], v114 offset:640
	ds_read_b128 v[30:33], v115 offset:640
	global_load_dwordx4 v[34:37], v[10:11], off offset:512
	global_load_dwordx4 v[38:41], v[14:15], off offset:512
	global_load_dwordx4 v[42:45], v[10:11], off offset:576
	global_load_dwordx4 v[46:49], v[14:15], off offset:576
	global_load_dwordx4 v[50:53], v[10:11], off offset:640
	global_load_dwordx4 v[54:57], v[14:15], off offset:640
	global_load_dwordx4 v[58:61], v[10:11], off offset:704
	global_load_dwordx4 v[62:65], v[14:15], off offset:704
	s_waitcnt vmcnt(14) lgkmcnt(7)
	v_mfma_f32_16x16x32_bf16 v[6:9], v[66:69], v[82:85], v[6:9]
	v_mfma_f32_16x16x32_bf16 v[2:5], v[66:69], v[86:89], v[2:5]
	s_waitcnt vmcnt(12) lgkmcnt(6)
	v_mfma_f32_16x16x32_bf16 v[6:9], v[70:73], v[90:93], v[6:9]
	v_mfma_f32_16x16x32_bf16 v[2:5], v[70:73], v[94:97], v[2:5]
	s_waitcnt vmcnt(10) lgkmcnt(5)
	v_mfma_f32_16x16x32_bf16 v[6:9], v[74:77], v[98:101], v[6:9]
	v_mfma_f32_16x16x32_bf16 v[2:5], v[74:77], v[102:105], v[2:5]
	s_waitcnt vmcnt(8) lgkmcnt(4)
	v_mfma_f32_16x16x32_bf16 v[6:9], v[78:81], v[106:109], v[6:9]
	v_mfma_f32_16x16x32_bf16 v[2:5], v[78:81], v[110:113], v[2:5]
	ds_read_b128 v[66:69], v114 offset:768
	ds_read_b128 v[70:73], v115 offset:768
	ds_read_b128 v[74:77], v114 offset:896
	ds_read_b128 v[78:81], v115 offset:896
	global_load_dwordx4 v[82:85], v[10:11], off offset:768
	global_load_dwordx4 v[86:89], v[14:15], off offset:768
	global_load_dwordx4 v[90:93], v[10:11], off offset:832
	global_load_dwordx4 v[94:97], v[14:15], off offset:832
	global_load_dwordx4 v[98:101], v[10:11], off offset:896
	global_load_dwordx4 v[102:105], v[14:15], off offset:896
	global_load_dwordx4 v[106:109], v[10:11], off offset:960
	global_load_dwordx4 v[110:113], v[14:15], off offset:960
	s_waitcnt vmcnt(14) lgkmcnt(7)
	v_mfma_f32_16x16x32_bf16 v[6:9], v[18:21], v[34:37], v[6:9]
	v_mfma_f32_16x16x32_bf16 v[2:5], v[18:21], v[38:41], v[2:5]
	s_waitcnt vmcnt(12) lgkmcnt(6)
	v_mfma_f32_16x16x32_bf16 v[6:9], v[22:25], v[42:45], v[6:9]
	v_mfma_f32_16x16x32_bf16 v[2:5], v[22:25], v[46:49], v[2:5]
	s_waitcnt vmcnt(10) lgkmcnt(5)
	v_mfma_f32_16x16x32_bf16 v[6:9], v[26:29], v[50:53], v[6:9]
	v_mfma_f32_16x16x32_bf16 v[2:5], v[26:29], v[54:57], v[2:5]
	s_waitcnt vmcnt(8) lgkmcnt(4)
	v_mfma_f32_16x16x32_bf16 v[6:9], v[30:33], v[58:61], v[6:9]
	v_mfma_f32_16x16x32_bf16 v[2:5], v[30:33], v[62:65], v[2:5]
	s_waitcnt vmcnt(6) lgkmcnt(3)
	v_mfma_f32_16x16x32_bf16 v[6:9], v[66:69], v[82:85], v[6:9]
	v_mfma_f32_16x16x32_bf16 v[2:5], v[66:69], v[86:89], v[2:5]
	s_waitcnt vmcnt(4) lgkmcnt(2)
	v_mfma_f32_16x16x32_bf16 v[6:9], v[70:73], v[90:93], v[6:9]
	v_mfma_f32_16x16x32_bf16 v[2:5], v[70:73], v[94:97], v[2:5]
	s_waitcnt vmcnt(2) lgkmcnt(1)
	v_mfma_f32_16x16x32_bf16 v[6:9], v[74:77], v[98:101], v[6:9]
	v_mfma_f32_16x16x32_bf16 v[2:5], v[74:77], v[102:105], v[2:5]
	s_waitcnt vmcnt(0) lgkmcnt(0)
	v_mfma_f32_16x16x32_bf16 v[6:9], v[78:81], v[106:109], v[6:9]
	v_mfma_f32_16x16x32_bf16 v[2:5], v[78:81], v[110:113], v[2:5]
	s_branch .Lcmp_done
.Lcmp_rot3:
	ds_read_b128 v[18:21], v114 offset:1536
	ds_read_b128 v[22:25], v115 offset:1536
	ds_read_b128 v[26:29], v114 offset:1664
	ds_read_b128 v[30:33], v115 offset:1664
	global_load_dwordx4 v[34:37], v[10:11], off offset:1536
	global_load_dwordx4 v[38:41], v[14:15], off offset:1536
	global_load_dwordx4 v[42:45], v[10:11], off offset:1600
	global_load_dwordx4 v[46:49], v[14:15], off offset:1600
	global_load_dwordx4 v[50:53], v[10:11], off offset:1664
	global_load_dwordx4 v[54:57], v[14:15], off offset:1664
	global_load_dwordx4 v[58:61], v[10:11], off offset:1728
	global_load_dwordx4 v[62:65], v[14:15], off offset:1728
	ds_read_b128 v[66:69], v114 offset:1792
	ds_read_b128 v[70:73], v115 offset:1792
	ds_read_b128 v[74:77], v114 offset:1920
	ds_read_b128 v[78:81], v115 offset:1920
	global_load_dwordx4 v[82:85], v[10:11], off offset:1792
	global_load_dwordx4 v[86:89], v[14:15], off offset:1792
	global_load_dwordx4 v[90:93], v[10:11], off offset:1856
	global_load_dwordx4 v[94:97], v[14:15], off offset:1856
	global_load_dwordx4 v[98:101], v[10:11], off offset:1920
	global_load_dwordx4 v[102:105], v[14:15], off offset:1920
	global_load_dwordx4 v[106:109], v[10:11], off offset:1984
	global_load_dwordx4 v[110:113], v[14:15], off offset:1984
	s_waitcnt vmcnt(14) lgkmcnt(7)
	v_mfma_f32_16x16x32_bf16 v[6:9], v[18:21], v[34:37], v[6:9]
	v_mfma_f32_16x16x32_bf16 v[2:5], v[18:21], v[38:41], v[2:5]
	s_waitcnt vmcnt(12) lgkmcnt(6)
	v_mfma_f32_16x16x32_bf16 v[6:9], v[22:25], v[42:45], v[6:9]
	v_mfma_f32_16x16x32_bf16 v[2:5], v[22:25], v[46:49], v[2:5]
	s_waitcnt vmcnt(10) lgkmcnt(5)
	v_mfma_f32_16x16x32_bf16 v[6:9], v[26:29], v[50:53], v[6:9]
	v_mfma_f32_16x16x32_bf16 v[2:5], v[26:29], v[54:57], v[2:5]
	s_waitcnt vmcnt(8) lgkmcnt(4)
	v_mfma_f32_16x16x32_bf16 v[6:9], v[30:33], v[58:61], v[6:9]
	v_mfma_f32_16x16x32_bf16 v[2:5], v[30:33], v[62:65], v[2:5]
	ds_read_b128 v[18:21], v116 offset:2048
	ds_read_b128 v[22:25], v117 offset:2048
	ds_read_b128 v[26:29], v116 offset:2176
	ds_read_b128 v[30:33], v117 offset:2176
	global_load_dwordx4 v[34:37], v[10:11], off offset:2048
	global_load_dwordx4 v[38:41], v[14:15], off offset:2048
	global_load_dwordx4 v[42:45], v[10:11], off offset:2112
	global_load_dwordx4 v[46:49], v[14:15], off offset:2112
	global_load_dwordx4 v[50:53], v[10:11], off offset:2176
	global_load_dwordx4 v[54:57], v[14:15], off offset:2176
	global_load_dwordx4 v[58:61], v[10:11], off offset:2240
	global_load_dwordx4 v[62:65], v[14:15], off offset:2240
	s_waitcnt vmcnt(14) lgkmcnt(7)
	v_mfma_f32_16x16x32_bf16 v[6:9], v[66:69], v[82:85], v[6:9]
	v_mfma_f32_16x16x32_bf16 v[2:5], v[66:69], v[86:89], v[2:5]
	s_waitcnt vmcnt(12) lgkmcnt(6)
	v_mfma_f32_16x16x32_bf16 v[6:9], v[70:73], v[90:93], v[6:9]
	v_mfma_f32_16x16x32_bf16 v[2:5], v[70:73], v[94:97], v[2:5]
	s_waitcnt vmcnt(10) lgkmcnt(5)
	v_mfma_f32_16x16x32_bf16 v[6:9], v[74:77], v[98:101], v[6:9]
	v_mfma_f32_16x16x32_bf16 v[2:5], v[74:77], v[102:105], v[2:5]
	s_waitcnt vmcnt(8) lgkmcnt(4)
	v_mfma_f32_16x16x32_bf16 v[6:9], v[78:81], v[106:109], v[6:9]
	v_mfma_f32_16x16x32_bf16 v[2:5], v[78:81], v[110:113], v[2:5]
	ds_read_b128 v[66:69], v116 offset:2304
	ds_read_b128 v[70:73], v117 offset:2304
	ds_read_b128 v[74:77], v116 offset:2432
	ds_read_b128 v[78:81], v117 offset:2432
	global_load_dwordx4 v[82:85], v[10:11], off offset:2304
	global_load_dwordx4 v[86:89], v[14:15], off offset:2304
	global_load_dwordx4 v[90:93], v[10:11], off offset:2368
	global_load_dwordx4 v[94:97], v[14:15], off offset:2368
	global_load_dwordx4 v[98:101], v[10:11], off offset:2432
	global_load_dwordx4 v[102:105], v[14:15], off offset:2432
	global_load_dwordx4 v[106:109], v[10:11], off offset:2496
	global_load_dwordx4 v[110:113], v[14:15], off offset:2496
	s_waitcnt vmcnt(14) lgkmcnt(7)
	v_mfma_f32_16x16x32_bf16 v[6:9], v[18:21], v[34:37], v[6:9]
	v_mfma_f32_16x16x32_bf16 v[2:5], v[18:21], v[38:41], v[2:5]
	s_waitcnt vmcnt(12) lgkmcnt(6)
	v_mfma_f32_16x16x32_bf16 v[6:9], v[22:25], v[42:45], v[6:9]
	v_mfma_f32_16x16x32_bf16 v[2:5], v[22:25], v[46:49], v[2:5]
	s_waitcnt vmcnt(10) lgkmcnt(5)
	v_mfma_f32_16x16x32_bf16 v[6:9], v[26:29], v[50:53], v[6:9]
	v_mfma_f32_16x16x32_bf16 v[2:5], v[26:29], v[54:57], v[2:5]
	s_waitcnt vmcnt(8) lgkmcnt(4)
	v_mfma_f32_16x16x32_bf16 v[6:9], v[30:33], v[58:61], v[6:9]
	v_mfma_f32_16x16x32_bf16 v[2:5], v[30:33], v[62:65], v[2:5]
	ds_read_b128 v[18:21], v116 offset:2560
	ds_read_b128 v[22:25], v117 offset:2560
	ds_read_b128 v[26:29], v116 offset:2688
	ds_read_b128 v[30:33], v117 offset:2688
	global_load_dwordx4 v[34:37], v[10:11], off offset:2560
	global_load_dwordx4 v[38:41], v[14:15], off offset:2560
	global_load_dwordx4 v[42:45], v[10:11], off offset:2624
	global_load_dwordx4 v[46:49], v[14:15], off offset:2624
	global_load_dwordx4 v[50:53], v[10:11], off offset:2688
	global_load_dwordx4 v[54:57], v[14:15], off offset:2688
	global_load_dwordx4 v[58:61], v[10:11], off offset:2752
	global_load_dwordx4 v[62:65], v[14:15], off offset:2752
	s_waitcnt vmcnt(14) lgkmcnt(7)
	v_mfma_f32_16x16x32_bf16 v[6:9], v[66:69], v[82:85], v[6:9]
	v_mfma_f32_16x16x32_bf16 v[2:5], v[66:69], v[86:89], v[2:5]
	s_waitcnt vmcnt(12) lgkmcnt(6)
	v_mfma_f32_16x16x32_bf16 v[6:9], v[70:73], v[90:93], v[6:9]
	v_mfma_f32_16x16x32_bf16 v[2:5], v[70:73], v[94:97], v[2:5]
	s_waitcnt vmcnt(10) lgkmcnt(5)
	v_mfma_f32_16x16x32_bf16 v[6:9], v[74:77], v[98:101], v[6:9]
	v_mfma_f32_16x16x32_bf16 v[2:5], v[74:77], v[102:105], v[2:5]
	s_waitcnt vmcnt(8) lgkmcnt(4)
	v_mfma_f32_16x16x32_bf16 v[6:9], v[78:81], v[106:109], v[6:9]
	v_mfma_f32_16x16x32_bf16 v[2:5], v[78:81], v[110:113], v[2:5]
	ds_read_b128 v[66:69], v116 offset:2816
	ds_read_b128 v[70:73], v117 offset:2816
	ds_read_b128 v[74:77], v116 offset:2944
	ds_read_b128 v[78:81], v117 offset:2944
	global_load_dwordx4 v[82:85], v[10:11], off offset:2816
	global_load_dwordx4 v[86:89], v[14:15], off offset:2816
	global_load_dwordx4 v[90:93], v[10:11], off offset:2880
	global_load_dwordx4 v[94:97], v[14:15], off offset:2880
	global_load_dwordx4 v[98:101], v[10:11], off offset:2944
	global_load_dwordx4 v[102:105], v[14:15], off offset:2944
	global_load_dwordx4 v[106:109], v[10:11], off offset:3008
	global_load_dwordx4 v[110:113], v[14:15], off offset:3008
	s_waitcnt vmcnt(14) lgkmcnt(7)
	v_mfma_f32_16x16x32_bf16 v[6:9], v[18:21], v[34:37], v[6:9]
	v_mfma_f32_16x16x32_bf16 v[2:5], v[18:21], v[38:41], v[2:5]
	s_waitcnt vmcnt(12) lgkmcnt(6)
	v_mfma_f32_16x16x32_bf16 v[6:9], v[22:25], v[42:45], v[6:9]
	v_mfma_f32_16x16x32_bf16 v[2:5], v[22:25], v[46:49], v[2:5]
	s_waitcnt vmcnt(10) lgkmcnt(5)
	v_mfma_f32_16x16x32_bf16 v[6:9], v[26:29], v[50:53], v[6:9]
	v_mfma_f32_16x16x32_bf16 v[2:5], v[26:29], v[54:57], v[2:5]
	s_waitcnt vmcnt(8) lgkmcnt(4)
	v_mfma_f32_16x16x32_bf16 v[6:9], v[30:33], v[58:61], v[6:9]
	v_mfma_f32_16x16x32_bf16 v[2:5], v[30:33], v[62:65], v[2:5]
	ds_read_b128 v[18:21], v116 offset:3072
	ds_read_b128 v[22:25], v117 offset:3072
	ds_read_b128 v[26:29], v116 offset:3200
	ds_read_b128 v[30:33], v117 offset:3200
	global_load_dwordx4 v[34:37], v[10:11], off offset:3072
	global_load_dwordx4 v[38:41], v[14:15], off offset:3072
	global_load_dwordx4 v[42:45], v[10:11], off offset:3136
	global_load_dwordx4 v[46:49], v[14:15], off offset:3136
	global_load_dwordx4 v[50:53], v[10:11], off offset:3200
	global_load_dwordx4 v[54:57], v[14:15], off offset:3200
	global_load_dwordx4 v[58:61], v[10:11], off offset:3264
	global_load_dwordx4 v[62:65], v[14:15], off offset:3264
	s_waitcnt vmcnt(14) lgkmcnt(7)
	v_mfma_f32_16x16x32_bf16 v[6:9], v[66:69], v[82:85], v[6:9]
	v_mfma_f32_16x16x32_bf16 v[2:5], v[66:69], v[86:89], v[2:5]
	s_waitcnt vmcnt(12) lgkmcnt(6)
	v_mfma_f32_16x16x32_bf16 v[6:9], v[70:73], v[90:93], v[6:9]
	v_mfma_f32_16x16x32_bf16 v[2:5], v[70:73], v[94:97], v[2:5]
	s_waitcnt vmcnt(10) lgkmcnt(5)
	v_mfma_f32_16x16x32_bf16 v[6:9], v[74:77], v[98:101], v[6:9]
	v_mfma_f32_16x16x32_bf16 v[2:5], v[74:77], v[102:105], v[2:5]
	s_waitcnt vmcnt(8) lgkmcnt(4)
	v_mfma_f32_16x16x32_bf16 v[6:9], v[78:81], v[106:109], v[6:9]
	v_mfma_f32_16x16x32_bf16 v[2:5], v[78:81], v[110:113], v[2:5]
	ds_read_b128 v[66:69], v116 offset:3328
	ds_read_b128 v[70:73], v117 offset:3328
	ds_read_b128 v[74:77], v116 offset:3456
	ds_read_b128 v[78:81], v117 offset:3456
	global_load_dwordx4 v[82:85], v[10:11], off offset:3328
	global_load_dwordx4 v[86:89], v[14:15], off offset:3328
	global_load_dwordx4 v[90:93], v[10:11], off offset:3392
	global_load_dwordx4 v[94:97], v[14:15], off offset:3392
	global_load_dwordx4 v[98:101], v[10:11], off offset:3456
	global_load_dwordx4 v[102:105], v[14:15], off offset:3456
	global_load_dwordx4 v[106:109], v[10:11], off offset:3520
	global_load_dwordx4 v[110:113], v[14:15], off offset:3520
	s_waitcnt vmcnt(14) lgkmcnt(7)
	v_mfma_f32_16x16x32_bf16 v[6:9], v[18:21], v[34:37], v[6:9]
	v_mfma_f32_16x16x32_bf16 v[2:5], v[18:21], v[38:41], v[2:5]
	s_waitcnt vmcnt(12) lgkmcnt(6)
	v_mfma_f32_16x16x32_bf16 v[6:9], v[22:25], v[42:45], v[6:9]
	v_mfma_f32_16x16x32_bf16 v[2:5], v[22:25], v[46:49], v[2:5]
	s_waitcnt vmcnt(10) lgkmcnt(5)
	v_mfma_f32_16x16x32_bf16 v[6:9], v[26:29], v[50:53], v[6:9]
	v_mfma_f32_16x16x32_bf16 v[2:5], v[26:29], v[54:57], v[2:5]
	s_waitcnt vmcnt(8) lgkmcnt(4)
	v_mfma_f32_16x16x32_bf16 v[6:9], v[30:33], v[58:61], v[6:9]
	v_mfma_f32_16x16x32_bf16 v[2:5], v[30:33], v[62:65], v[2:5]
	ds_read_b128 v[18:21], v116 offset:3584
	ds_read_b128 v[22:25], v117 offset:3584
	ds_read_b128 v[26:29], v116 offset:3712
	ds_read_b128 v[30:33], v117 offset:3712
	global_load_dwordx4 v[34:37], v[10:11], off offset:3584
	global_load_dwordx4 v[38:41], v[14:15], off offset:3584
	global_load_dwordx4 v[42:45], v[10:11], off offset:3648
	global_load_dwordx4 v[46:49], v[14:15], off offset:3648
	global_load_dwordx4 v[50:53], v[10:11], off offset:3712
	global_load_dwordx4 v[54:57], v[14:15], off offset:3712
	global_load_dwordx4 v[58:61], v[10:11], off offset:3776
	global_load_dwordx4 v[62:65], v[14:15], off offset:3776
	s_waitcnt vmcnt(14) lgkmcnt(7)
	v_mfma_f32_16x16x32_bf16 v[6:9], v[66:69], v[82:85], v[6:9]
	v_mfma_f32_16x16x32_bf16 v[2:5], v[66:69], v[86:89], v[2:5]
	s_waitcnt vmcnt(12) lgkmcnt(6)
	v_mfma_f32_16x16x32_bf16 v[6:9], v[70:73], v[90:93], v[6:9]
	v_mfma_f32_16x16x32_bf16 v[2:5], v[70:73], v[94:97], v[2:5]
	s_waitcnt vmcnt(10) lgkmcnt(5)
	v_mfma_f32_16x16x32_bf16 v[6:9], v[74:77], v[98:101], v[6:9]
	v_mfma_f32_16x16x32_bf16 v[2:5], v[74:77], v[102:105], v[2:5]
	s_waitcnt vmcnt(8) lgkmcnt(4)
	v_mfma_f32_16x16x32_bf16 v[6:9], v[78:81], v[106:109], v[6:9]
	v_mfma_f32_16x16x32_bf16 v[2:5], v[78:81], v[110:113], v[2:5]
	ds_read_b128 v[66:69], v116 offset:3840
	ds_read_b128 v[70:73], v117 offset:3840
	ds_read_b128 v[74:77], v116 offset:3968
	ds_read_b128 v[78:81], v117 offset:3968
	global_load_dwordx4 v[82:85], v[10:11], off offset:3840
	global_load_dwordx4 v[86:89], v[14:15], off offset:3840
	global_load_dwordx4 v[90:93], v[10:11], off offset:3904
	global_load_dwordx4 v[94:97], v[14:15], off offset:3904
	global_load_dwordx4 v[98:101], v[10:11], off offset:3968
	global_load_dwordx4 v[102:105], v[14:15], off offset:3968
	global_load_dwordx4 v[106:109], v[10:11], off offset:4032
	global_load_dwordx4 v[110:113], v[14:15], off offset:4032
	s_waitcnt vmcnt(14) lgkmcnt(7)
	v_mfma_f32_16x16x32_bf16 v[6:9], v[18:21], v[34:37], v[6:9]
	v_mfma_f32_16x16x32_bf16 v[2:5], v[18:21], v[38:41], v[2:5]
	s_waitcnt vmcnt(12) lgkmcnt(6)
	v_mfma_f32_16x16x32_bf16 v[6:9], v[22:25], v[42:45], v[6:9]
	v_mfma_f32_16x16x32_bf16 v[2:5], v[22:25], v[46:49], v[2:5]
	s_waitcnt vmcnt(10) lgkmcnt(5)
	v_mfma_f32_16x16x32_bf16 v[6:9], v[26:29], v[50:53], v[6:9]
	v_mfma_f32_16x16x32_bf16 v[2:5], v[26:29], v[54:57], v[2:5]
	s_waitcnt vmcnt(8) lgkmcnt(4)
	v_mfma_f32_16x16x32_bf16 v[6:9], v[30:33], v[58:61], v[6:9]
	v_mfma_f32_16x16x32_bf16 v[2:5], v[30:33], v[62:65], v[2:5]
	ds_read_b128 v[18:21], v114
	ds_read_b128 v[22:25], v115
	ds_read_b128 v[26:29], v114 offset:128
	ds_read_b128 v[30:33], v115 offset:128
	global_load_dwordx4 v[34:37], v[10:11], off
	global_load_dwordx4 v[38:41], v[14:15], off
	global_load_dwordx4 v[42:45], v[10:11], off offset:64
	global_load_dwordx4 v[46:49], v[14:15], off offset:64
	global_load_dwordx4 v[50:53], v[10:11], off offset:128
	global_load_dwordx4 v[54:57], v[14:15], off offset:128
	global_load_dwordx4 v[58:61], v[10:11], off offset:192
	global_load_dwordx4 v[62:65], v[14:15], off offset:192
	s_waitcnt vmcnt(14) lgkmcnt(7)
	v_mfma_f32_16x16x32_bf16 v[6:9], v[66:69], v[82:85], v[6:9]
	v_mfma_f32_16x16x32_bf16 v[2:5], v[66:69], v[86:89], v[2:5]
	s_waitcnt vmcnt(12) lgkmcnt(6)
	v_mfma_f32_16x16x32_bf16 v[6:9], v[70:73], v[90:93], v[6:9]
	v_mfma_f32_16x16x32_bf16 v[2:5], v[70:73], v[94:97], v[2:5]
	s_waitcnt vmcnt(10) lgkmcnt(5)
	v_mfma_f32_16x16x32_bf16 v[6:9], v[74:77], v[98:101], v[6:9]
	v_mfma_f32_16x16x32_bf16 v[2:5], v[74:77], v[102:105], v[2:5]
	s_waitcnt vmcnt(8) lgkmcnt(4)
	v_mfma_f32_16x16x32_bf16 v[6:9], v[78:81], v[106:109], v[6:9]
	v_mfma_f32_16x16x32_bf16 v[2:5], v[78:81], v[110:113], v[2:5]
	ds_read_b128 v[66:69], v114 offset:256
	ds_read_b128 v[70:73], v115 offset:256
	ds_read_b128 v[74:77], v114 offset:384
	ds_read_b128 v[78:81], v115 offset:384
	global_load_dwordx4 v[82:85], v[10:11], off offset:256
	global_load_dwordx4 v[86:89], v[14:15], off offset:256
	global_load_dwordx4 v[90:93], v[10:11], off offset:320
	global_load_dwordx4 v[94:97], v[14:15], off offset:320
	global_load_dwordx4 v[98:101], v[10:11], off offset:384
	global_load_dwordx4 v[102:105], v[14:15], off offset:384
	global_load_dwordx4 v[106:109], v[10:11], off offset:448
	global_load_dwordx4 v[110:113], v[14:15], off offset:448
	s_waitcnt vmcnt(14) lgkmcnt(7)
	v_mfma_f32_16x16x32_bf16 v[6:9], v[18:21], v[34:37], v[6:9]
	v_mfma_f32_16x16x32_bf16 v[2:5], v[18:21], v[38:41], v[2:5]
	s_waitcnt vmcnt(12) lgkmcnt(6)
	v_mfma_f32_16x16x32_bf16 v[6:9], v[22:25], v[42:45], v[6:9]
	v_mfma_f32_16x16x32_bf16 v[2:5], v[22:25], v[46:49], v[2:5]
	s_waitcnt vmcnt(10) lgkmcnt(5)
	v_mfma_f32_16x16x32_bf16 v[6:9], v[26:29], v[50:53], v[6:9]
	v_mfma_f32_16x16x32_bf16 v[2:5], v[26:29], v[54:57], v[2:5]
	s_waitcnt vmcnt(8) lgkmcnt(4)
	v_mfma_f32_16x16x32_bf16 v[6:9], v[30:33], v[58:61], v[6:9]
	v_mfma_f32_16x16x32_bf16 v[2:5], v[30:33], v[62:65], v[2:5]
	ds_read_b128 v[18:21], v114 offset:512
	ds_read_b128 v[22:25], v115 offset:512
	ds_read_b128 v[26:29], v114 offset:640
	ds_read_b128 v[30:33], v115 offset:640
	global_load_dwordx4 v[34:37], v[10:11], off offset:512
	global_load_dwordx4 v[38:41], v[14:15], off offset:512
	global_load_dwordx4 v[42:45], v[10:11], off offset:576
	global_load_dwordx4 v[46:49], v[14:15], off offset:576
	global_load_dwordx4 v[50:53], v[10:11], off offset:640
	global_load_dwordx4 v[54:57], v[14:15], off offset:640
	global_load_dwordx4 v[58:61], v[10:11], off offset:704
	global_load_dwordx4 v[62:65], v[14:15], off offset:704
	s_waitcnt vmcnt(14) lgkmcnt(7)
	v_mfma_f32_16x16x32_bf16 v[6:9], v[66:69], v[82:85], v[6:9]
	v_mfma_f32_16x16x32_bf16 v[2:5], v[66:69], v[86:89], v[2:5]
	s_waitcnt vmcnt(12) lgkmcnt(6)
	v_mfma_f32_16x16x32_bf16 v[6:9], v[70:73], v[90:93], v[6:9]
	v_mfma_f32_16x16x32_bf16 v[2:5], v[70:73], v[94:97], v[2:5]
	s_waitcnt vmcnt(10) lgkmcnt(5)
	v_mfma_f32_16x16x32_bf16 v[6:9], v[74:77], v[98:101], v[6:9]
	v_mfma_f32_16x16x32_bf16 v[2:5], v[74:77], v[102:105], v[2:5]
	s_waitcnt vmcnt(8) lgkmcnt(4)
	v_mfma_f32_16x16x32_bf16 v[6:9], v[78:81], v[106:109], v[6:9]
	v_mfma_f32_16x16x32_bf16 v[2:5], v[78:81], v[110:113], v[2:5]
	ds_read_b128 v[66:69], v114 offset:768
	ds_read_b128 v[70:73], v115 offset:768
	ds_read_b128 v[74:77], v114 offset:896
	ds_read_b128 v[78:81], v115 offset:896
	global_load_dwordx4 v[82:85], v[10:11], off offset:768
	global_load_dwordx4 v[86:89], v[14:15], off offset:768
	global_load_dwordx4 v[90:93], v[10:11], off offset:832
	global_load_dwordx4 v[94:97], v[14:15], off offset:832
	global_load_dwordx4 v[98:101], v[10:11], off offset:896
	global_load_dwordx4 v[102:105], v[14:15], off offset:896
	global_load_dwordx4 v[106:109], v[10:11], off offset:960
	global_load_dwordx4 v[110:113], v[14:15], off offset:960
	s_waitcnt vmcnt(14) lgkmcnt(7)
	v_mfma_f32_16x16x32_bf16 v[6:9], v[18:21], v[34:37], v[6:9]
	v_mfma_f32_16x16x32_bf16 v[2:5], v[18:21], v[38:41], v[2:5]
	s_waitcnt vmcnt(12) lgkmcnt(6)
	v_mfma_f32_16x16x32_bf16 v[6:9], v[22:25], v[42:45], v[6:9]
	v_mfma_f32_16x16x32_bf16 v[2:5], v[22:25], v[46:49], v[2:5]
	s_waitcnt vmcnt(10) lgkmcnt(5)
	v_mfma_f32_16x16x32_bf16 v[6:9], v[26:29], v[50:53], v[6:9]
	v_mfma_f32_16x16x32_bf16 v[2:5], v[26:29], v[54:57], v[2:5]
	s_waitcnt vmcnt(8) lgkmcnt(4)
	v_mfma_f32_16x16x32_bf16 v[6:9], v[30:33], v[58:61], v[6:9]
	v_mfma_f32_16x16x32_bf16 v[2:5], v[30:33], v[62:65], v[2:5]
	ds_read_b128 v[18:21], v114 offset:1024
	ds_read_b128 v[22:25], v115 offset:1024
	ds_read_b128 v[26:29], v114 offset:1152
	ds_read_b128 v[30:33], v115 offset:1152
	global_load_dwordx4 v[34:37], v[10:11], off offset:1024
	global_load_dwordx4 v[38:41], v[14:15], off offset:1024
	global_load_dwordx4 v[42:45], v[10:11], off offset:1088
	global_load_dwordx4 v[46:49], v[14:15], off offset:1088
	global_load_dwordx4 v[50:53], v[10:11], off offset:1152
	global_load_dwordx4 v[54:57], v[14:15], off offset:1152
	global_load_dwordx4 v[58:61], v[10:11], off offset:1216
	global_load_dwordx4 v[62:65], v[14:15], off offset:1216
	s_waitcnt vmcnt(14) lgkmcnt(7)
	v_mfma_f32_16x16x32_bf16 v[6:9], v[66:69], v[82:85], v[6:9]
	v_mfma_f32_16x16x32_bf16 v[2:5], v[66:69], v[86:89], v[2:5]
	s_waitcnt vmcnt(12) lgkmcnt(6)
	v_mfma_f32_16x16x32_bf16 v[6:9], v[70:73], v[90:93], v[6:9]
	v_mfma_f32_16x16x32_bf16 v[2:5], v[70:73], v[94:97], v[2:5]
	s_waitcnt vmcnt(10) lgkmcnt(5)
	v_mfma_f32_16x16x32_bf16 v[6:9], v[74:77], v[98:101], v[6:9]
	v_mfma_f32_16x16x32_bf16 v[2:5], v[74:77], v[102:105], v[2:5]
	s_waitcnt vmcnt(8) lgkmcnt(4)
	v_mfma_f32_16x16x32_bf16 v[6:9], v[78:81], v[106:109], v[6:9]
	v_mfma_f32_16x16x32_bf16 v[2:5], v[78:81], v[110:113], v[2:5]
	ds_read_b128 v[66:69], v114 offset:1280
	ds_read_b128 v[70:73], v115 offset:1280
	ds_read_b128 v[74:77], v114 offset:1408
	ds_read_b128 v[78:81], v115 offset:1408
	global_load_dwordx4 v[82:85], v[10:11], off offset:1280
	global_load_dwordx4 v[86:89], v[14:15], off offset:1280
	global_load_dwordx4 v[90:93], v[10:11], off offset:1344
	global_load_dwordx4 v[94:97], v[14:15], off offset:1344
	global_load_dwordx4 v[98:101], v[10:11], off offset:1408
	global_load_dwordx4 v[102:105], v[14:15], off offset:1408
	global_load_dwordx4 v[106:109], v[10:11], off offset:1472
	global_load_dwordx4 v[110:113], v[14:15], off offset:1472
	s_waitcnt vmcnt(14) lgkmcnt(7)
	v_mfma_f32_16x16x32_bf16 v[6:9], v[18:21], v[34:37], v[6:9]
	v_mfma_f32_16x16x32_bf16 v[2:5], v[18:21], v[38:41], v[2:5]
	s_waitcnt vmcnt(12) lgkmcnt(6)
	v_mfma_f32_16x16x32_bf16 v[6:9], v[22:25], v[42:45], v[6:9]
	v_mfma_f32_16x16x32_bf16 v[2:5], v[22:25], v[46:49], v[2:5]
	s_waitcnt vmcnt(10) lgkmcnt(5)
	v_mfma_f32_16x16x32_bf16 v[6:9], v[26:29], v[50:53], v[6:9]
	v_mfma_f32_16x16x32_bf16 v[2:5], v[26:29], v[54:57], v[2:5]
	s_waitcnt vmcnt(8) lgkmcnt(4)
	v_mfma_f32_16x16x32_bf16 v[6:9], v[30:33], v[58:61], v[6:9]
	v_mfma_f32_16x16x32_bf16 v[2:5], v[30:33], v[62:65], v[2:5]
	s_waitcnt vmcnt(6) lgkmcnt(3)
	v_mfma_f32_16x16x32_bf16 v[6:9], v[66:69], v[82:85], v[6:9]
	v_mfma_f32_16x16x32_bf16 v[2:5], v[66:69], v[86:89], v[2:5]
	s_waitcnt vmcnt(4) lgkmcnt(2)
	v_mfma_f32_16x16x32_bf16 v[6:9], v[70:73], v[90:93], v[6:9]
	v_mfma_f32_16x16x32_bf16 v[2:5], v[70:73], v[94:97], v[2:5]
	s_waitcnt vmcnt(2) lgkmcnt(1)
	v_mfma_f32_16x16x32_bf16 v[6:9], v[74:77], v[98:101], v[6:9]
	v_mfma_f32_16x16x32_bf16 v[2:5], v[74:77], v[102:105], v[2:5]
	s_waitcnt vmcnt(0) lgkmcnt(0)
	v_mfma_f32_16x16x32_bf16 v[6:9], v[78:81], v[106:109], v[6:9]
	v_mfma_f32_16x16x32_bf16 v[2:5], v[78:81], v[110:113], v[2:5]
	s_branch .Lcmp_done
.Lcmp_rot4:
	ds_read_b128 v[18:21], v116 offset:2048
	ds_read_b128 v[22:25], v117 offset:2048
	ds_read_b128 v[26:29], v116 offset:2176
	ds_read_b128 v[30:33], v117 offset:2176
	global_load_dwordx4 v[34:37], v[10:11], off offset:2048
	global_load_dwordx4 v[38:41], v[14:15], off offset:2048
	global_load_dwordx4 v[42:45], v[10:11], off offset:2112
	global_load_dwordx4 v[46:49], v[14:15], off offset:2112
	global_load_dwordx4 v[50:53], v[10:11], off offset:2176
	global_load_dwordx4 v[54:57], v[14:15], off offset:2176
	global_load_dwordx4 v[58:61], v[10:11], off offset:2240
	global_load_dwordx4 v[62:65], v[14:15], off offset:2240
	ds_read_b128 v[66:69], v116 offset:2304
	ds_read_b128 v[70:73], v117 offset:2304
	ds_read_b128 v[74:77], v116 offset:2432
	ds_read_b128 v[78:81], v117 offset:2432
	global_load_dwordx4 v[82:85], v[10:11], off offset:2304
	global_load_dwordx4 v[86:89], v[14:15], off offset:2304
	global_load_dwordx4 v[90:93], v[10:11], off offset:2368
	global_load_dwordx4 v[94:97], v[14:15], off offset:2368
	global_load_dwordx4 v[98:101], v[10:11], off offset:2432
	global_load_dwordx4 v[102:105], v[14:15], off offset:2432
	global_load_dwordx4 v[106:109], v[10:11], off offset:2496
	global_load_dwordx4 v[110:113], v[14:15], off offset:2496
	s_waitcnt vmcnt(14) lgkmcnt(7)
	v_mfma_f32_16x16x32_bf16 v[6:9], v[18:21], v[34:37], v[6:9]
	v_mfma_f32_16x16x32_bf16 v[2:5], v[18:21], v[38:41], v[2:5]
	s_waitcnt vmcnt(12) lgkmcnt(6)
	v_mfma_f32_16x16x32_bf16 v[6:9], v[22:25], v[42:45], v[6:9]
	v_mfma_f32_16x16x32_bf16 v[2:5], v[22:25], v[46:49], v[2:5]
	s_waitcnt vmcnt(10) lgkmcnt(5)
	v_mfma_f32_16x16x32_bf16 v[6:9], v[26:29], v[50:53], v[6:9]
	v_mfma_f32_16x16x32_bf16 v[2:5], v[26:29], v[54:57], v[2:5]
	s_waitcnt vmcnt(8) lgkmcnt(4)
	v_mfma_f32_16x16x32_bf16 v[6:9], v[30:33], v[58:61], v[6:9]
	v_mfma_f32_16x16x32_bf16 v[2:5], v[30:33], v[62:65], v[2:5]
	ds_read_b128 v[18:21], v116 offset:2560
	ds_read_b128 v[22:25], v117 offset:2560
	ds_read_b128 v[26:29], v116 offset:2688
	ds_read_b128 v[30:33], v117 offset:2688
	global_load_dwordx4 v[34:37], v[10:11], off offset:2560
	global_load_dwordx4 v[38:41], v[14:15], off offset:2560
	global_load_dwordx4 v[42:45], v[10:11], off offset:2624
	global_load_dwordx4 v[46:49], v[14:15], off offset:2624
	global_load_dwordx4 v[50:53], v[10:11], off offset:2688
	global_load_dwordx4 v[54:57], v[14:15], off offset:2688
	global_load_dwordx4 v[58:61], v[10:11], off offset:2752
	global_load_dwordx4 v[62:65], v[14:15], off offset:2752
	s_waitcnt vmcnt(14) lgkmcnt(7)
	v_mfma_f32_16x16x32_bf16 v[6:9], v[66:69], v[82:85], v[6:9]
	v_mfma_f32_16x16x32_bf16 v[2:5], v[66:69], v[86:89], v[2:5]
	s_waitcnt vmcnt(12) lgkmcnt(6)
	v_mfma_f32_16x16x32_bf16 v[6:9], v[70:73], v[90:93], v[6:9]
	v_mfma_f32_16x16x32_bf16 v[2:5], v[70:73], v[94:97], v[2:5]
	s_waitcnt vmcnt(10) lgkmcnt(5)
	v_mfma_f32_16x16x32_bf16 v[6:9], v[74:77], v[98:101], v[6:9]
	v_mfma_f32_16x16x32_bf16 v[2:5], v[74:77], v[102:105], v[2:5]
	s_waitcnt vmcnt(8) lgkmcnt(4)
	v_mfma_f32_16x16x32_bf16 v[6:9], v[78:81], v[106:109], v[6:9]
	v_mfma_f32_16x16x32_bf16 v[2:5], v[78:81], v[110:113], v[2:5]
	ds_read_b128 v[66:69], v116 offset:2816
	ds_read_b128 v[70:73], v117 offset:2816
	ds_read_b128 v[74:77], v116 offset:2944
	ds_read_b128 v[78:81], v117 offset:2944
	global_load_dwordx4 v[82:85], v[10:11], off offset:2816
	global_load_dwordx4 v[86:89], v[14:15], off offset:2816
	global_load_dwordx4 v[90:93], v[10:11], off offset:2880
	global_load_dwordx4 v[94:97], v[14:15], off offset:2880
	global_load_dwordx4 v[98:101], v[10:11], off offset:2944
	global_load_dwordx4 v[102:105], v[14:15], off offset:2944
	global_load_dwordx4 v[106:109], v[10:11], off offset:3008
	global_load_dwordx4 v[110:113], v[14:15], off offset:3008
	s_waitcnt vmcnt(14) lgkmcnt(7)
	v_mfma_f32_16x16x32_bf16 v[6:9], v[18:21], v[34:37], v[6:9]
	v_mfma_f32_16x16x32_bf16 v[2:5], v[18:21], v[38:41], v[2:5]
	s_waitcnt vmcnt(12) lgkmcnt(6)
	v_mfma_f32_16x16x32_bf16 v[6:9], v[22:25], v[42:45], v[6:9]
	v_mfma_f32_16x16x32_bf16 v[2:5], v[22:25], v[46:49], v[2:5]
	s_waitcnt vmcnt(10) lgkmcnt(5)
	v_mfma_f32_16x16x32_bf16 v[6:9], v[26:29], v[50:53], v[6:9]
	v_mfma_f32_16x16x32_bf16 v[2:5], v[26:29], v[54:57], v[2:5]
	s_waitcnt vmcnt(8) lgkmcnt(4)
	v_mfma_f32_16x16x32_bf16 v[6:9], v[30:33], v[58:61], v[6:9]
	v_mfma_f32_16x16x32_bf16 v[2:5], v[30:33], v[62:65], v[2:5]
	ds_read_b128 v[18:21], v116 offset:3072
	ds_read_b128 v[22:25], v117 offset:3072
	ds_read_b128 v[26:29], v116 offset:3200
	ds_read_b128 v[30:33], v117 offset:3200
	global_load_dwordx4 v[34:37], v[10:11], off offset:3072
	global_load_dwordx4 v[38:41], v[14:15], off offset:3072
	global_load_dwordx4 v[42:45], v[10:11], off offset:3136
	global_load_dwordx4 v[46:49], v[14:15], off offset:3136
	global_load_dwordx4 v[50:53], v[10:11], off offset:3200
	global_load_dwordx4 v[54:57], v[14:15], off offset:3200
	global_load_dwordx4 v[58:61], v[10:11], off offset:3264
	global_load_dwordx4 v[62:65], v[14:15], off offset:3264
	s_waitcnt vmcnt(14) lgkmcnt(7)
	v_mfma_f32_16x16x32_bf16 v[6:9], v[66:69], v[82:85], v[6:9]
	v_mfma_f32_16x16x32_bf16 v[2:5], v[66:69], v[86:89], v[2:5]
	s_waitcnt vmcnt(12) lgkmcnt(6)
	v_mfma_f32_16x16x32_bf16 v[6:9], v[70:73], v[90:93], v[6:9]
	v_mfma_f32_16x16x32_bf16 v[2:5], v[70:73], v[94:97], v[2:5]
	s_waitcnt vmcnt(10) lgkmcnt(5)
	v_mfma_f32_16x16x32_bf16 v[6:9], v[74:77], v[98:101], v[6:9]
	v_mfma_f32_16x16x32_bf16 v[2:5], v[74:77], v[102:105], v[2:5]
	s_waitcnt vmcnt(8) lgkmcnt(4)
	v_mfma_f32_16x16x32_bf16 v[6:9], v[78:81], v[106:109], v[6:9]
	v_mfma_f32_16x16x32_bf16 v[2:5], v[78:81], v[110:113], v[2:5]
	ds_read_b128 v[66:69], v116 offset:3328
	ds_read_b128 v[70:73], v117 offset:3328
	ds_read_b128 v[74:77], v116 offset:3456
	ds_read_b128 v[78:81], v117 offset:3456
	global_load_dwordx4 v[82:85], v[10:11], off offset:3328
	global_load_dwordx4 v[86:89], v[14:15], off offset:3328
	global_load_dwordx4 v[90:93], v[10:11], off offset:3392
	global_load_dwordx4 v[94:97], v[14:15], off offset:3392
	global_load_dwordx4 v[98:101], v[10:11], off offset:3456
	global_load_dwordx4 v[102:105], v[14:15], off offset:3456
	global_load_dwordx4 v[106:109], v[10:11], off offset:3520
	global_load_dwordx4 v[110:113], v[14:15], off offset:3520
	s_waitcnt vmcnt(14) lgkmcnt(7)
	v_mfma_f32_16x16x32_bf16 v[6:9], v[18:21], v[34:37], v[6:9]
	v_mfma_f32_16x16x32_bf16 v[2:5], v[18:21], v[38:41], v[2:5]
	s_waitcnt vmcnt(12) lgkmcnt(6)
	v_mfma_f32_16x16x32_bf16 v[6:9], v[22:25], v[42:45], v[6:9]
	v_mfma_f32_16x16x32_bf16 v[2:5], v[22:25], v[46:49], v[2:5]
	s_waitcnt vmcnt(10) lgkmcnt(5)
	v_mfma_f32_16x16x32_bf16 v[6:9], v[26:29], v[50:53], v[6:9]
	v_mfma_f32_16x16x32_bf16 v[2:5], v[26:29], v[54:57], v[2:5]
	s_waitcnt vmcnt(8) lgkmcnt(4)
	v_mfma_f32_16x16x32_bf16 v[6:9], v[30:33], v[58:61], v[6:9]
	v_mfma_f32_16x16x32_bf16 v[2:5], v[30:33], v[62:65], v[2:5]
	ds_read_b128 v[18:21], v116 offset:3584
	ds_read_b128 v[22:25], v117 offset:3584
	ds_read_b128 v[26:29], v116 offset:3712
	ds_read_b128 v[30:33], v117 offset:3712
	global_load_dwordx4 v[34:37], v[10:11], off offset:3584
	global_load_dwordx4 v[38:41], v[14:15], off offset:3584
	global_load_dwordx4 v[42:45], v[10:11], off offset:3648
	global_load_dwordx4 v[46:49], v[14:15], off offset:3648
	global_load_dwordx4 v[50:53], v[10:11], off offset:3712
	global_load_dwordx4 v[54:57], v[14:15], off offset:3712
	global_load_dwordx4 v[58:61], v[10:11], off offset:3776
	global_load_dwordx4 v[62:65], v[14:15], off offset:3776
	s_waitcnt vmcnt(14) lgkmcnt(7)
	v_mfma_f32_16x16x32_bf16 v[6:9], v[66:69], v[82:85], v[6:9]
	v_mfma_f32_16x16x32_bf16 v[2:5], v[66:69], v[86:89], v[2:5]
	s_waitcnt vmcnt(12) lgkmcnt(6)
	v_mfma_f32_16x16x32_bf16 v[6:9], v[70:73], v[90:93], v[6:9]
	v_mfma_f32_16x16x32_bf16 v[2:5], v[70:73], v[94:97], v[2:5]
	s_waitcnt vmcnt(10) lgkmcnt(5)
	v_mfma_f32_16x16x32_bf16 v[6:9], v[74:77], v[98:101], v[6:9]
	v_mfma_f32_16x16x32_bf16 v[2:5], v[74:77], v[102:105], v[2:5]
	s_waitcnt vmcnt(8) lgkmcnt(4)
	v_mfma_f32_16x16x32_bf16 v[6:9], v[78:81], v[106:109], v[6:9]
	v_mfma_f32_16x16x32_bf16 v[2:5], v[78:81], v[110:113], v[2:5]
	ds_read_b128 v[66:69], v116 offset:3840
	ds_read_b128 v[70:73], v117 offset:3840
	ds_read_b128 v[74:77], v116 offset:3968
	ds_read_b128 v[78:81], v117 offset:3968
	global_load_dwordx4 v[82:85], v[10:11], off offset:3840
	global_load_dwordx4 v[86:89], v[14:15], off offset:3840
	global_load_dwordx4 v[90:93], v[10:11], off offset:3904
	global_load_dwordx4 v[94:97], v[14:15], off offset:3904
	global_load_dwordx4 v[98:101], v[10:11], off offset:3968
	global_load_dwordx4 v[102:105], v[14:15], off offset:3968
	global_load_dwordx4 v[106:109], v[10:11], off offset:4032
	global_load_dwordx4 v[110:113], v[14:15], off offset:4032
	s_waitcnt vmcnt(14) lgkmcnt(7)
	v_mfma_f32_16x16x32_bf16 v[6:9], v[18:21], v[34:37], v[6:9]
	v_mfma_f32_16x16x32_bf16 v[2:5], v[18:21], v[38:41], v[2:5]
	s_waitcnt vmcnt(12) lgkmcnt(6)
	v_mfma_f32_16x16x32_bf16 v[6:9], v[22:25], v[42:45], v[6:9]
	v_mfma_f32_16x16x32_bf16 v[2:5], v[22:25], v[46:49], v[2:5]
	s_waitcnt vmcnt(10) lgkmcnt(5)
	v_mfma_f32_16x16x32_bf16 v[6:9], v[26:29], v[50:53], v[6:9]
	v_mfma_f32_16x16x32_bf16 v[2:5], v[26:29], v[54:57], v[2:5]
	s_waitcnt vmcnt(8) lgkmcnt(4)
	v_mfma_f32_16x16x32_bf16 v[6:9], v[30:33], v[58:61], v[6:9]
	v_mfma_f32_16x16x32_bf16 v[2:5], v[30:33], v[62:65], v[2:5]
	ds_read_b128 v[18:21], v114
	ds_read_b128 v[22:25], v115
	ds_read_b128 v[26:29], v114 offset:128
	ds_read_b128 v[30:33], v115 offset:128
	global_load_dwordx4 v[34:37], v[10:11], off
	global_load_dwordx4 v[38:41], v[14:15], off
	global_load_dwordx4 v[42:45], v[10:11], off offset:64
	global_load_dwordx4 v[46:49], v[14:15], off offset:64
	global_load_dwordx4 v[50:53], v[10:11], off offset:128
	global_load_dwordx4 v[54:57], v[14:15], off offset:128
	global_load_dwordx4 v[58:61], v[10:11], off offset:192
	global_load_dwordx4 v[62:65], v[14:15], off offset:192
	s_waitcnt vmcnt(14) lgkmcnt(7)
	v_mfma_f32_16x16x32_bf16 v[6:9], v[66:69], v[82:85], v[6:9]
	v_mfma_f32_16x16x32_bf16 v[2:5], v[66:69], v[86:89], v[2:5]
	s_waitcnt vmcnt(12) lgkmcnt(6)
	v_mfma_f32_16x16x32_bf16 v[6:9], v[70:73], v[90:93], v[6:9]
	v_mfma_f32_16x16x32_bf16 v[2:5], v[70:73], v[94:97], v[2:5]
	s_waitcnt vmcnt(10) lgkmcnt(5)
	v_mfma_f32_16x16x32_bf16 v[6:9], v[74:77], v[98:101], v[6:9]
	v_mfma_f32_16x16x32_bf16 v[2:5], v[74:77], v[102:105], v[2:5]
	s_waitcnt vmcnt(8) lgkmcnt(4)
	v_mfma_f32_16x16x32_bf16 v[6:9], v[78:81], v[106:109], v[6:9]
	v_mfma_f32_16x16x32_bf16 v[2:5], v[78:81], v[110:113], v[2:5]
	ds_read_b128 v[66:69], v114 offset:256
	ds_read_b128 v[70:73], v115 offset:256
	ds_read_b128 v[74:77], v114 offset:384
	ds_read_b128 v[78:81], v115 offset:384
	global_load_dwordx4 v[82:85], v[10:11], off offset:256
	global_load_dwordx4 v[86:89], v[14:15], off offset:256
	global_load_dwordx4 v[90:93], v[10:11], off offset:320
	global_load_dwordx4 v[94:97], v[14:15], off offset:320
	global_load_dwordx4 v[98:101], v[10:11], off offset:384
	global_load_dwordx4 v[102:105], v[14:15], off offset:384
	global_load_dwordx4 v[106:109], v[10:11], off offset:448
	global_load_dwordx4 v[110:113], v[14:15], off offset:448
	s_waitcnt vmcnt(14) lgkmcnt(7)
	v_mfma_f32_16x16x32_bf16 v[6:9], v[18:21], v[34:37], v[6:9]
	v_mfma_f32_16x16x32_bf16 v[2:5], v[18:21], v[38:41], v[2:5]
	s_waitcnt vmcnt(12) lgkmcnt(6)
	v_mfma_f32_16x16x32_bf16 v[6:9], v[22:25], v[42:45], v[6:9]
	v_mfma_f32_16x16x32_bf16 v[2:5], v[22:25], v[46:49], v[2:5]
	s_waitcnt vmcnt(10) lgkmcnt(5)
	v_mfma_f32_16x16x32_bf16 v[6:9], v[26:29], v[50:53], v[6:9]
	v_mfma_f32_16x16x32_bf16 v[2:5], v[26:29], v[54:57], v[2:5]
	s_waitcnt vmcnt(8) lgkmcnt(4)
	v_mfma_f32_16x16x32_bf16 v[6:9], v[30:33], v[58:61], v[6:9]
	v_mfma_f32_16x16x32_bf16 v[2:5], v[30:33], v[62:65], v[2:5]
	ds_read_b128 v[18:21], v114 offset:512
	ds_read_b128 v[22:25], v115 offset:512
	ds_read_b128 v[26:29], v114 offset:640
	ds_read_b128 v[30:33], v115 offset:640
	global_load_dwordx4 v[34:37], v[10:11], off offset:512
	global_load_dwordx4 v[38:41], v[14:15], off offset:512
	global_load_dwordx4 v[42:45], v[10:11], off offset:576
	global_load_dwordx4 v[46:49], v[14:15], off offset:576
	global_load_dwordx4 v[50:53], v[10:11], off offset:640
	global_load_dwordx4 v[54:57], v[14:15], off offset:640
	global_load_dwordx4 v[58:61], v[10:11], off offset:704
	global_load_dwordx4 v[62:65], v[14:15], off offset:704
	s_waitcnt vmcnt(14) lgkmcnt(7)
	v_mfma_f32_16x16x32_bf16 v[6:9], v[66:69], v[82:85], v[6:9]
	v_mfma_f32_16x16x32_bf16 v[2:5], v[66:69], v[86:89], v[2:5]
	s_waitcnt vmcnt(12) lgkmcnt(6)
	v_mfma_f32_16x16x32_bf16 v[6:9], v[70:73], v[90:93], v[6:9]
	v_mfma_f32_16x16x32_bf16 v[2:5], v[70:73], v[94:97], v[2:5]
	s_waitcnt vmcnt(10) lgkmcnt(5)
	v_mfma_f32_16x16x32_bf16 v[6:9], v[74:77], v[98:101], v[6:9]
	v_mfma_f32_16x16x32_bf16 v[2:5], v[74:77], v[102:105], v[2:5]
	s_waitcnt vmcnt(8) lgkmcnt(4)
	v_mfma_f32_16x16x32_bf16 v[6:9], v[78:81], v[106:109], v[6:9]
	v_mfma_f32_16x16x32_bf16 v[2:5], v[78:81], v[110:113], v[2:5]
	ds_read_b128 v[66:69], v114 offset:768
	ds_read_b128 v[70:73], v115 offset:768
	ds_read_b128 v[74:77], v114 offset:896
	ds_read_b128 v[78:81], v115 offset:896
	global_load_dwordx4 v[82:85], v[10:11], off offset:768
	global_load_dwordx4 v[86:89], v[14:15], off offset:768
	global_load_dwordx4 v[90:93], v[10:11], off offset:832
	global_load_dwordx4 v[94:97], v[14:15], off offset:832
	global_load_dwordx4 v[98:101], v[10:11], off offset:896
	global_load_dwordx4 v[102:105], v[14:15], off offset:896
	global_load_dwordx4 v[106:109], v[10:11], off offset:960
	global_load_dwordx4 v[110:113], v[14:15], off offset:960
	s_waitcnt vmcnt(14) lgkmcnt(7)
	v_mfma_f32_16x16x32_bf16 v[6:9], v[18:21], v[34:37], v[6:9]
	v_mfma_f32_16x16x32_bf16 v[2:5], v[18:21], v[38:41], v[2:5]
	s_waitcnt vmcnt(12) lgkmcnt(6)
	v_mfma_f32_16x16x32_bf16 v[6:9], v[22:25], v[42:45], v[6:9]
	v_mfma_f32_16x16x32_bf16 v[2:5], v[22:25], v[46:49], v[2:5]
	s_waitcnt vmcnt(10) lgkmcnt(5)
	v_mfma_f32_16x16x32_bf16 v[6:9], v[26:29], v[50:53], v[6:9]
	v_mfma_f32_16x16x32_bf16 v[2:5], v[26:29], v[54:57], v[2:5]
	s_waitcnt vmcnt(8) lgkmcnt(4)
	v_mfma_f32_16x16x32_bf16 v[6:9], v[30:33], v[58:61], v[6:9]
	v_mfma_f32_16x16x32_bf16 v[2:5], v[30:33], v[62:65], v[2:5]
	ds_read_b128 v[18:21], v114 offset:1024
	ds_read_b128 v[22:25], v115 offset:1024
	ds_read_b128 v[26:29], v114 offset:1152
	ds_read_b128 v[30:33], v115 offset:1152
	global_load_dwordx4 v[34:37], v[10:11], off offset:1024
	global_load_dwordx4 v[38:41], v[14:15], off offset:1024
	global_load_dwordx4 v[42:45], v[10:11], off offset:1088
	global_load_dwordx4 v[46:49], v[14:15], off offset:1088
	global_load_dwordx4 v[50:53], v[10:11], off offset:1152
	global_load_dwordx4 v[54:57], v[14:15], off offset:1152
	global_load_dwordx4 v[58:61], v[10:11], off offset:1216
	global_load_dwordx4 v[62:65], v[14:15], off offset:1216
	s_waitcnt vmcnt(14) lgkmcnt(7)
	v_mfma_f32_16x16x32_bf16 v[6:9], v[66:69], v[82:85], v[6:9]
	v_mfma_f32_16x16x32_bf16 v[2:5], v[66:69], v[86:89], v[2:5]
	s_waitcnt vmcnt(12) lgkmcnt(6)
	v_mfma_f32_16x16x32_bf16 v[6:9], v[70:73], v[90:93], v[6:9]
	v_mfma_f32_16x16x32_bf16 v[2:5], v[70:73], v[94:97], v[2:5]
	s_waitcnt vmcnt(10) lgkmcnt(5)
	v_mfma_f32_16x16x32_bf16 v[6:9], v[74:77], v[98:101], v[6:9]
	v_mfma_f32_16x16x32_bf16 v[2:5], v[74:77], v[102:105], v[2:5]
	s_waitcnt vmcnt(8) lgkmcnt(4)
	v_mfma_f32_16x16x32_bf16 v[6:9], v[78:81], v[106:109], v[6:9]
	v_mfma_f32_16x16x32_bf16 v[2:5], v[78:81], v[110:113], v[2:5]
	ds_read_b128 v[66:69], v114 offset:1280
	ds_read_b128 v[70:73], v115 offset:1280
	ds_read_b128 v[74:77], v114 offset:1408
	ds_read_b128 v[78:81], v115 offset:1408
	global_load_dwordx4 v[82:85], v[10:11], off offset:1280
	global_load_dwordx4 v[86:89], v[14:15], off offset:1280
	global_load_dwordx4 v[90:93], v[10:11], off offset:1344
	global_load_dwordx4 v[94:97], v[14:15], off offset:1344
	global_load_dwordx4 v[98:101], v[10:11], off offset:1408
	global_load_dwordx4 v[102:105], v[14:15], off offset:1408
	global_load_dwordx4 v[106:109], v[10:11], off offset:1472
	global_load_dwordx4 v[110:113], v[14:15], off offset:1472
	s_waitcnt vmcnt(14) lgkmcnt(7)
	v_mfma_f32_16x16x32_bf16 v[6:9], v[18:21], v[34:37], v[6:9]
	v_mfma_f32_16x16x32_bf16 v[2:5], v[18:21], v[38:41], v[2:5]
	s_waitcnt vmcnt(12) lgkmcnt(6)
	v_mfma_f32_16x16x32_bf16 v[6:9], v[22:25], v[42:45], v[6:9]
	v_mfma_f32_16x16x32_bf16 v[2:5], v[22:25], v[46:49], v[2:5]
	s_waitcnt vmcnt(10) lgkmcnt(5)
	v_mfma_f32_16x16x32_bf16 v[6:9], v[26:29], v[50:53], v[6:9]
	v_mfma_f32_16x16x32_bf16 v[2:5], v[26:29], v[54:57], v[2:5]
	s_waitcnt vmcnt(8) lgkmcnt(4)
	v_mfma_f32_16x16x32_bf16 v[6:9], v[30:33], v[58:61], v[6:9]
	v_mfma_f32_16x16x32_bf16 v[2:5], v[30:33], v[62:65], v[2:5]
	ds_read_b128 v[18:21], v114 offset:1536
	ds_read_b128 v[22:25], v115 offset:1536
	ds_read_b128 v[26:29], v114 offset:1664
	ds_read_b128 v[30:33], v115 offset:1664
	global_load_dwordx4 v[34:37], v[10:11], off offset:1536
	global_load_dwordx4 v[38:41], v[14:15], off offset:1536
	global_load_dwordx4 v[42:45], v[10:11], off offset:1600
	global_load_dwordx4 v[46:49], v[14:15], off offset:1600
	global_load_dwordx4 v[50:53], v[10:11], off offset:1664
	global_load_dwordx4 v[54:57], v[14:15], off offset:1664
	global_load_dwordx4 v[58:61], v[10:11], off offset:1728
	global_load_dwordx4 v[62:65], v[14:15], off offset:1728
	s_waitcnt vmcnt(14) lgkmcnt(7)
	v_mfma_f32_16x16x32_bf16 v[6:9], v[66:69], v[82:85], v[6:9]
	v_mfma_f32_16x16x32_bf16 v[2:5], v[66:69], v[86:89], v[2:5]
	s_waitcnt vmcnt(12) lgkmcnt(6)
	v_mfma_f32_16x16x32_bf16 v[6:9], v[70:73], v[90:93], v[6:9]
	v_mfma_f32_16x16x32_bf16 v[2:5], v[70:73], v[94:97], v[2:5]
	s_waitcnt vmcnt(10) lgkmcnt(5)
	v_mfma_f32_16x16x32_bf16 v[6:9], v[74:77], v[98:101], v[6:9]
	v_mfma_f32_16x16x32_bf16 v[2:5], v[74:77], v[102:105], v[2:5]
	s_waitcnt vmcnt(8) lgkmcnt(4)
	v_mfma_f32_16x16x32_bf16 v[6:9], v[78:81], v[106:109], v[6:9]
	v_mfma_f32_16x16x32_bf16 v[2:5], v[78:81], v[110:113], v[2:5]
	ds_read_b128 v[66:69], v114 offset:1792
	ds_read_b128 v[70:73], v115 offset:1792
	ds_read_b128 v[74:77], v114 offset:1920
	ds_read_b128 v[78:81], v115 offset:1920
	global_load_dwordx4 v[82:85], v[10:11], off offset:1792
	global_load_dwordx4 v[86:89], v[14:15], off offset:1792
	global_load_dwordx4 v[90:93], v[10:11], off offset:1856
	global_load_dwordx4 v[94:97], v[14:15], off offset:1856
	global_load_dwordx4 v[98:101], v[10:11], off offset:1920
	global_load_dwordx4 v[102:105], v[14:15], off offset:1920
	global_load_dwordx4 v[106:109], v[10:11], off offset:1984
	global_load_dwordx4 v[110:113], v[14:15], off offset:1984
	s_waitcnt vmcnt(14) lgkmcnt(7)
	v_mfma_f32_16x16x32_bf16 v[6:9], v[18:21], v[34:37], v[6:9]
	v_mfma_f32_16x16x32_bf16 v[2:5], v[18:21], v[38:41], v[2:5]
	s_waitcnt vmcnt(12) lgkmcnt(6)
	v_mfma_f32_16x16x32_bf16 v[6:9], v[22:25], v[42:45], v[6:9]
	v_mfma_f32_16x16x32_bf16 v[2:5], v[22:25], v[46:49], v[2:5]
	s_waitcnt vmcnt(10) lgkmcnt(5)
	v_mfma_f32_16x16x32_bf16 v[6:9], v[26:29], v[50:53], v[6:9]
	v_mfma_f32_16x16x32_bf16 v[2:5], v[26:29], v[54:57], v[2:5]
	s_waitcnt vmcnt(8) lgkmcnt(4)
	v_mfma_f32_16x16x32_bf16 v[6:9], v[30:33], v[58:61], v[6:9]
	v_mfma_f32_16x16x32_bf16 v[2:5], v[30:33], v[62:65], v[2:5]
	s_waitcnt vmcnt(6) lgkmcnt(3)
	v_mfma_f32_16x16x32_bf16 v[6:9], v[66:69], v[82:85], v[6:9]
	v_mfma_f32_16x16x32_bf16 v[2:5], v[66:69], v[86:89], v[2:5]
	s_waitcnt vmcnt(4) lgkmcnt(2)
	v_mfma_f32_16x16x32_bf16 v[6:9], v[70:73], v[90:93], v[6:9]
	v_mfma_f32_16x16x32_bf16 v[2:5], v[70:73], v[94:97], v[2:5]
	s_waitcnt vmcnt(2) lgkmcnt(1)
	v_mfma_f32_16x16x32_bf16 v[6:9], v[74:77], v[98:101], v[6:9]
	v_mfma_f32_16x16x32_bf16 v[2:5], v[74:77], v[102:105], v[2:5]
	s_waitcnt vmcnt(0) lgkmcnt(0)
	v_mfma_f32_16x16x32_bf16 v[6:9], v[78:81], v[106:109], v[6:9]
	v_mfma_f32_16x16x32_bf16 v[2:5], v[78:81], v[110:113], v[2:5]
	s_branch .Lcmp_done
.Lcmp_rot5:
	ds_read_b128 v[18:21], v116 offset:2560
	ds_read_b128 v[22:25], v117 offset:2560
	ds_read_b128 v[26:29], v116 offset:2688
	ds_read_b128 v[30:33], v117 offset:2688
	global_load_dwordx4 v[34:37], v[10:11], off offset:2560
	global_load_dwordx4 v[38:41], v[14:15], off offset:2560
	global_load_dwordx4 v[42:45], v[10:11], off offset:2624
	global_load_dwordx4 v[46:49], v[14:15], off offset:2624
	global_load_dwordx4 v[50:53], v[10:11], off offset:2688
	global_load_dwordx4 v[54:57], v[14:15], off offset:2688
	global_load_dwordx4 v[58:61], v[10:11], off offset:2752
	global_load_dwordx4 v[62:65], v[14:15], off offset:2752
	ds_read_b128 v[66:69], v116 offset:2816
	ds_read_b128 v[70:73], v117 offset:2816
	ds_read_b128 v[74:77], v116 offset:2944
	ds_read_b128 v[78:81], v117 offset:2944
	global_load_dwordx4 v[82:85], v[10:11], off offset:2816
	global_load_dwordx4 v[86:89], v[14:15], off offset:2816
	global_load_dwordx4 v[90:93], v[10:11], off offset:2880
	global_load_dwordx4 v[94:97], v[14:15], off offset:2880
	global_load_dwordx4 v[98:101], v[10:11], off offset:2944
	global_load_dwordx4 v[102:105], v[14:15], off offset:2944
	global_load_dwordx4 v[106:109], v[10:11], off offset:3008
	global_load_dwordx4 v[110:113], v[14:15], off offset:3008
	s_waitcnt vmcnt(14) lgkmcnt(7)
	v_mfma_f32_16x16x32_bf16 v[6:9], v[18:21], v[34:37], v[6:9]
	v_mfma_f32_16x16x32_bf16 v[2:5], v[18:21], v[38:41], v[2:5]
	s_waitcnt vmcnt(12) lgkmcnt(6)
	v_mfma_f32_16x16x32_bf16 v[6:9], v[22:25], v[42:45], v[6:9]
	v_mfma_f32_16x16x32_bf16 v[2:5], v[22:25], v[46:49], v[2:5]
	s_waitcnt vmcnt(10) lgkmcnt(5)
	v_mfma_f32_16x16x32_bf16 v[6:9], v[26:29], v[50:53], v[6:9]
	v_mfma_f32_16x16x32_bf16 v[2:5], v[26:29], v[54:57], v[2:5]
	s_waitcnt vmcnt(8) lgkmcnt(4)
	v_mfma_f32_16x16x32_bf16 v[6:9], v[30:33], v[58:61], v[6:9]
	v_mfma_f32_16x16x32_bf16 v[2:5], v[30:33], v[62:65], v[2:5]
	ds_read_b128 v[18:21], v116 offset:3072
	ds_read_b128 v[22:25], v117 offset:3072
	ds_read_b128 v[26:29], v116 offset:3200
	ds_read_b128 v[30:33], v117 offset:3200
	global_load_dwordx4 v[34:37], v[10:11], off offset:3072
	global_load_dwordx4 v[38:41], v[14:15], off offset:3072
	global_load_dwordx4 v[42:45], v[10:11], off offset:3136
	global_load_dwordx4 v[46:49], v[14:15], off offset:3136
	global_load_dwordx4 v[50:53], v[10:11], off offset:3200
	global_load_dwordx4 v[54:57], v[14:15], off offset:3200
	global_load_dwordx4 v[58:61], v[10:11], off offset:3264
	global_load_dwordx4 v[62:65], v[14:15], off offset:3264
	s_waitcnt vmcnt(14) lgkmcnt(7)
	v_mfma_f32_16x16x32_bf16 v[6:9], v[66:69], v[82:85], v[6:9]
	v_mfma_f32_16x16x32_bf16 v[2:5], v[66:69], v[86:89], v[2:5]
	s_waitcnt vmcnt(12) lgkmcnt(6)
	v_mfma_f32_16x16x32_bf16 v[6:9], v[70:73], v[90:93], v[6:9]
	v_mfma_f32_16x16x32_bf16 v[2:5], v[70:73], v[94:97], v[2:5]
	s_waitcnt vmcnt(10) lgkmcnt(5)
	v_mfma_f32_16x16x32_bf16 v[6:9], v[74:77], v[98:101], v[6:9]
	v_mfma_f32_16x16x32_bf16 v[2:5], v[74:77], v[102:105], v[2:5]
	s_waitcnt vmcnt(8) lgkmcnt(4)
	v_mfma_f32_16x16x32_bf16 v[6:9], v[78:81], v[106:109], v[6:9]
	v_mfma_f32_16x16x32_bf16 v[2:5], v[78:81], v[110:113], v[2:5]
	ds_read_b128 v[66:69], v116 offset:3328
	ds_read_b128 v[70:73], v117 offset:3328
	ds_read_b128 v[74:77], v116 offset:3456
	ds_read_b128 v[78:81], v117 offset:3456
	global_load_dwordx4 v[82:85], v[10:11], off offset:3328
	global_load_dwordx4 v[86:89], v[14:15], off offset:3328
	global_load_dwordx4 v[90:93], v[10:11], off offset:3392
	global_load_dwordx4 v[94:97], v[14:15], off offset:3392
	global_load_dwordx4 v[98:101], v[10:11], off offset:3456
	global_load_dwordx4 v[102:105], v[14:15], off offset:3456
	global_load_dwordx4 v[106:109], v[10:11], off offset:3520
	global_load_dwordx4 v[110:113], v[14:15], off offset:3520
	s_waitcnt vmcnt(14) lgkmcnt(7)
	v_mfma_f32_16x16x32_bf16 v[6:9], v[18:21], v[34:37], v[6:9]
	v_mfma_f32_16x16x32_bf16 v[2:5], v[18:21], v[38:41], v[2:5]
	s_waitcnt vmcnt(12) lgkmcnt(6)
	v_mfma_f32_16x16x32_bf16 v[6:9], v[22:25], v[42:45], v[6:9]
	v_mfma_f32_16x16x32_bf16 v[2:5], v[22:25], v[46:49], v[2:5]
	s_waitcnt vmcnt(10) lgkmcnt(5)
	v_mfma_f32_16x16x32_bf16 v[6:9], v[26:29], v[50:53], v[6:9]
	v_mfma_f32_16x16x32_bf16 v[2:5], v[26:29], v[54:57], v[2:5]
	s_waitcnt vmcnt(8) lgkmcnt(4)
	v_mfma_f32_16x16x32_bf16 v[6:9], v[30:33], v[58:61], v[6:9]
	v_mfma_f32_16x16x32_bf16 v[2:5], v[30:33], v[62:65], v[2:5]
	ds_read_b128 v[18:21], v116 offset:3584
	ds_read_b128 v[22:25], v117 offset:3584
	ds_read_b128 v[26:29], v116 offset:3712
	ds_read_b128 v[30:33], v117 offset:3712
	global_load_dwordx4 v[34:37], v[10:11], off offset:3584
	global_load_dwordx4 v[38:41], v[14:15], off offset:3584
	global_load_dwordx4 v[42:45], v[10:11], off offset:3648
	global_load_dwordx4 v[46:49], v[14:15], off offset:3648
	global_load_dwordx4 v[50:53], v[10:11], off offset:3712
	global_load_dwordx4 v[54:57], v[14:15], off offset:3712
	global_load_dwordx4 v[58:61], v[10:11], off offset:3776
	global_load_dwordx4 v[62:65], v[14:15], off offset:3776
	s_waitcnt vmcnt(14) lgkmcnt(7)
	v_mfma_f32_16x16x32_bf16 v[6:9], v[66:69], v[82:85], v[6:9]
	v_mfma_f32_16x16x32_bf16 v[2:5], v[66:69], v[86:89], v[2:5]
	s_waitcnt vmcnt(12) lgkmcnt(6)
	v_mfma_f32_16x16x32_bf16 v[6:9], v[70:73], v[90:93], v[6:9]
	v_mfma_f32_16x16x32_bf16 v[2:5], v[70:73], v[94:97], v[2:5]
	s_waitcnt vmcnt(10) lgkmcnt(5)
	v_mfma_f32_16x16x32_bf16 v[6:9], v[74:77], v[98:101], v[6:9]
	v_mfma_f32_16x16x32_bf16 v[2:5], v[74:77], v[102:105], v[2:5]
	s_waitcnt vmcnt(8) lgkmcnt(4)
	v_mfma_f32_16x16x32_bf16 v[6:9], v[78:81], v[106:109], v[6:9]
	v_mfma_f32_16x16x32_bf16 v[2:5], v[78:81], v[110:113], v[2:5]
	ds_read_b128 v[66:69], v116 offset:3840
	ds_read_b128 v[70:73], v117 offset:3840
	ds_read_b128 v[74:77], v116 offset:3968
	ds_read_b128 v[78:81], v117 offset:3968
	global_load_dwordx4 v[82:85], v[10:11], off offset:3840
	global_load_dwordx4 v[86:89], v[14:15], off offset:3840
	global_load_dwordx4 v[90:93], v[10:11], off offset:3904
	global_load_dwordx4 v[94:97], v[14:15], off offset:3904
	global_load_dwordx4 v[98:101], v[10:11], off offset:3968
	global_load_dwordx4 v[102:105], v[14:15], off offset:3968
	global_load_dwordx4 v[106:109], v[10:11], off offset:4032
	global_load_dwordx4 v[110:113], v[14:15], off offset:4032
	s_waitcnt vmcnt(14) lgkmcnt(7)
	v_mfma_f32_16x16x32_bf16 v[6:9], v[18:21], v[34:37], v[6:9]
	v_mfma_f32_16x16x32_bf16 v[2:5], v[18:21], v[38:41], v[2:5]
	s_waitcnt vmcnt(12) lgkmcnt(6)
	v_mfma_f32_16x16x32_bf16 v[6:9], v[22:25], v[42:45], v[6:9]
	v_mfma_f32_16x16x32_bf16 v[2:5], v[22:25], v[46:49], v[2:5]
	s_waitcnt vmcnt(10) lgkmcnt(5)
	v_mfma_f32_16x16x32_bf16 v[6:9], v[26:29], v[50:53], v[6:9]
	v_mfma_f32_16x16x32_bf16 v[2:5], v[26:29], v[54:57], v[2:5]
	s_waitcnt vmcnt(8) lgkmcnt(4)
	v_mfma_f32_16x16x32_bf16 v[6:9], v[30:33], v[58:61], v[6:9]
	v_mfma_f32_16x16x32_bf16 v[2:5], v[30:33], v[62:65], v[2:5]
	ds_read_b128 v[18:21], v114
	ds_read_b128 v[22:25], v115
	ds_read_b128 v[26:29], v114 offset:128
	ds_read_b128 v[30:33], v115 offset:128
	global_load_dwordx4 v[34:37], v[10:11], off
	global_load_dwordx4 v[38:41], v[14:15], off
	global_load_dwordx4 v[42:45], v[10:11], off offset:64
	global_load_dwordx4 v[46:49], v[14:15], off offset:64
	global_load_dwordx4 v[50:53], v[10:11], off offset:128
	global_load_dwordx4 v[54:57], v[14:15], off offset:128
	global_load_dwordx4 v[58:61], v[10:11], off offset:192
	global_load_dwordx4 v[62:65], v[14:15], off offset:192
	s_waitcnt vmcnt(14) lgkmcnt(7)
	v_mfma_f32_16x16x32_bf16 v[6:9], v[66:69], v[82:85], v[6:9]
	v_mfma_f32_16x16x32_bf16 v[2:5], v[66:69], v[86:89], v[2:5]
	s_waitcnt vmcnt(12) lgkmcnt(6)
	v_mfma_f32_16x16x32_bf16 v[6:9], v[70:73], v[90:93], v[6:9]
	v_mfma_f32_16x16x32_bf16 v[2:5], v[70:73], v[94:97], v[2:5]
	s_waitcnt vmcnt(10) lgkmcnt(5)
	v_mfma_f32_16x16x32_bf16 v[6:9], v[74:77], v[98:101], v[6:9]
	v_mfma_f32_16x16x32_bf16 v[2:5], v[74:77], v[102:105], v[2:5]
	s_waitcnt vmcnt(8) lgkmcnt(4)
	v_mfma_f32_16x16x32_bf16 v[6:9], v[78:81], v[106:109], v[6:9]
	v_mfma_f32_16x16x32_bf16 v[2:5], v[78:81], v[110:113], v[2:5]
	ds_read_b128 v[66:69], v114 offset:256
	ds_read_b128 v[70:73], v115 offset:256
	ds_read_b128 v[74:77], v114 offset:384
	ds_read_b128 v[78:81], v115 offset:384
	global_load_dwordx4 v[82:85], v[10:11], off offset:256
	global_load_dwordx4 v[86:89], v[14:15], off offset:256
	global_load_dwordx4 v[90:93], v[10:11], off offset:320
	global_load_dwordx4 v[94:97], v[14:15], off offset:320
	global_load_dwordx4 v[98:101], v[10:11], off offset:384
	global_load_dwordx4 v[102:105], v[14:15], off offset:384
	global_load_dwordx4 v[106:109], v[10:11], off offset:448
	global_load_dwordx4 v[110:113], v[14:15], off offset:448
	s_waitcnt vmcnt(14) lgkmcnt(7)
	v_mfma_f32_16x16x32_bf16 v[6:9], v[18:21], v[34:37], v[6:9]
	v_mfma_f32_16x16x32_bf16 v[2:5], v[18:21], v[38:41], v[2:5]
	s_waitcnt vmcnt(12) lgkmcnt(6)
	v_mfma_f32_16x16x32_bf16 v[6:9], v[22:25], v[42:45], v[6:9]
	v_mfma_f32_16x16x32_bf16 v[2:5], v[22:25], v[46:49], v[2:5]
	s_waitcnt vmcnt(10) lgkmcnt(5)
	v_mfma_f32_16x16x32_bf16 v[6:9], v[26:29], v[50:53], v[6:9]
	v_mfma_f32_16x16x32_bf16 v[2:5], v[26:29], v[54:57], v[2:5]
	s_waitcnt vmcnt(8) lgkmcnt(4)
	v_mfma_f32_16x16x32_bf16 v[6:9], v[30:33], v[58:61], v[6:9]
	v_mfma_f32_16x16x32_bf16 v[2:5], v[30:33], v[62:65], v[2:5]
	ds_read_b128 v[18:21], v114 offset:512
	ds_read_b128 v[22:25], v115 offset:512
	ds_read_b128 v[26:29], v114 offset:640
	ds_read_b128 v[30:33], v115 offset:640
	global_load_dwordx4 v[34:37], v[10:11], off offset:512
	global_load_dwordx4 v[38:41], v[14:15], off offset:512
	global_load_dwordx4 v[42:45], v[10:11], off offset:576
	global_load_dwordx4 v[46:49], v[14:15], off offset:576
	global_load_dwordx4 v[50:53], v[10:11], off offset:640
	global_load_dwordx4 v[54:57], v[14:15], off offset:640
	global_load_dwordx4 v[58:61], v[10:11], off offset:704
	global_load_dwordx4 v[62:65], v[14:15], off offset:704
	s_waitcnt vmcnt(14) lgkmcnt(7)
	v_mfma_f32_16x16x32_bf16 v[6:9], v[66:69], v[82:85], v[6:9]
	v_mfma_f32_16x16x32_bf16 v[2:5], v[66:69], v[86:89], v[2:5]
	s_waitcnt vmcnt(12) lgkmcnt(6)
	v_mfma_f32_16x16x32_bf16 v[6:9], v[70:73], v[90:93], v[6:9]
	v_mfma_f32_16x16x32_bf16 v[2:5], v[70:73], v[94:97], v[2:5]
	s_waitcnt vmcnt(10) lgkmcnt(5)
	v_mfma_f32_16x16x32_bf16 v[6:9], v[74:77], v[98:101], v[6:9]
	v_mfma_f32_16x16x32_bf16 v[2:5], v[74:77], v[102:105], v[2:5]
	s_waitcnt vmcnt(8) lgkmcnt(4)
	v_mfma_f32_16x16x32_bf16 v[6:9], v[78:81], v[106:109], v[6:9]
	v_mfma_f32_16x16x32_bf16 v[2:5], v[78:81], v[110:113], v[2:5]
	ds_read_b128 v[66:69], v114 offset:768
	ds_read_b128 v[70:73], v115 offset:768
	ds_read_b128 v[74:77], v114 offset:896
	ds_read_b128 v[78:81], v115 offset:896
	global_load_dwordx4 v[82:85], v[10:11], off offset:768
	global_load_dwordx4 v[86:89], v[14:15], off offset:768
	global_load_dwordx4 v[90:93], v[10:11], off offset:832
	global_load_dwordx4 v[94:97], v[14:15], off offset:832
	global_load_dwordx4 v[98:101], v[10:11], off offset:896
	global_load_dwordx4 v[102:105], v[14:15], off offset:896
	global_load_dwordx4 v[106:109], v[10:11], off offset:960
	global_load_dwordx4 v[110:113], v[14:15], off offset:960
	s_waitcnt vmcnt(14) lgkmcnt(7)
	v_mfma_f32_16x16x32_bf16 v[6:9], v[18:21], v[34:37], v[6:9]
	v_mfma_f32_16x16x32_bf16 v[2:5], v[18:21], v[38:41], v[2:5]
	s_waitcnt vmcnt(12) lgkmcnt(6)
	v_mfma_f32_16x16x32_bf16 v[6:9], v[22:25], v[42:45], v[6:9]
	v_mfma_f32_16x16x32_bf16 v[2:5], v[22:25], v[46:49], v[2:5]
	s_waitcnt vmcnt(10) lgkmcnt(5)
	v_mfma_f32_16x16x32_bf16 v[6:9], v[26:29], v[50:53], v[6:9]
	v_mfma_f32_16x16x32_bf16 v[2:5], v[26:29], v[54:57], v[2:5]
	s_waitcnt vmcnt(8) lgkmcnt(4)
	v_mfma_f32_16x16x32_bf16 v[6:9], v[30:33], v[58:61], v[6:9]
	v_mfma_f32_16x16x32_bf16 v[2:5], v[30:33], v[62:65], v[2:5]
	ds_read_b128 v[18:21], v114 offset:1024
	ds_read_b128 v[22:25], v115 offset:1024
	ds_read_b128 v[26:29], v114 offset:1152
	ds_read_b128 v[30:33], v115 offset:1152
	global_load_dwordx4 v[34:37], v[10:11], off offset:1024
	global_load_dwordx4 v[38:41], v[14:15], off offset:1024
	global_load_dwordx4 v[42:45], v[10:11], off offset:1088
	global_load_dwordx4 v[46:49], v[14:15], off offset:1088
	global_load_dwordx4 v[50:53], v[10:11], off offset:1152
	global_load_dwordx4 v[54:57], v[14:15], off offset:1152
	global_load_dwordx4 v[58:61], v[10:11], off offset:1216
	global_load_dwordx4 v[62:65], v[14:15], off offset:1216
	s_waitcnt vmcnt(14) lgkmcnt(7)
	v_mfma_f32_16x16x32_bf16 v[6:9], v[66:69], v[82:85], v[6:9]
	v_mfma_f32_16x16x32_bf16 v[2:5], v[66:69], v[86:89], v[2:5]
	s_waitcnt vmcnt(12) lgkmcnt(6)
	v_mfma_f32_16x16x32_bf16 v[6:9], v[70:73], v[90:93], v[6:9]
	v_mfma_f32_16x16x32_bf16 v[2:5], v[70:73], v[94:97], v[2:5]
	s_waitcnt vmcnt(10) lgkmcnt(5)
	v_mfma_f32_16x16x32_bf16 v[6:9], v[74:77], v[98:101], v[6:9]
	v_mfma_f32_16x16x32_bf16 v[2:5], v[74:77], v[102:105], v[2:5]
	s_waitcnt vmcnt(8) lgkmcnt(4)
	v_mfma_f32_16x16x32_bf16 v[6:9], v[78:81], v[106:109], v[6:9]
	v_mfma_f32_16x16x32_bf16 v[2:5], v[78:81], v[110:113], v[2:5]
	ds_read_b128 v[66:69], v114 offset:1280
	ds_read_b128 v[70:73], v115 offset:1280
	ds_read_b128 v[74:77], v114 offset:1408
	ds_read_b128 v[78:81], v115 offset:1408
	global_load_dwordx4 v[82:85], v[10:11], off offset:1280
	global_load_dwordx4 v[86:89], v[14:15], off offset:1280
	global_load_dwordx4 v[90:93], v[10:11], off offset:1344
	global_load_dwordx4 v[94:97], v[14:15], off offset:1344
	global_load_dwordx4 v[98:101], v[10:11], off offset:1408
	global_load_dwordx4 v[102:105], v[14:15], off offset:1408
	global_load_dwordx4 v[106:109], v[10:11], off offset:1472
	global_load_dwordx4 v[110:113], v[14:15], off offset:1472
	s_waitcnt vmcnt(14) lgkmcnt(7)
	v_mfma_f32_16x16x32_bf16 v[6:9], v[18:21], v[34:37], v[6:9]
	v_mfma_f32_16x16x32_bf16 v[2:5], v[18:21], v[38:41], v[2:5]
	s_waitcnt vmcnt(12) lgkmcnt(6)
	v_mfma_f32_16x16x32_bf16 v[6:9], v[22:25], v[42:45], v[6:9]
	v_mfma_f32_16x16x32_bf16 v[2:5], v[22:25], v[46:49], v[2:5]
	s_waitcnt vmcnt(10) lgkmcnt(5)
	v_mfma_f32_16x16x32_bf16 v[6:9], v[26:29], v[50:53], v[6:9]
	v_mfma_f32_16x16x32_bf16 v[2:5], v[26:29], v[54:57], v[2:5]
	s_waitcnt vmcnt(8) lgkmcnt(4)
	v_mfma_f32_16x16x32_bf16 v[6:9], v[30:33], v[58:61], v[6:9]
	v_mfma_f32_16x16x32_bf16 v[2:5], v[30:33], v[62:65], v[2:5]
	ds_read_b128 v[18:21], v114 offset:1536
	ds_read_b128 v[22:25], v115 offset:1536
	ds_read_b128 v[26:29], v114 offset:1664
	ds_read_b128 v[30:33], v115 offset:1664
	global_load_dwordx4 v[34:37], v[10:11], off offset:1536
	global_load_dwordx4 v[38:41], v[14:15], off offset:1536
	global_load_dwordx4 v[42:45], v[10:11], off offset:1600
	global_load_dwordx4 v[46:49], v[14:15], off offset:1600
	global_load_dwordx4 v[50:53], v[10:11], off offset:1664
	global_load_dwordx4 v[54:57], v[14:15], off offset:1664
	global_load_dwordx4 v[58:61], v[10:11], off offset:1728
	global_load_dwordx4 v[62:65], v[14:15], off offset:1728
	s_waitcnt vmcnt(14) lgkmcnt(7)
	v_mfma_f32_16x16x32_bf16 v[6:9], v[66:69], v[82:85], v[6:9]
	v_mfma_f32_16x16x32_bf16 v[2:5], v[66:69], v[86:89], v[2:5]
	s_waitcnt vmcnt(12) lgkmcnt(6)
	v_mfma_f32_16x16x32_bf16 v[6:9], v[70:73], v[90:93], v[6:9]
	v_mfma_f32_16x16x32_bf16 v[2:5], v[70:73], v[94:97], v[2:5]
	s_waitcnt vmcnt(10) lgkmcnt(5)
	v_mfma_f32_16x16x32_bf16 v[6:9], v[74:77], v[98:101], v[6:9]
	v_mfma_f32_16x16x32_bf16 v[2:5], v[74:77], v[102:105], v[2:5]
	s_waitcnt vmcnt(8) lgkmcnt(4)
	v_mfma_f32_16x16x32_bf16 v[6:9], v[78:81], v[106:109], v[6:9]
	v_mfma_f32_16x16x32_bf16 v[2:5], v[78:81], v[110:113], v[2:5]
	ds_read_b128 v[66:69], v114 offset:1792
	ds_read_b128 v[70:73], v115 offset:1792
	ds_read_b128 v[74:77], v114 offset:1920
	ds_read_b128 v[78:81], v115 offset:1920
	global_load_dwordx4 v[82:85], v[10:11], off offset:1792
	global_load_dwordx4 v[86:89], v[14:15], off offset:1792
	global_load_dwordx4 v[90:93], v[10:11], off offset:1856
	global_load_dwordx4 v[94:97], v[14:15], off offset:1856
	global_load_dwordx4 v[98:101], v[10:11], off offset:1920
	global_load_dwordx4 v[102:105], v[14:15], off offset:1920
	global_load_dwordx4 v[106:109], v[10:11], off offset:1984
	global_load_dwordx4 v[110:113], v[14:15], off offset:1984
	s_waitcnt vmcnt(14) lgkmcnt(7)
	v_mfma_f32_16x16x32_bf16 v[6:9], v[18:21], v[34:37], v[6:9]
	v_mfma_f32_16x16x32_bf16 v[2:5], v[18:21], v[38:41], v[2:5]
	s_waitcnt vmcnt(12) lgkmcnt(6)
	v_mfma_f32_16x16x32_bf16 v[6:9], v[22:25], v[42:45], v[6:9]
	v_mfma_f32_16x16x32_bf16 v[2:5], v[22:25], v[46:49], v[2:5]
	s_waitcnt vmcnt(10) lgkmcnt(5)
	v_mfma_f32_16x16x32_bf16 v[6:9], v[26:29], v[50:53], v[6:9]
	v_mfma_f32_16x16x32_bf16 v[2:5], v[26:29], v[54:57], v[2:5]
	s_waitcnt vmcnt(8) lgkmcnt(4)
	v_mfma_f32_16x16x32_bf16 v[6:9], v[30:33], v[58:61], v[6:9]
	v_mfma_f32_16x16x32_bf16 v[2:5], v[30:33], v[62:65], v[2:5]
	ds_read_b128 v[18:21], v116 offset:2048
	ds_read_b128 v[22:25], v117 offset:2048
	ds_read_b128 v[26:29], v116 offset:2176
	ds_read_b128 v[30:33], v117 offset:2176
	global_load_dwordx4 v[34:37], v[10:11], off offset:2048
	global_load_dwordx4 v[38:41], v[14:15], off offset:2048
	global_load_dwordx4 v[42:45], v[10:11], off offset:2112
	global_load_dwordx4 v[46:49], v[14:15], off offset:2112
	global_load_dwordx4 v[50:53], v[10:11], off offset:2176
	global_load_dwordx4 v[54:57], v[14:15], off offset:2176
	global_load_dwordx4 v[58:61], v[10:11], off offset:2240
	global_load_dwordx4 v[62:65], v[14:15], off offset:2240
	s_waitcnt vmcnt(14) lgkmcnt(7)
	v_mfma_f32_16x16x32_bf16 v[6:9], v[66:69], v[82:85], v[6:9]
	v_mfma_f32_16x16x32_bf16 v[2:5], v[66:69], v[86:89], v[2:5]
	s_waitcnt vmcnt(12) lgkmcnt(6)
	v_mfma_f32_16x16x32_bf16 v[6:9], v[70:73], v[90:93], v[6:9]
	v_mfma_f32_16x16x32_bf16 v[2:5], v[70:73], v[94:97], v[2:5]
	s_waitcnt vmcnt(10) lgkmcnt(5)
	v_mfma_f32_16x16x32_bf16 v[6:9], v[74:77], v[98:101], v[6:9]
	v_mfma_f32_16x16x32_bf16 v[2:5], v[74:77], v[102:105], v[2:5]
	s_waitcnt vmcnt(8) lgkmcnt(4)
	v_mfma_f32_16x16x32_bf16 v[6:9], v[78:81], v[106:109], v[6:9]
	v_mfma_f32_16x16x32_bf16 v[2:5], v[78:81], v[110:113], v[2:5]
	ds_read_b128 v[66:69], v116 offset:2304
	ds_read_b128 v[70:73], v117 offset:2304
	ds_read_b128 v[74:77], v116 offset:2432
	ds_read_b128 v[78:81], v117 offset:2432
	global_load_dwordx4 v[82:85], v[10:11], off offset:2304
	global_load_dwordx4 v[86:89], v[14:15], off offset:2304
	global_load_dwordx4 v[90:93], v[10:11], off offset:2368
	global_load_dwordx4 v[94:97], v[14:15], off offset:2368
	global_load_dwordx4 v[98:101], v[10:11], off offset:2432
	global_load_dwordx4 v[102:105], v[14:15], off offset:2432
	global_load_dwordx4 v[106:109], v[10:11], off offset:2496
	global_load_dwordx4 v[110:113], v[14:15], off offset:2496
	s_waitcnt vmcnt(14) lgkmcnt(7)
	v_mfma_f32_16x16x32_bf16 v[6:9], v[18:21], v[34:37], v[6:9]
	v_mfma_f32_16x16x32_bf16 v[2:5], v[18:21], v[38:41], v[2:5]
	s_waitcnt vmcnt(12) lgkmcnt(6)
	v_mfma_f32_16x16x32_bf16 v[6:9], v[22:25], v[42:45], v[6:9]
	v_mfma_f32_16x16x32_bf16 v[2:5], v[22:25], v[46:49], v[2:5]
	s_waitcnt vmcnt(10) lgkmcnt(5)
	v_mfma_f32_16x16x32_bf16 v[6:9], v[26:29], v[50:53], v[6:9]
	v_mfma_f32_16x16x32_bf16 v[2:5], v[26:29], v[54:57], v[2:5]
	s_waitcnt vmcnt(8) lgkmcnt(4)
	v_mfma_f32_16x16x32_bf16 v[6:9], v[30:33], v[58:61], v[6:9]
	v_mfma_f32_16x16x32_bf16 v[2:5], v[30:33], v[62:65], v[2:5]
	s_waitcnt vmcnt(6) lgkmcnt(3)
	v_mfma_f32_16x16x32_bf16 v[6:9], v[66:69], v[82:85], v[6:9]
	v_mfma_f32_16x16x32_bf16 v[2:5], v[66:69], v[86:89], v[2:5]
	s_waitcnt vmcnt(4) lgkmcnt(2)
	v_mfma_f32_16x16x32_bf16 v[6:9], v[70:73], v[90:93], v[6:9]
	v_mfma_f32_16x16x32_bf16 v[2:5], v[70:73], v[94:97], v[2:5]
	s_waitcnt vmcnt(2) lgkmcnt(1)
	v_mfma_f32_16x16x32_bf16 v[6:9], v[74:77], v[98:101], v[6:9]
	v_mfma_f32_16x16x32_bf16 v[2:5], v[74:77], v[102:105], v[2:5]
	s_waitcnt vmcnt(0) lgkmcnt(0)
	v_mfma_f32_16x16x32_bf16 v[6:9], v[78:81], v[106:109], v[6:9]
	v_mfma_f32_16x16x32_bf16 v[2:5], v[78:81], v[110:113], v[2:5]
	s_branch .Lcmp_done
.Lcmp_rot6:
	ds_read_b128 v[18:21], v116 offset:3072
	ds_read_b128 v[22:25], v117 offset:3072
	ds_read_b128 v[26:29], v116 offset:3200
	ds_read_b128 v[30:33], v117 offset:3200
	global_load_dwordx4 v[34:37], v[10:11], off offset:3072
	global_load_dwordx4 v[38:41], v[14:15], off offset:3072
	global_load_dwordx4 v[42:45], v[10:11], off offset:3136
	global_load_dwordx4 v[46:49], v[14:15], off offset:3136
	global_load_dwordx4 v[50:53], v[10:11], off offset:3200
	global_load_dwordx4 v[54:57], v[14:15], off offset:3200
	global_load_dwordx4 v[58:61], v[10:11], off offset:3264
	global_load_dwordx4 v[62:65], v[14:15], off offset:3264
	ds_read_b128 v[66:69], v116 offset:3328
	ds_read_b128 v[70:73], v117 offset:3328
	ds_read_b128 v[74:77], v116 offset:3456
	ds_read_b128 v[78:81], v117 offset:3456
	global_load_dwordx4 v[82:85], v[10:11], off offset:3328
	global_load_dwordx4 v[86:89], v[14:15], off offset:3328
	global_load_dwordx4 v[90:93], v[10:11], off offset:3392
	global_load_dwordx4 v[94:97], v[14:15], off offset:3392
	global_load_dwordx4 v[98:101], v[10:11], off offset:3456
	global_load_dwordx4 v[102:105], v[14:15], off offset:3456
	global_load_dwordx4 v[106:109], v[10:11], off offset:3520
	global_load_dwordx4 v[110:113], v[14:15], off offset:3520
	s_waitcnt vmcnt(14) lgkmcnt(7)
	v_mfma_f32_16x16x32_bf16 v[6:9], v[18:21], v[34:37], v[6:9]
	v_mfma_f32_16x16x32_bf16 v[2:5], v[18:21], v[38:41], v[2:5]
	s_waitcnt vmcnt(12) lgkmcnt(6)
	v_mfma_f32_16x16x32_bf16 v[6:9], v[22:25], v[42:45], v[6:9]
	v_mfma_f32_16x16x32_bf16 v[2:5], v[22:25], v[46:49], v[2:5]
	s_waitcnt vmcnt(10) lgkmcnt(5)
	v_mfma_f32_16x16x32_bf16 v[6:9], v[26:29], v[50:53], v[6:9]
	v_mfma_f32_16x16x32_bf16 v[2:5], v[26:29], v[54:57], v[2:5]
	s_waitcnt vmcnt(8) lgkmcnt(4)
	v_mfma_f32_16x16x32_bf16 v[6:9], v[30:33], v[58:61], v[6:9]
	v_mfma_f32_16x16x32_bf16 v[2:5], v[30:33], v[62:65], v[2:5]
	ds_read_b128 v[18:21], v116 offset:3584
	ds_read_b128 v[22:25], v117 offset:3584
	ds_read_b128 v[26:29], v116 offset:3712
	ds_read_b128 v[30:33], v117 offset:3712
	global_load_dwordx4 v[34:37], v[10:11], off offset:3584
	global_load_dwordx4 v[38:41], v[14:15], off offset:3584
	global_load_dwordx4 v[42:45], v[10:11], off offset:3648
	global_load_dwordx4 v[46:49], v[14:15], off offset:3648
	global_load_dwordx4 v[50:53], v[10:11], off offset:3712
	global_load_dwordx4 v[54:57], v[14:15], off offset:3712
	global_load_dwordx4 v[58:61], v[10:11], off offset:3776
	global_load_dwordx4 v[62:65], v[14:15], off offset:3776
	s_waitcnt vmcnt(14) lgkmcnt(7)
	v_mfma_f32_16x16x32_bf16 v[6:9], v[66:69], v[82:85], v[6:9]
	v_mfma_f32_16x16x32_bf16 v[2:5], v[66:69], v[86:89], v[2:5]
	s_waitcnt vmcnt(12) lgkmcnt(6)
	v_mfma_f32_16x16x32_bf16 v[6:9], v[70:73], v[90:93], v[6:9]
	v_mfma_f32_16x16x32_bf16 v[2:5], v[70:73], v[94:97], v[2:5]
	s_waitcnt vmcnt(10) lgkmcnt(5)
	v_mfma_f32_16x16x32_bf16 v[6:9], v[74:77], v[98:101], v[6:9]
	v_mfma_f32_16x16x32_bf16 v[2:5], v[74:77], v[102:105], v[2:5]
	s_waitcnt vmcnt(8) lgkmcnt(4)
	v_mfma_f32_16x16x32_bf16 v[6:9], v[78:81], v[106:109], v[6:9]
	v_mfma_f32_16x16x32_bf16 v[2:5], v[78:81], v[110:113], v[2:5]
	ds_read_b128 v[66:69], v116 offset:3840
	ds_read_b128 v[70:73], v117 offset:3840
	ds_read_b128 v[74:77], v116 offset:3968
	ds_read_b128 v[78:81], v117 offset:3968
	global_load_dwordx4 v[82:85], v[10:11], off offset:3840
	global_load_dwordx4 v[86:89], v[14:15], off offset:3840
	global_load_dwordx4 v[90:93], v[10:11], off offset:3904
	global_load_dwordx4 v[94:97], v[14:15], off offset:3904
	global_load_dwordx4 v[98:101], v[10:11], off offset:3968
	global_load_dwordx4 v[102:105], v[14:15], off offset:3968
	global_load_dwordx4 v[106:109], v[10:11], off offset:4032
	global_load_dwordx4 v[110:113], v[14:15], off offset:4032
	s_waitcnt vmcnt(14) lgkmcnt(7)
	v_mfma_f32_16x16x32_bf16 v[6:9], v[18:21], v[34:37], v[6:9]
	v_mfma_f32_16x16x32_bf16 v[2:5], v[18:21], v[38:41], v[2:5]
	s_waitcnt vmcnt(12) lgkmcnt(6)
	v_mfma_f32_16x16x32_bf16 v[6:9], v[22:25], v[42:45], v[6:9]
	v_mfma_f32_16x16x32_bf16 v[2:5], v[22:25], v[46:49], v[2:5]
	s_waitcnt vmcnt(10) lgkmcnt(5)
	v_mfma_f32_16x16x32_bf16 v[6:9], v[26:29], v[50:53], v[6:9]
	v_mfma_f32_16x16x32_bf16 v[2:5], v[26:29], v[54:57], v[2:5]
	s_waitcnt vmcnt(8) lgkmcnt(4)
	v_mfma_f32_16x16x32_bf16 v[6:9], v[30:33], v[58:61], v[6:9]
	v_mfma_f32_16x16x32_bf16 v[2:5], v[30:33], v[62:65], v[2:5]
	ds_read_b128 v[18:21], v114
	ds_read_b128 v[22:25], v115
	ds_read_b128 v[26:29], v114 offset:128
	ds_read_b128 v[30:33], v115 offset:128
	global_load_dwordx4 v[34:37], v[10:11], off
	global_load_dwordx4 v[38:41], v[14:15], off
	global_load_dwordx4 v[42:45], v[10:11], off offset:64
	global_load_dwordx4 v[46:49], v[14:15], off offset:64
	global_load_dwordx4 v[50:53], v[10:11], off offset:128
	global_load_dwordx4 v[54:57], v[14:15], off offset:128
	global_load_dwordx4 v[58:61], v[10:11], off offset:192
	global_load_dwordx4 v[62:65], v[14:15], off offset:192
	s_waitcnt vmcnt(14) lgkmcnt(7)
	v_mfma_f32_16x16x32_bf16 v[6:9], v[66:69], v[82:85], v[6:9]
	v_mfma_f32_16x16x32_bf16 v[2:5], v[66:69], v[86:89], v[2:5]
	s_waitcnt vmcnt(12) lgkmcnt(6)
	v_mfma_f32_16x16x32_bf16 v[6:9], v[70:73], v[90:93], v[6:9]
	v_mfma_f32_16x16x32_bf16 v[2:5], v[70:73], v[94:97], v[2:5]
	s_waitcnt vmcnt(10) lgkmcnt(5)
	v_mfma_f32_16x16x32_bf16 v[6:9], v[74:77], v[98:101], v[6:9]
	v_mfma_f32_16x16x32_bf16 v[2:5], v[74:77], v[102:105], v[2:5]
	s_waitcnt vmcnt(8) lgkmcnt(4)
	v_mfma_f32_16x16x32_bf16 v[6:9], v[78:81], v[106:109], v[6:9]
	v_mfma_f32_16x16x32_bf16 v[2:5], v[78:81], v[110:113], v[2:5]
	ds_read_b128 v[66:69], v114 offset:256
	ds_read_b128 v[70:73], v115 offset:256
	ds_read_b128 v[74:77], v114 offset:384
	ds_read_b128 v[78:81], v115 offset:384
	global_load_dwordx4 v[82:85], v[10:11], off offset:256
	global_load_dwordx4 v[86:89], v[14:15], off offset:256
	global_load_dwordx4 v[90:93], v[10:11], off offset:320
	global_load_dwordx4 v[94:97], v[14:15], off offset:320
	global_load_dwordx4 v[98:101], v[10:11], off offset:384
	global_load_dwordx4 v[102:105], v[14:15], off offset:384
	global_load_dwordx4 v[106:109], v[10:11], off offset:448
	global_load_dwordx4 v[110:113], v[14:15], off offset:448
	s_waitcnt vmcnt(14) lgkmcnt(7)
	v_mfma_f32_16x16x32_bf16 v[6:9], v[18:21], v[34:37], v[6:9]
	v_mfma_f32_16x16x32_bf16 v[2:5], v[18:21], v[38:41], v[2:5]
	s_waitcnt vmcnt(12) lgkmcnt(6)
	v_mfma_f32_16x16x32_bf16 v[6:9], v[22:25], v[42:45], v[6:9]
	v_mfma_f32_16x16x32_bf16 v[2:5], v[22:25], v[46:49], v[2:5]
	s_waitcnt vmcnt(10) lgkmcnt(5)
	v_mfma_f32_16x16x32_bf16 v[6:9], v[26:29], v[50:53], v[6:9]
	v_mfma_f32_16x16x32_bf16 v[2:5], v[26:29], v[54:57], v[2:5]
	s_waitcnt vmcnt(8) lgkmcnt(4)
	v_mfma_f32_16x16x32_bf16 v[6:9], v[30:33], v[58:61], v[6:9]
	v_mfma_f32_16x16x32_bf16 v[2:5], v[30:33], v[62:65], v[2:5]
	ds_read_b128 v[18:21], v114 offset:512
	ds_read_b128 v[22:25], v115 offset:512
	ds_read_b128 v[26:29], v114 offset:640
	ds_read_b128 v[30:33], v115 offset:640
	global_load_dwordx4 v[34:37], v[10:11], off offset:512
	global_load_dwordx4 v[38:41], v[14:15], off offset:512
	global_load_dwordx4 v[42:45], v[10:11], off offset:576
	global_load_dwordx4 v[46:49], v[14:15], off offset:576
	global_load_dwordx4 v[50:53], v[10:11], off offset:640
	global_load_dwordx4 v[54:57], v[14:15], off offset:640
	global_load_dwordx4 v[58:61], v[10:11], off offset:704
	global_load_dwordx4 v[62:65], v[14:15], off offset:704
	s_waitcnt vmcnt(14) lgkmcnt(7)
	v_mfma_f32_16x16x32_bf16 v[6:9], v[66:69], v[82:85], v[6:9]
	v_mfma_f32_16x16x32_bf16 v[2:5], v[66:69], v[86:89], v[2:5]
	s_waitcnt vmcnt(12) lgkmcnt(6)
	v_mfma_f32_16x16x32_bf16 v[6:9], v[70:73], v[90:93], v[6:9]
	v_mfma_f32_16x16x32_bf16 v[2:5], v[70:73], v[94:97], v[2:5]
	s_waitcnt vmcnt(10) lgkmcnt(5)
	v_mfma_f32_16x16x32_bf16 v[6:9], v[74:77], v[98:101], v[6:9]
	v_mfma_f32_16x16x32_bf16 v[2:5], v[74:77], v[102:105], v[2:5]
	s_waitcnt vmcnt(8) lgkmcnt(4)
	v_mfma_f32_16x16x32_bf16 v[6:9], v[78:81], v[106:109], v[6:9]
	v_mfma_f32_16x16x32_bf16 v[2:5], v[78:81], v[110:113], v[2:5]
	ds_read_b128 v[66:69], v114 offset:768
	ds_read_b128 v[70:73], v115 offset:768
	ds_read_b128 v[74:77], v114 offset:896
	ds_read_b128 v[78:81], v115 offset:896
	global_load_dwordx4 v[82:85], v[10:11], off offset:768
	global_load_dwordx4 v[86:89], v[14:15], off offset:768
	global_load_dwordx4 v[90:93], v[10:11], off offset:832
	global_load_dwordx4 v[94:97], v[14:15], off offset:832
	global_load_dwordx4 v[98:101], v[10:11], off offset:896
	global_load_dwordx4 v[102:105], v[14:15], off offset:896
	global_load_dwordx4 v[106:109], v[10:11], off offset:960
	global_load_dwordx4 v[110:113], v[14:15], off offset:960
	s_waitcnt vmcnt(14) lgkmcnt(7)
	v_mfma_f32_16x16x32_bf16 v[6:9], v[18:21], v[34:37], v[6:9]
	v_mfma_f32_16x16x32_bf16 v[2:5], v[18:21], v[38:41], v[2:5]
	s_waitcnt vmcnt(12) lgkmcnt(6)
	v_mfma_f32_16x16x32_bf16 v[6:9], v[22:25], v[42:45], v[6:9]
	v_mfma_f32_16x16x32_bf16 v[2:5], v[22:25], v[46:49], v[2:5]
	s_waitcnt vmcnt(10) lgkmcnt(5)
	v_mfma_f32_16x16x32_bf16 v[6:9], v[26:29], v[50:53], v[6:9]
	v_mfma_f32_16x16x32_bf16 v[2:5], v[26:29], v[54:57], v[2:5]
	s_waitcnt vmcnt(8) lgkmcnt(4)
	v_mfma_f32_16x16x32_bf16 v[6:9], v[30:33], v[58:61], v[6:9]
	v_mfma_f32_16x16x32_bf16 v[2:5], v[30:33], v[62:65], v[2:5]
	ds_read_b128 v[18:21], v114 offset:1024
	ds_read_b128 v[22:25], v115 offset:1024
	ds_read_b128 v[26:29], v114 offset:1152
	ds_read_b128 v[30:33], v115 offset:1152
	global_load_dwordx4 v[34:37], v[10:11], off offset:1024
	global_load_dwordx4 v[38:41], v[14:15], off offset:1024
	global_load_dwordx4 v[42:45], v[10:11], off offset:1088
	global_load_dwordx4 v[46:49], v[14:15], off offset:1088
	global_load_dwordx4 v[50:53], v[10:11], off offset:1152
	global_load_dwordx4 v[54:57], v[14:15], off offset:1152
	global_load_dwordx4 v[58:61], v[10:11], off offset:1216
	global_load_dwordx4 v[62:65], v[14:15], off offset:1216
	s_waitcnt vmcnt(14) lgkmcnt(7)
	v_mfma_f32_16x16x32_bf16 v[6:9], v[66:69], v[82:85], v[6:9]
	v_mfma_f32_16x16x32_bf16 v[2:5], v[66:69], v[86:89], v[2:5]
	s_waitcnt vmcnt(12) lgkmcnt(6)
	v_mfma_f32_16x16x32_bf16 v[6:9], v[70:73], v[90:93], v[6:9]
	v_mfma_f32_16x16x32_bf16 v[2:5], v[70:73], v[94:97], v[2:5]
	s_waitcnt vmcnt(10) lgkmcnt(5)
	v_mfma_f32_16x16x32_bf16 v[6:9], v[74:77], v[98:101], v[6:9]
	v_mfma_f32_16x16x32_bf16 v[2:5], v[74:77], v[102:105], v[2:5]
	s_waitcnt vmcnt(8) lgkmcnt(4)
	v_mfma_f32_16x16x32_bf16 v[6:9], v[78:81], v[106:109], v[6:9]
	v_mfma_f32_16x16x32_bf16 v[2:5], v[78:81], v[110:113], v[2:5]
	ds_read_b128 v[66:69], v114 offset:1280
	ds_read_b128 v[70:73], v115 offset:1280
	ds_read_b128 v[74:77], v114 offset:1408
	ds_read_b128 v[78:81], v115 offset:1408
	global_load_dwordx4 v[82:85], v[10:11], off offset:1280
	global_load_dwordx4 v[86:89], v[14:15], off offset:1280
	global_load_dwordx4 v[90:93], v[10:11], off offset:1344
	global_load_dwordx4 v[94:97], v[14:15], off offset:1344
	global_load_dwordx4 v[98:101], v[10:11], off offset:1408
	global_load_dwordx4 v[102:105], v[14:15], off offset:1408
	global_load_dwordx4 v[106:109], v[10:11], off offset:1472
	global_load_dwordx4 v[110:113], v[14:15], off offset:1472
	s_waitcnt vmcnt(14) lgkmcnt(7)
	v_mfma_f32_16x16x32_bf16 v[6:9], v[18:21], v[34:37], v[6:9]
	v_mfma_f32_16x16x32_bf16 v[2:5], v[18:21], v[38:41], v[2:5]
	s_waitcnt vmcnt(12) lgkmcnt(6)
	v_mfma_f32_16x16x32_bf16 v[6:9], v[22:25], v[42:45], v[6:9]
	v_mfma_f32_16x16x32_bf16 v[2:5], v[22:25], v[46:49], v[2:5]
	s_waitcnt vmcnt(10) lgkmcnt(5)
	v_mfma_f32_16x16x32_bf16 v[6:9], v[26:29], v[50:53], v[6:9]
	v_mfma_f32_16x16x32_bf16 v[2:5], v[26:29], v[54:57], v[2:5]
	s_waitcnt vmcnt(8) lgkmcnt(4)
	v_mfma_f32_16x16x32_bf16 v[6:9], v[30:33], v[58:61], v[6:9]
	v_mfma_f32_16x16x32_bf16 v[2:5], v[30:33], v[62:65], v[2:5]
	ds_read_b128 v[18:21], v114 offset:1536
	ds_read_b128 v[22:25], v115 offset:1536
	ds_read_b128 v[26:29], v114 offset:1664
	ds_read_b128 v[30:33], v115 offset:1664
	global_load_dwordx4 v[34:37], v[10:11], off offset:1536
	global_load_dwordx4 v[38:41], v[14:15], off offset:1536
	global_load_dwordx4 v[42:45], v[10:11], off offset:1600
	global_load_dwordx4 v[46:49], v[14:15], off offset:1600
	global_load_dwordx4 v[50:53], v[10:11], off offset:1664
	global_load_dwordx4 v[54:57], v[14:15], off offset:1664
	global_load_dwordx4 v[58:61], v[10:11], off offset:1728
	global_load_dwordx4 v[62:65], v[14:15], off offset:1728
	s_waitcnt vmcnt(14) lgkmcnt(7)
	v_mfma_f32_16x16x32_bf16 v[6:9], v[66:69], v[82:85], v[6:9]
	v_mfma_f32_16x16x32_bf16 v[2:5], v[66:69], v[86:89], v[2:5]
	s_waitcnt vmcnt(12) lgkmcnt(6)
	v_mfma_f32_16x16x32_bf16 v[6:9], v[70:73], v[90:93], v[6:9]
	v_mfma_f32_16x16x32_bf16 v[2:5], v[70:73], v[94:97], v[2:5]
	s_waitcnt vmcnt(10) lgkmcnt(5)
	v_mfma_f32_16x16x32_bf16 v[6:9], v[74:77], v[98:101], v[6:9]
	v_mfma_f32_16x16x32_bf16 v[2:5], v[74:77], v[102:105], v[2:5]
	s_waitcnt vmcnt(8) lgkmcnt(4)
	v_mfma_f32_16x16x32_bf16 v[6:9], v[78:81], v[106:109], v[6:9]
	v_mfma_f32_16x16x32_bf16 v[2:5], v[78:81], v[110:113], v[2:5]
	ds_read_b128 v[66:69], v114 offset:1792
	ds_read_b128 v[70:73], v115 offset:1792
	ds_read_b128 v[74:77], v114 offset:1920
	ds_read_b128 v[78:81], v115 offset:1920
	global_load_dwordx4 v[82:85], v[10:11], off offset:1792
	global_load_dwordx4 v[86:89], v[14:15], off offset:1792
	global_load_dwordx4 v[90:93], v[10:11], off offset:1856
	global_load_dwordx4 v[94:97], v[14:15], off offset:1856
	global_load_dwordx4 v[98:101], v[10:11], off offset:1920
	global_load_dwordx4 v[102:105], v[14:15], off offset:1920
	global_load_dwordx4 v[106:109], v[10:11], off offset:1984
	global_load_dwordx4 v[110:113], v[14:15], off offset:1984
	s_waitcnt vmcnt(14) lgkmcnt(7)
	v_mfma_f32_16x16x32_bf16 v[6:9], v[18:21], v[34:37], v[6:9]
	v_mfma_f32_16x16x32_bf16 v[2:5], v[18:21], v[38:41], v[2:5]
	s_waitcnt vmcnt(12) lgkmcnt(6)
	v_mfma_f32_16x16x32_bf16 v[6:9], v[22:25], v[42:45], v[6:9]
	v_mfma_f32_16x16x32_bf16 v[2:5], v[22:25], v[46:49], v[2:5]
	s_waitcnt vmcnt(10) lgkmcnt(5)
	v_mfma_f32_16x16x32_bf16 v[6:9], v[26:29], v[50:53], v[6:9]
	v_mfma_f32_16x16x32_bf16 v[2:5], v[26:29], v[54:57], v[2:5]
	s_waitcnt vmcnt(8) lgkmcnt(4)
	v_mfma_f32_16x16x32_bf16 v[6:9], v[30:33], v[58:61], v[6:9]
	v_mfma_f32_16x16x32_bf16 v[2:5], v[30:33], v[62:65], v[2:5]
	ds_read_b128 v[18:21], v116 offset:2048
	ds_read_b128 v[22:25], v117 offset:2048
	ds_read_b128 v[26:29], v116 offset:2176
	ds_read_b128 v[30:33], v117 offset:2176
	global_load_dwordx4 v[34:37], v[10:11], off offset:2048
	global_load_dwordx4 v[38:41], v[14:15], off offset:2048
	global_load_dwordx4 v[42:45], v[10:11], off offset:2112
	global_load_dwordx4 v[46:49], v[14:15], off offset:2112
	global_load_dwordx4 v[50:53], v[10:11], off offset:2176
	global_load_dwordx4 v[54:57], v[14:15], off offset:2176
	global_load_dwordx4 v[58:61], v[10:11], off offset:2240
	global_load_dwordx4 v[62:65], v[14:15], off offset:2240
	s_waitcnt vmcnt(14) lgkmcnt(7)
	v_mfma_f32_16x16x32_bf16 v[6:9], v[66:69], v[82:85], v[6:9]
	v_mfma_f32_16x16x32_bf16 v[2:5], v[66:69], v[86:89], v[2:5]
	s_waitcnt vmcnt(12) lgkmcnt(6)
	v_mfma_f32_16x16x32_bf16 v[6:9], v[70:73], v[90:93], v[6:9]
	v_mfma_f32_16x16x32_bf16 v[2:5], v[70:73], v[94:97], v[2:5]
	s_waitcnt vmcnt(10) lgkmcnt(5)
	v_mfma_f32_16x16x32_bf16 v[6:9], v[74:77], v[98:101], v[6:9]
	v_mfma_f32_16x16x32_bf16 v[2:5], v[74:77], v[102:105], v[2:5]
	s_waitcnt vmcnt(8) lgkmcnt(4)
	v_mfma_f32_16x16x32_bf16 v[6:9], v[78:81], v[106:109], v[6:9]
	v_mfma_f32_16x16x32_bf16 v[2:5], v[78:81], v[110:113], v[2:5]
	ds_read_b128 v[66:69], v116 offset:2304
	ds_read_b128 v[70:73], v117 offset:2304
	ds_read_b128 v[74:77], v116 offset:2432
	ds_read_b128 v[78:81], v117 offset:2432
	global_load_dwordx4 v[82:85], v[10:11], off offset:2304
	global_load_dwordx4 v[86:89], v[14:15], off offset:2304
	global_load_dwordx4 v[90:93], v[10:11], off offset:2368
	global_load_dwordx4 v[94:97], v[14:15], off offset:2368
	global_load_dwordx4 v[98:101], v[10:11], off offset:2432
	global_load_dwordx4 v[102:105], v[14:15], off offset:2432
	global_load_dwordx4 v[106:109], v[10:11], off offset:2496
	global_load_dwordx4 v[110:113], v[14:15], off offset:2496
	s_waitcnt vmcnt(14) lgkmcnt(7)
	v_mfma_f32_16x16x32_bf16 v[6:9], v[18:21], v[34:37], v[6:9]
	v_mfma_f32_16x16x32_bf16 v[2:5], v[18:21], v[38:41], v[2:5]
	s_waitcnt vmcnt(12) lgkmcnt(6)
	v_mfma_f32_16x16x32_bf16 v[6:9], v[22:25], v[42:45], v[6:9]
	v_mfma_f32_16x16x32_bf16 v[2:5], v[22:25], v[46:49], v[2:5]
	s_waitcnt vmcnt(10) lgkmcnt(5)
	v_mfma_f32_16x16x32_bf16 v[6:9], v[26:29], v[50:53], v[6:9]
	v_mfma_f32_16x16x32_bf16 v[2:5], v[26:29], v[54:57], v[2:5]
	s_waitcnt vmcnt(8) lgkmcnt(4)
	v_mfma_f32_16x16x32_bf16 v[6:9], v[30:33], v[58:61], v[6:9]
	v_mfma_f32_16x16x32_bf16 v[2:5], v[30:33], v[62:65], v[2:5]
	ds_read_b128 v[18:21], v116 offset:2560
	ds_read_b128 v[22:25], v117 offset:2560
	ds_read_b128 v[26:29], v116 offset:2688
	ds_read_b128 v[30:33], v117 offset:2688
	global_load_dwordx4 v[34:37], v[10:11], off offset:2560
	global_load_dwordx4 v[38:41], v[14:15], off offset:2560
	global_load_dwordx4 v[42:45], v[10:11], off offset:2624
	global_load_dwordx4 v[46:49], v[14:15], off offset:2624
	global_load_dwordx4 v[50:53], v[10:11], off offset:2688
	global_load_dwordx4 v[54:57], v[14:15], off offset:2688
	global_load_dwordx4 v[58:61], v[10:11], off offset:2752
	global_load_dwordx4 v[62:65], v[14:15], off offset:2752
	s_waitcnt vmcnt(14) lgkmcnt(7)
	v_mfma_f32_16x16x32_bf16 v[6:9], v[66:69], v[82:85], v[6:9]
	v_mfma_f32_16x16x32_bf16 v[2:5], v[66:69], v[86:89], v[2:5]
	s_waitcnt vmcnt(12) lgkmcnt(6)
	v_mfma_f32_16x16x32_bf16 v[6:9], v[70:73], v[90:93], v[6:9]
	v_mfma_f32_16x16x32_bf16 v[2:5], v[70:73], v[94:97], v[2:5]
	s_waitcnt vmcnt(10) lgkmcnt(5)
	v_mfma_f32_16x16x32_bf16 v[6:9], v[74:77], v[98:101], v[6:9]
	v_mfma_f32_16x16x32_bf16 v[2:5], v[74:77], v[102:105], v[2:5]
	s_waitcnt vmcnt(8) lgkmcnt(4)
	v_mfma_f32_16x16x32_bf16 v[6:9], v[78:81], v[106:109], v[6:9]
	v_mfma_f32_16x16x32_bf16 v[2:5], v[78:81], v[110:113], v[2:5]
	ds_read_b128 v[66:69], v116 offset:2816
	ds_read_b128 v[70:73], v117 offset:2816
	ds_read_b128 v[74:77], v116 offset:2944
	ds_read_b128 v[78:81], v117 offset:2944
	global_load_dwordx4 v[82:85], v[10:11], off offset:2816
	global_load_dwordx4 v[86:89], v[14:15], off offset:2816
	global_load_dwordx4 v[90:93], v[10:11], off offset:2880
	global_load_dwordx4 v[94:97], v[14:15], off offset:2880
	global_load_dwordx4 v[98:101], v[10:11], off offset:2944
	global_load_dwordx4 v[102:105], v[14:15], off offset:2944
	global_load_dwordx4 v[106:109], v[10:11], off offset:3008
	global_load_dwordx4 v[110:113], v[14:15], off offset:3008
	s_waitcnt vmcnt(14) lgkmcnt(7)
	v_mfma_f32_16x16x32_bf16 v[6:9], v[18:21], v[34:37], v[6:9]
	v_mfma_f32_16x16x32_bf16 v[2:5], v[18:21], v[38:41], v[2:5]
	s_waitcnt vmcnt(12) lgkmcnt(6)
	v_mfma_f32_16x16x32_bf16 v[6:9], v[22:25], v[42:45], v[6:9]
	v_mfma_f32_16x16x32_bf16 v[2:5], v[22:25], v[46:49], v[2:5]
	s_waitcnt vmcnt(10) lgkmcnt(5)
	v_mfma_f32_16x16x32_bf16 v[6:9], v[26:29], v[50:53], v[6:9]
	v_mfma_f32_16x16x32_bf16 v[2:5], v[26:29], v[54:57], v[2:5]
	s_waitcnt vmcnt(8) lgkmcnt(4)
	v_mfma_f32_16x16x32_bf16 v[6:9], v[30:33], v[58:61], v[6:9]
	v_mfma_f32_16x16x32_bf16 v[2:5], v[30:33], v[62:65], v[2:5]
	s_waitcnt vmcnt(6) lgkmcnt(3)
	v_mfma_f32_16x16x32_bf16 v[6:9], v[66:69], v[82:85], v[6:9]
	v_mfma_f32_16x16x32_bf16 v[2:5], v[66:69], v[86:89], v[2:5]
	s_waitcnt vmcnt(4) lgkmcnt(2)
	v_mfma_f32_16x16x32_bf16 v[6:9], v[70:73], v[90:93], v[6:9]
	v_mfma_f32_16x16x32_bf16 v[2:5], v[70:73], v[94:97], v[2:5]
	s_waitcnt vmcnt(2) lgkmcnt(1)
	v_mfma_f32_16x16x32_bf16 v[6:9], v[74:77], v[98:101], v[6:9]
	v_mfma_f32_16x16x32_bf16 v[2:5], v[74:77], v[102:105], v[2:5]
	s_waitcnt vmcnt(0) lgkmcnt(0)
	v_mfma_f32_16x16x32_bf16 v[6:9], v[78:81], v[106:109], v[6:9]
	v_mfma_f32_16x16x32_bf16 v[2:5], v[78:81], v[110:113], v[2:5]
	s_branch .Lcmp_done
.Lcmp_rot7:
	ds_read_b128 v[18:21], v116 offset:3584
	ds_read_b128 v[22:25], v117 offset:3584
	ds_read_b128 v[26:29], v116 offset:3712
	ds_read_b128 v[30:33], v117 offset:3712
	global_load_dwordx4 v[34:37], v[10:11], off offset:3584
	global_load_dwordx4 v[38:41], v[14:15], off offset:3584
	global_load_dwordx4 v[42:45], v[10:11], off offset:3648
	global_load_dwordx4 v[46:49], v[14:15], off offset:3648
	global_load_dwordx4 v[50:53], v[10:11], off offset:3712
	global_load_dwordx4 v[54:57], v[14:15], off offset:3712
	global_load_dwordx4 v[58:61], v[10:11], off offset:3776
	global_load_dwordx4 v[62:65], v[14:15], off offset:3776
	ds_read_b128 v[66:69], v116 offset:3840
	ds_read_b128 v[70:73], v117 offset:3840
	ds_read_b128 v[74:77], v116 offset:3968
	ds_read_b128 v[78:81], v117 offset:3968
	global_load_dwordx4 v[82:85], v[10:11], off offset:3840
	global_load_dwordx4 v[86:89], v[14:15], off offset:3840
	global_load_dwordx4 v[90:93], v[10:11], off offset:3904
	global_load_dwordx4 v[94:97], v[14:15], off offset:3904
	global_load_dwordx4 v[98:101], v[10:11], off offset:3968
	global_load_dwordx4 v[102:105], v[14:15], off offset:3968
	global_load_dwordx4 v[106:109], v[10:11], off offset:4032
	global_load_dwordx4 v[110:113], v[14:15], off offset:4032
	s_waitcnt vmcnt(14) lgkmcnt(7)
	v_mfma_f32_16x16x32_bf16 v[6:9], v[18:21], v[34:37], v[6:9]
	v_mfma_f32_16x16x32_bf16 v[2:5], v[18:21], v[38:41], v[2:5]
	s_waitcnt vmcnt(12) lgkmcnt(6)
	v_mfma_f32_16x16x32_bf16 v[6:9], v[22:25], v[42:45], v[6:9]
	v_mfma_f32_16x16x32_bf16 v[2:5], v[22:25], v[46:49], v[2:5]
	s_waitcnt vmcnt(10) lgkmcnt(5)
	v_mfma_f32_16x16x32_bf16 v[6:9], v[26:29], v[50:53], v[6:9]
	v_mfma_f32_16x16x32_bf16 v[2:5], v[26:29], v[54:57], v[2:5]
	s_waitcnt vmcnt(8) lgkmcnt(4)
	v_mfma_f32_16x16x32_bf16 v[6:9], v[30:33], v[58:61], v[6:9]
	v_mfma_f32_16x16x32_bf16 v[2:5], v[30:33], v[62:65], v[2:5]
	ds_read_b128 v[18:21], v114
	ds_read_b128 v[22:25], v115
	ds_read_b128 v[26:29], v114 offset:128
	ds_read_b128 v[30:33], v115 offset:128
	global_load_dwordx4 v[34:37], v[10:11], off
	global_load_dwordx4 v[38:41], v[14:15], off
	global_load_dwordx4 v[42:45], v[10:11], off offset:64
	global_load_dwordx4 v[46:49], v[14:15], off offset:64
	global_load_dwordx4 v[50:53], v[10:11], off offset:128
	global_load_dwordx4 v[54:57], v[14:15], off offset:128
	global_load_dwordx4 v[58:61], v[10:11], off offset:192
	global_load_dwordx4 v[62:65], v[14:15], off offset:192
	s_waitcnt vmcnt(14) lgkmcnt(7)
	v_mfma_f32_16x16x32_bf16 v[6:9], v[66:69], v[82:85], v[6:9]
	v_mfma_f32_16x16x32_bf16 v[2:5], v[66:69], v[86:89], v[2:5]
	s_waitcnt vmcnt(12) lgkmcnt(6)
	v_mfma_f32_16x16x32_bf16 v[6:9], v[70:73], v[90:93], v[6:9]
	v_mfma_f32_16x16x32_bf16 v[2:5], v[70:73], v[94:97], v[2:5]
	s_waitcnt vmcnt(10) lgkmcnt(5)
	v_mfma_f32_16x16x32_bf16 v[6:9], v[74:77], v[98:101], v[6:9]
	v_mfma_f32_16x16x32_bf16 v[2:5], v[74:77], v[102:105], v[2:5]
	s_waitcnt vmcnt(8) lgkmcnt(4)
	v_mfma_f32_16x16x32_bf16 v[6:9], v[78:81], v[106:109], v[6:9]
	v_mfma_f32_16x16x32_bf16 v[2:5], v[78:81], v[110:113], v[2:5]
	ds_read_b128 v[66:69], v114 offset:256
	ds_read_b128 v[70:73], v115 offset:256
	ds_read_b128 v[74:77], v114 offset:384
	ds_read_b128 v[78:81], v115 offset:384
	global_load_dwordx4 v[82:85], v[10:11], off offset:256
	global_load_dwordx4 v[86:89], v[14:15], off offset:256
	global_load_dwordx4 v[90:93], v[10:11], off offset:320
	global_load_dwordx4 v[94:97], v[14:15], off offset:320
	global_load_dwordx4 v[98:101], v[10:11], off offset:384
	global_load_dwordx4 v[102:105], v[14:15], off offset:384
	global_load_dwordx4 v[106:109], v[10:11], off offset:448
	global_load_dwordx4 v[110:113], v[14:15], off offset:448
	s_waitcnt vmcnt(14) lgkmcnt(7)
	v_mfma_f32_16x16x32_bf16 v[6:9], v[18:21], v[34:37], v[6:9]
	v_mfma_f32_16x16x32_bf16 v[2:5], v[18:21], v[38:41], v[2:5]
	s_waitcnt vmcnt(12) lgkmcnt(6)
	v_mfma_f32_16x16x32_bf16 v[6:9], v[22:25], v[42:45], v[6:9]
	v_mfma_f32_16x16x32_bf16 v[2:5], v[22:25], v[46:49], v[2:5]
	s_waitcnt vmcnt(10) lgkmcnt(5)
	v_mfma_f32_16x16x32_bf16 v[6:9], v[26:29], v[50:53], v[6:9]
	v_mfma_f32_16x16x32_bf16 v[2:5], v[26:29], v[54:57], v[2:5]
	s_waitcnt vmcnt(8) lgkmcnt(4)
	v_mfma_f32_16x16x32_bf16 v[6:9], v[30:33], v[58:61], v[6:9]
	v_mfma_f32_16x16x32_bf16 v[2:5], v[30:33], v[62:65], v[2:5]
	ds_read_b128 v[18:21], v114 offset:512
	ds_read_b128 v[22:25], v115 offset:512
	ds_read_b128 v[26:29], v114 offset:640
	ds_read_b128 v[30:33], v115 offset:640
	global_load_dwordx4 v[34:37], v[10:11], off offset:512
	global_load_dwordx4 v[38:41], v[14:15], off offset:512
	global_load_dwordx4 v[42:45], v[10:11], off offset:576
	global_load_dwordx4 v[46:49], v[14:15], off offset:576
	global_load_dwordx4 v[50:53], v[10:11], off offset:640
	global_load_dwordx4 v[54:57], v[14:15], off offset:640
	global_load_dwordx4 v[58:61], v[10:11], off offset:704
	global_load_dwordx4 v[62:65], v[14:15], off offset:704
	s_waitcnt vmcnt(14) lgkmcnt(7)
	v_mfma_f32_16x16x32_bf16 v[6:9], v[66:69], v[82:85], v[6:9]
	v_mfma_f32_16x16x32_bf16 v[2:5], v[66:69], v[86:89], v[2:5]
	s_waitcnt vmcnt(12) lgkmcnt(6)
	v_mfma_f32_16x16x32_bf16 v[6:9], v[70:73], v[90:93], v[6:9]
	v_mfma_f32_16x16x32_bf16 v[2:5], v[70:73], v[94:97], v[2:5]
	s_waitcnt vmcnt(10) lgkmcnt(5)
	v_mfma_f32_16x16x32_bf16 v[6:9], v[74:77], v[98:101], v[6:9]
	v_mfma_f32_16x16x32_bf16 v[2:5], v[74:77], v[102:105], v[2:5]
	s_waitcnt vmcnt(8) lgkmcnt(4)
	v_mfma_f32_16x16x32_bf16 v[6:9], v[78:81], v[106:109], v[6:9]
	v_mfma_f32_16x16x32_bf16 v[2:5], v[78:81], v[110:113], v[2:5]
	ds_read_b128 v[66:69], v114 offset:768
	ds_read_b128 v[70:73], v115 offset:768
	ds_read_b128 v[74:77], v114 offset:896
	ds_read_b128 v[78:81], v115 offset:896
	global_load_dwordx4 v[82:85], v[10:11], off offset:768
	global_load_dwordx4 v[86:89], v[14:15], off offset:768
	global_load_dwordx4 v[90:93], v[10:11], off offset:832
	global_load_dwordx4 v[94:97], v[14:15], off offset:832
	global_load_dwordx4 v[98:101], v[10:11], off offset:896
	global_load_dwordx4 v[102:105], v[14:15], off offset:896
	global_load_dwordx4 v[106:109], v[10:11], off offset:960
	global_load_dwordx4 v[110:113], v[14:15], off offset:960
	s_waitcnt vmcnt(14) lgkmcnt(7)
	v_mfma_f32_16x16x32_bf16 v[6:9], v[18:21], v[34:37], v[6:9]
	v_mfma_f32_16x16x32_bf16 v[2:5], v[18:21], v[38:41], v[2:5]
	s_waitcnt vmcnt(12) lgkmcnt(6)
	v_mfma_f32_16x16x32_bf16 v[6:9], v[22:25], v[42:45], v[6:9]
	v_mfma_f32_16x16x32_bf16 v[2:5], v[22:25], v[46:49], v[2:5]
	s_waitcnt vmcnt(10) lgkmcnt(5)
	v_mfma_f32_16x16x32_bf16 v[6:9], v[26:29], v[50:53], v[6:9]
	v_mfma_f32_16x16x32_bf16 v[2:5], v[26:29], v[54:57], v[2:5]
	s_waitcnt vmcnt(8) lgkmcnt(4)
	v_mfma_f32_16x16x32_bf16 v[6:9], v[30:33], v[58:61], v[6:9]
	v_mfma_f32_16x16x32_bf16 v[2:5], v[30:33], v[62:65], v[2:5]
	ds_read_b128 v[18:21], v114 offset:1024
	ds_read_b128 v[22:25], v115 offset:1024
	ds_read_b128 v[26:29], v114 offset:1152
	ds_read_b128 v[30:33], v115 offset:1152
	global_load_dwordx4 v[34:37], v[10:11], off offset:1024
	global_load_dwordx4 v[38:41], v[14:15], off offset:1024
	global_load_dwordx4 v[42:45], v[10:11], off offset:1088
	global_load_dwordx4 v[46:49], v[14:15], off offset:1088
	global_load_dwordx4 v[50:53], v[10:11], off offset:1152
	global_load_dwordx4 v[54:57], v[14:15], off offset:1152
	global_load_dwordx4 v[58:61], v[10:11], off offset:1216
	global_load_dwordx4 v[62:65], v[14:15], off offset:1216
	s_waitcnt vmcnt(14) lgkmcnt(7)
	v_mfma_f32_16x16x32_bf16 v[6:9], v[66:69], v[82:85], v[6:9]
	v_mfma_f32_16x16x32_bf16 v[2:5], v[66:69], v[86:89], v[2:5]
	s_waitcnt vmcnt(12) lgkmcnt(6)
	v_mfma_f32_16x16x32_bf16 v[6:9], v[70:73], v[90:93], v[6:9]
	v_mfma_f32_16x16x32_bf16 v[2:5], v[70:73], v[94:97], v[2:5]
	s_waitcnt vmcnt(10) lgkmcnt(5)
	v_mfma_f32_16x16x32_bf16 v[6:9], v[74:77], v[98:101], v[6:9]
	v_mfma_f32_16x16x32_bf16 v[2:5], v[74:77], v[102:105], v[2:5]
	s_waitcnt vmcnt(8) lgkmcnt(4)
	v_mfma_f32_16x16x32_bf16 v[6:9], v[78:81], v[106:109], v[6:9]
	v_mfma_f32_16x16x32_bf16 v[2:5], v[78:81], v[110:113], v[2:5]
	ds_read_b128 v[66:69], v114 offset:1280
	ds_read_b128 v[70:73], v115 offset:1280
	ds_read_b128 v[74:77], v114 offset:1408
	ds_read_b128 v[78:81], v115 offset:1408
	global_load_dwordx4 v[82:85], v[10:11], off offset:1280
	global_load_dwordx4 v[86:89], v[14:15], off offset:1280
	global_load_dwordx4 v[90:93], v[10:11], off offset:1344
	global_load_dwordx4 v[94:97], v[14:15], off offset:1344
	global_load_dwordx4 v[98:101], v[10:11], off offset:1408
	global_load_dwordx4 v[102:105], v[14:15], off offset:1408
	global_load_dwordx4 v[106:109], v[10:11], off offset:1472
	global_load_dwordx4 v[110:113], v[14:15], off offset:1472
	s_waitcnt vmcnt(14) lgkmcnt(7)
	v_mfma_f32_16x16x32_bf16 v[6:9], v[18:21], v[34:37], v[6:9]
	v_mfma_f32_16x16x32_bf16 v[2:5], v[18:21], v[38:41], v[2:5]
	s_waitcnt vmcnt(12) lgkmcnt(6)
	v_mfma_f32_16x16x32_bf16 v[6:9], v[22:25], v[42:45], v[6:9]
	v_mfma_f32_16x16x32_bf16 v[2:5], v[22:25], v[46:49], v[2:5]
	s_waitcnt vmcnt(10) lgkmcnt(5)
	v_mfma_f32_16x16x32_bf16 v[6:9], v[26:29], v[50:53], v[6:9]
	v_mfma_f32_16x16x32_bf16 v[2:5], v[26:29], v[54:57], v[2:5]
	s_waitcnt vmcnt(8) lgkmcnt(4)
	v_mfma_f32_16x16x32_bf16 v[6:9], v[30:33], v[58:61], v[6:9]
	v_mfma_f32_16x16x32_bf16 v[2:5], v[30:33], v[62:65], v[2:5]
	ds_read_b128 v[18:21], v114 offset:1536
	ds_read_b128 v[22:25], v115 offset:1536
	ds_read_b128 v[26:29], v114 offset:1664
	ds_read_b128 v[30:33], v115 offset:1664
	global_load_dwordx4 v[34:37], v[10:11], off offset:1536
	global_load_dwordx4 v[38:41], v[14:15], off offset:1536
	global_load_dwordx4 v[42:45], v[10:11], off offset:1600
	global_load_dwordx4 v[46:49], v[14:15], off offset:1600
	global_load_dwordx4 v[50:53], v[10:11], off offset:1664
	global_load_dwordx4 v[54:57], v[14:15], off offset:1664
	global_load_dwordx4 v[58:61], v[10:11], off offset:1728
	global_load_dwordx4 v[62:65], v[14:15], off offset:1728
	s_waitcnt vmcnt(14) lgkmcnt(7)
	v_mfma_f32_16x16x32_bf16 v[6:9], v[66:69], v[82:85], v[6:9]
	v_mfma_f32_16x16x32_bf16 v[2:5], v[66:69], v[86:89], v[2:5]
	s_waitcnt vmcnt(12) lgkmcnt(6)
	v_mfma_f32_16x16x32_bf16 v[6:9], v[70:73], v[90:93], v[6:9]
	v_mfma_f32_16x16x32_bf16 v[2:5], v[70:73], v[94:97], v[2:5]
	s_waitcnt vmcnt(10) lgkmcnt(5)
	v_mfma_f32_16x16x32_bf16 v[6:9], v[74:77], v[98:101], v[6:9]
	v_mfma_f32_16x16x32_bf16 v[2:5], v[74:77], v[102:105], v[2:5]
	s_waitcnt vmcnt(8) lgkmcnt(4)
	v_mfma_f32_16x16x32_bf16 v[6:9], v[78:81], v[106:109], v[6:9]
	v_mfma_f32_16x16x32_bf16 v[2:5], v[78:81], v[110:113], v[2:5]
	ds_read_b128 v[66:69], v114 offset:1792
	ds_read_b128 v[70:73], v115 offset:1792
	ds_read_b128 v[74:77], v114 offset:1920
	ds_read_b128 v[78:81], v115 offset:1920
	global_load_dwordx4 v[82:85], v[10:11], off offset:1792
	global_load_dwordx4 v[86:89], v[14:15], off offset:1792
	global_load_dwordx4 v[90:93], v[10:11], off offset:1856
	global_load_dwordx4 v[94:97], v[14:15], off offset:1856
	global_load_dwordx4 v[98:101], v[10:11], off offset:1920
	global_load_dwordx4 v[102:105], v[14:15], off offset:1920
	global_load_dwordx4 v[106:109], v[10:11], off offset:1984
	global_load_dwordx4 v[110:113], v[14:15], off offset:1984
	s_waitcnt vmcnt(14) lgkmcnt(7)
	v_mfma_f32_16x16x32_bf16 v[6:9], v[18:21], v[34:37], v[6:9]
	v_mfma_f32_16x16x32_bf16 v[2:5], v[18:21], v[38:41], v[2:5]
	s_waitcnt vmcnt(12) lgkmcnt(6)
	v_mfma_f32_16x16x32_bf16 v[6:9], v[22:25], v[42:45], v[6:9]
	v_mfma_f32_16x16x32_bf16 v[2:5], v[22:25], v[46:49], v[2:5]
	s_waitcnt vmcnt(10) lgkmcnt(5)
	v_mfma_f32_16x16x32_bf16 v[6:9], v[26:29], v[50:53], v[6:9]
	v_mfma_f32_16x16x32_bf16 v[2:5], v[26:29], v[54:57], v[2:5]
	s_waitcnt vmcnt(8) lgkmcnt(4)
	v_mfma_f32_16x16x32_bf16 v[6:9], v[30:33], v[58:61], v[6:9]
	v_mfma_f32_16x16x32_bf16 v[2:5], v[30:33], v[62:65], v[2:5]
	ds_read_b128 v[18:21], v116 offset:2048
	ds_read_b128 v[22:25], v117 offset:2048
	ds_read_b128 v[26:29], v116 offset:2176
	ds_read_b128 v[30:33], v117 offset:2176
	global_load_dwordx4 v[34:37], v[10:11], off offset:2048
	global_load_dwordx4 v[38:41], v[14:15], off offset:2048
	global_load_dwordx4 v[42:45], v[10:11], off offset:2112
	global_load_dwordx4 v[46:49], v[14:15], off offset:2112
	global_load_dwordx4 v[50:53], v[10:11], off offset:2176
	global_load_dwordx4 v[54:57], v[14:15], off offset:2176
	global_load_dwordx4 v[58:61], v[10:11], off offset:2240
	global_load_dwordx4 v[62:65], v[14:15], off offset:2240
	s_waitcnt vmcnt(14) lgkmcnt(7)
	v_mfma_f32_16x16x32_bf16 v[6:9], v[66:69], v[82:85], v[6:9]
	v_mfma_f32_16x16x32_bf16 v[2:5], v[66:69], v[86:89], v[2:5]
	s_waitcnt vmcnt(12) lgkmcnt(6)
	v_mfma_f32_16x16x32_bf16 v[6:9], v[70:73], v[90:93], v[6:9]
	v_mfma_f32_16x16x32_bf16 v[2:5], v[70:73], v[94:97], v[2:5]
	s_waitcnt vmcnt(10) lgkmcnt(5)
	v_mfma_f32_16x16x32_bf16 v[6:9], v[74:77], v[98:101], v[6:9]
	v_mfma_f32_16x16x32_bf16 v[2:5], v[74:77], v[102:105], v[2:5]
	s_waitcnt vmcnt(8) lgkmcnt(4)
	v_mfma_f32_16x16x32_bf16 v[6:9], v[78:81], v[106:109], v[6:9]
	v_mfma_f32_16x16x32_bf16 v[2:5], v[78:81], v[110:113], v[2:5]
	ds_read_b128 v[66:69], v116 offset:2304
	ds_read_b128 v[70:73], v117 offset:2304
	ds_read_b128 v[74:77], v116 offset:2432
	ds_read_b128 v[78:81], v117 offset:2432
	global_load_dwordx4 v[82:85], v[10:11], off offset:2304
	global_load_dwordx4 v[86:89], v[14:15], off offset:2304
	global_load_dwordx4 v[90:93], v[10:11], off offset:2368
	global_load_dwordx4 v[94:97], v[14:15], off offset:2368
	global_load_dwordx4 v[98:101], v[10:11], off offset:2432
	global_load_dwordx4 v[102:105], v[14:15], off offset:2432
	global_load_dwordx4 v[106:109], v[10:11], off offset:2496
	global_load_dwordx4 v[110:113], v[14:15], off offset:2496
	s_waitcnt vmcnt(14) lgkmcnt(7)
	v_mfma_f32_16x16x32_bf16 v[6:9], v[18:21], v[34:37], v[6:9]
	v_mfma_f32_16x16x32_bf16 v[2:5], v[18:21], v[38:41], v[2:5]
	s_waitcnt vmcnt(12) lgkmcnt(6)
	v_mfma_f32_16x16x32_bf16 v[6:9], v[22:25], v[42:45], v[6:9]
	v_mfma_f32_16x16x32_bf16 v[2:5], v[22:25], v[46:49], v[2:5]
	s_waitcnt vmcnt(10) lgkmcnt(5)
	v_mfma_f32_16x16x32_bf16 v[6:9], v[26:29], v[50:53], v[6:9]
	v_mfma_f32_16x16x32_bf16 v[2:5], v[26:29], v[54:57], v[2:5]
	s_waitcnt vmcnt(8) lgkmcnt(4)
	v_mfma_f32_16x16x32_bf16 v[6:9], v[30:33], v[58:61], v[6:9]
	v_mfma_f32_16x16x32_bf16 v[2:5], v[30:33], v[62:65], v[2:5]
	ds_read_b128 v[18:21], v116 offset:2560
	ds_read_b128 v[22:25], v117 offset:2560
	ds_read_b128 v[26:29], v116 offset:2688
	ds_read_b128 v[30:33], v117 offset:2688
	global_load_dwordx4 v[34:37], v[10:11], off offset:2560
	global_load_dwordx4 v[38:41], v[14:15], off offset:2560
	global_load_dwordx4 v[42:45], v[10:11], off offset:2624
	global_load_dwordx4 v[46:49], v[14:15], off offset:2624
	global_load_dwordx4 v[50:53], v[10:11], off offset:2688
	global_load_dwordx4 v[54:57], v[14:15], off offset:2688
	global_load_dwordx4 v[58:61], v[10:11], off offset:2752
	global_load_dwordx4 v[62:65], v[14:15], off offset:2752
	s_waitcnt vmcnt(14) lgkmcnt(7)
	v_mfma_f32_16x16x32_bf16 v[6:9], v[66:69], v[82:85], v[6:9]
	v_mfma_f32_16x16x32_bf16 v[2:5], v[66:69], v[86:89], v[2:5]
	s_waitcnt vmcnt(12) lgkmcnt(6)
	v_mfma_f32_16x16x32_bf16 v[6:9], v[70:73], v[90:93], v[6:9]
	v_mfma_f32_16x16x32_bf16 v[2:5], v[70:73], v[94:97], v[2:5]
	s_waitcnt vmcnt(10) lgkmcnt(5)
	v_mfma_f32_16x16x32_bf16 v[6:9], v[74:77], v[98:101], v[6:9]
	v_mfma_f32_16x16x32_bf16 v[2:5], v[74:77], v[102:105], v[2:5]
	s_waitcnt vmcnt(8) lgkmcnt(4)
	v_mfma_f32_16x16x32_bf16 v[6:9], v[78:81], v[106:109], v[6:9]
	v_mfma_f32_16x16x32_bf16 v[2:5], v[78:81], v[110:113], v[2:5]
	ds_read_b128 v[66:69], v116 offset:2816
	ds_read_b128 v[70:73], v117 offset:2816
	ds_read_b128 v[74:77], v116 offset:2944
	ds_read_b128 v[78:81], v117 offset:2944
	global_load_dwordx4 v[82:85], v[10:11], off offset:2816
	global_load_dwordx4 v[86:89], v[14:15], off offset:2816
	global_load_dwordx4 v[90:93], v[10:11], off offset:2880
	global_load_dwordx4 v[94:97], v[14:15], off offset:2880
	global_load_dwordx4 v[98:101], v[10:11], off offset:2944
	global_load_dwordx4 v[102:105], v[14:15], off offset:2944
	global_load_dwordx4 v[106:109], v[10:11], off offset:3008
	global_load_dwordx4 v[110:113], v[14:15], off offset:3008
	s_waitcnt vmcnt(14) lgkmcnt(7)
	v_mfma_f32_16x16x32_bf16 v[6:9], v[18:21], v[34:37], v[6:9]
	v_mfma_f32_16x16x32_bf16 v[2:5], v[18:21], v[38:41], v[2:5]
	s_waitcnt vmcnt(12) lgkmcnt(6)
	v_mfma_f32_16x16x32_bf16 v[6:9], v[22:25], v[42:45], v[6:9]
	v_mfma_f32_16x16x32_bf16 v[2:5], v[22:25], v[46:49], v[2:5]
	s_waitcnt vmcnt(10) lgkmcnt(5)
	v_mfma_f32_16x16x32_bf16 v[6:9], v[26:29], v[50:53], v[6:9]
	v_mfma_f32_16x16x32_bf16 v[2:5], v[26:29], v[54:57], v[2:5]
	s_waitcnt vmcnt(8) lgkmcnt(4)
	v_mfma_f32_16x16x32_bf16 v[6:9], v[30:33], v[58:61], v[6:9]
	v_mfma_f32_16x16x32_bf16 v[2:5], v[30:33], v[62:65], v[2:5]
	ds_read_b128 v[18:21], v116 offset:3072
	ds_read_b128 v[22:25], v117 offset:3072
	ds_read_b128 v[26:29], v116 offset:3200
	ds_read_b128 v[30:33], v117 offset:3200
	global_load_dwordx4 v[34:37], v[10:11], off offset:3072
	global_load_dwordx4 v[38:41], v[14:15], off offset:3072
	global_load_dwordx4 v[42:45], v[10:11], off offset:3136
	global_load_dwordx4 v[46:49], v[14:15], off offset:3136
	global_load_dwordx4 v[50:53], v[10:11], off offset:3200
	global_load_dwordx4 v[54:57], v[14:15], off offset:3200
	global_load_dwordx4 v[58:61], v[10:11], off offset:3264
	global_load_dwordx4 v[62:65], v[14:15], off offset:3264
	s_waitcnt vmcnt(14) lgkmcnt(7)
	v_mfma_f32_16x16x32_bf16 v[6:9], v[66:69], v[82:85], v[6:9]
	v_mfma_f32_16x16x32_bf16 v[2:5], v[66:69], v[86:89], v[2:5]
	s_waitcnt vmcnt(12) lgkmcnt(6)
	v_mfma_f32_16x16x32_bf16 v[6:9], v[70:73], v[90:93], v[6:9]
	v_mfma_f32_16x16x32_bf16 v[2:5], v[70:73], v[94:97], v[2:5]
	s_waitcnt vmcnt(10) lgkmcnt(5)
	v_mfma_f32_16x16x32_bf16 v[6:9], v[74:77], v[98:101], v[6:9]
	v_mfma_f32_16x16x32_bf16 v[2:5], v[74:77], v[102:105], v[2:5]
	s_waitcnt vmcnt(8) lgkmcnt(4)
	v_mfma_f32_16x16x32_bf16 v[6:9], v[78:81], v[106:109], v[6:9]
	v_mfma_f32_16x16x32_bf16 v[2:5], v[78:81], v[110:113], v[2:5]
	ds_read_b128 v[66:69], v116 offset:3328
	ds_read_b128 v[70:73], v117 offset:3328
	ds_read_b128 v[74:77], v116 offset:3456
	ds_read_b128 v[78:81], v117 offset:3456
	global_load_dwordx4 v[82:85], v[10:11], off offset:3328
	global_load_dwordx4 v[86:89], v[14:15], off offset:3328
	global_load_dwordx4 v[90:93], v[10:11], off offset:3392
	global_load_dwordx4 v[94:97], v[14:15], off offset:3392
	global_load_dwordx4 v[98:101], v[10:11], off offset:3456
	global_load_dwordx4 v[102:105], v[14:15], off offset:3456
	global_load_dwordx4 v[106:109], v[10:11], off offset:3520
	global_load_dwordx4 v[110:113], v[14:15], off offset:3520
	s_waitcnt vmcnt(14) lgkmcnt(7)
	v_mfma_f32_16x16x32_bf16 v[6:9], v[18:21], v[34:37], v[6:9]
	v_mfma_f32_16x16x32_bf16 v[2:5], v[18:21], v[38:41], v[2:5]
	s_waitcnt vmcnt(12) lgkmcnt(6)
	v_mfma_f32_16x16x32_bf16 v[6:9], v[22:25], v[42:45], v[6:9]
	v_mfma_f32_16x16x32_bf16 v[2:5], v[22:25], v[46:49], v[2:5]
	s_waitcnt vmcnt(10) lgkmcnt(5)
	v_mfma_f32_16x16x32_bf16 v[6:9], v[26:29], v[50:53], v[6:9]
	v_mfma_f32_16x16x32_bf16 v[2:5], v[26:29], v[54:57], v[2:5]
	s_waitcnt vmcnt(8) lgkmcnt(4)
	v_mfma_f32_16x16x32_bf16 v[6:9], v[30:33], v[58:61], v[6:9]
	v_mfma_f32_16x16x32_bf16 v[2:5], v[30:33], v[62:65], v[2:5]
	s_waitcnt vmcnt(6) lgkmcnt(3)
	v_mfma_f32_16x16x32_bf16 v[6:9], v[66:69], v[82:85], v[6:9]
	v_mfma_f32_16x16x32_bf16 v[2:5], v[66:69], v[86:89], v[2:5]
	s_waitcnt vmcnt(4) lgkmcnt(2)
	v_mfma_f32_16x16x32_bf16 v[6:9], v[70:73], v[90:93], v[6:9]
	v_mfma_f32_16x16x32_bf16 v[2:5], v[70:73], v[94:97], v[2:5]
	s_waitcnt vmcnt(2) lgkmcnt(1)
	v_mfma_f32_16x16x32_bf16 v[6:9], v[74:77], v[98:101], v[6:9]
	v_mfma_f32_16x16x32_bf16 v[2:5], v[74:77], v[102:105], v[2:5]
	s_waitcnt vmcnt(0) lgkmcnt(0)
	v_mfma_f32_16x16x32_bf16 v[6:9], v[78:81], v[106:109], v[6:9]
	v_mfma_f32_16x16x32_bf16 v[2:5], v[78:81], v[110:113], v[2:5]
.Lcmp_done:
	s_lshl_b32 s14, s81, 6
	s_and_b32 s18, s14, 0xffffe000
	s_ashr_i32 s19, s18, 31
	v_lshl_add_u64 v[66:67], s[18:19], 2, v[142:143]
	s_mov_b64 s[18:19], 0x1000
	v_lshl_add_u64 v[68:69], v[66:67], 0, s[18:19]
	s_mov_b64 s[18:19], 0x2000
	v_lshl_add_u64 v[70:71], v[66:67], 0, s[18:19]
	s_mov_b64 s[18:19], 0x3000
	v_lshl_add_u64 v[72:73], v[66:67], 0, s[18:19]
	s_mov_b64 s[18:19], 0x4000
	v_lshl_add_u64 v[74:75], v[66:67], 0, s[18:19]
	s_mov_b64 s[18:19], 0x5000
	v_lshl_add_u64 v[76:77], v[66:67], 0, s[18:19]
	s_mov_b64 s[18:19], 0x6000
	v_lshl_add_u64 v[78:79], v[66:67], 0, s[18:19]
	s_mov_b64 s[18:19], 0x7000
	v_lshl_add_u64 v[80:81], v[66:67], 0, s[18:19]
	global_load_dword v30, v[66:67], off
	global_load_dword v31, v[66:67], off offset:1024
	global_load_dword v32, v[66:67], off offset:2048
	global_load_dword v33, v[66:67], off offset:3072
	global_load_dword v34, v[68:69], off
	global_load_dword v35, v[68:69], off offset:1024
	global_load_dword v36, v[68:69], off offset:2048
	global_load_dword v37, v[68:69], off offset:3072
	global_load_dword v38, v[70:71], off
	global_load_dword v39, v[70:71], off offset:1024
	global_load_dword v40, v[70:71], off offset:2048
	global_load_dword v41, v[70:71], off offset:3072
	global_load_dword v42, v[72:73], off
	global_load_dword v43, v[72:73], off offset:1024
	global_load_dword v44, v[72:73], off offset:2048
	global_load_dword v45, v[72:73], off offset:3072
	global_load_dword v46, v[74:75], off
	global_load_dword v47, v[74:75], off offset:1024
	global_load_dword v48, v[74:75], off offset:2048
	global_load_dword v49, v[74:75], off offset:3072
	global_load_dword v50, v[76:77], off
	global_load_dword v51, v[76:77], off offset:1024
	global_load_dword v52, v[76:77], off offset:2048
	global_load_dword v53, v[76:77], off offset:3072
	global_load_dword v54, v[78:79], off
	global_load_dword v55, v[78:79], off offset:1024
	global_load_dword v56, v[78:79], off offset:2048
	global_load_dword v57, v[78:79], off offset:3072
	global_load_dword v58, v[80:81], off
	global_load_dword v59, v[80:81], off offset:1024
	global_load_dword v60, v[80:81], off offset:2048
	global_load_dword v61, v[80:81], off offset:3072
	global_load_dword v82, v[66:67], off offset:64
	global_load_dword v83, v[66:67], off offset:1088
	global_load_dword v84, v[66:67], off offset:2112
	global_load_dword v85, v[66:67], off offset:3136
	global_load_dword v86, v[68:69], off offset:64
	global_load_dword v87, v[68:69], off offset:1088
	global_load_dword v88, v[68:69], off offset:2112
	global_load_dword v89, v[68:69], off offset:3136
	global_load_dword v90, v[70:71], off offset:64
	global_load_dword v91, v[70:71], off offset:1088
	global_load_dword v92, v[70:71], off offset:2112
	global_load_dword v93, v[70:71], off offset:3136
	global_load_dword v94, v[72:73], off offset:64
	global_load_dword v95, v[72:73], off offset:1088
	global_load_dword v96, v[72:73], off offset:2112
	global_load_dword v97, v[72:73], off offset:3136
	s_waitcnt vmcnt(47)
	v_add_f32_e32 v0, 0, v30
	s_waitcnt vmcnt(46)
	v_add_f32_e32 v0, v0, v31
	s_waitcnt vmcnt(45)
	v_add_f32_e32 v0, v0, v32
	s_waitcnt vmcnt(44)
	v_add_f32_e32 v0, v0, v33
	s_waitcnt vmcnt(43)
	v_add_f32_e32 v0, v0, v34
	s_waitcnt vmcnt(42)
	v_add_f32_e32 v0, v0, v35
	s_waitcnt vmcnt(41)
	v_add_f32_e32 v0, v0, v36
	s_waitcnt vmcnt(40)
	v_add_f32_e32 v0, v0, v37
	s_waitcnt vmcnt(39)
	v_add_f32_e32 v0, v0, v38
	s_waitcnt vmcnt(38)
	v_add_f32_e32 v0, v0, v39
	s_waitcnt vmcnt(37)
	v_add_f32_e32 v0, v0, v40
	s_waitcnt vmcnt(36)
	v_add_f32_e32 v0, v0, v41
	s_waitcnt vmcnt(35)
	v_add_f32_e32 v0, v0, v42
	s_waitcnt vmcnt(34)
	v_add_f32_e32 v0, v0, v43
	s_waitcnt vmcnt(33)
	v_add_f32_e32 v0, v0, v44
	s_waitcnt vmcnt(32)
	v_add_f32_e32 v0, v0, v45
	s_waitcnt vmcnt(31)
	v_add_f32_e32 v0, v0, v46
	s_waitcnt vmcnt(30)
	v_add_f32_e32 v0, v0, v47
	s_waitcnt vmcnt(29)
	v_add_f32_e32 v0, v0, v48
	s_waitcnt vmcnt(28)
	v_add_f32_e32 v0, v0, v49
	s_waitcnt vmcnt(27)
	v_add_f32_e32 v0, v0, v50
	s_waitcnt vmcnt(26)
	v_add_f32_e32 v0, v0, v51
	s_waitcnt vmcnt(25)
	v_add_f32_e32 v0, v0, v52
	s_waitcnt vmcnt(24)
	v_add_f32_e32 v0, v0, v53
	s_waitcnt vmcnt(23)
	v_add_f32_e32 v0, v0, v54
	s_waitcnt vmcnt(22)
	v_add_f32_e32 v0, v0, v55
	s_waitcnt vmcnt(21)
	v_add_f32_e32 v0, v0, v56
	s_waitcnt vmcnt(20)
	v_add_f32_e32 v0, v0, v57
	s_waitcnt vmcnt(19)
	v_add_f32_e32 v0, v0, v58
	s_waitcnt vmcnt(18)
	v_add_f32_e32 v0, v0, v59
	s_waitcnt vmcnt(17)
	v_add_f32_e32 v0, v0, v60
	s_waitcnt vmcnt(16)
	v_add_f32_e32 v0, v0, v61
	global_load_dword v98, v[74:75], off offset:64
	global_load_dword v99, v[74:75], off offset:1088
	global_load_dword v100, v[74:75], off offset:2112
	global_load_dword v101, v[74:75], off offset:3136
	global_load_dword v102, v[76:77], off offset:64
	global_load_dword v103, v[76:77], off offset:1088
	global_load_dword v104, v[76:77], off offset:2112
	global_load_dword v105, v[76:77], off offset:3136
	global_load_dword v106, v[78:79], off offset:64
	global_load_dword v107, v[78:79], off offset:1088
	global_load_dword v108, v[78:79], off offset:2112
	global_load_dword v109, v[78:79], off offset:3136
	global_load_dword v110, v[80:81], off offset:64
	global_load_dword v111, v[80:81], off offset:1088
	global_load_dword v112, v[80:81], off offset:2112
	global_load_dword v113, v[80:81], off offset:3136
	v_add_f32_e32 v6, v6, v0
	v_mul_f32_e32 v26, 0x3d372713, v6
	v_mul_f32_e32 v26, v6, v26
	v_fma_f32 v26, v6, v26, v6
	v_mul_f32_e32 v26, 0x3f4c422a, v26
	v_add_f32_e32 v26, v26, v26
	v_mul_f32_e32 v26, 0x3fb8aa3b, v26
	v_exp_f32_e32 v26, v26
	v_mul_f32_e32 v6, 0.5, v6
	v_add_f32_e32 v26, 1.0, v26
	v_div_scale_f32 v27, s[18:19], v26, v26, 2.0
	v_rcp_f32_e32 v28, v27
	s_nop 0
	v_fma_f32 v29, -v27, v28, 1.0
	v_fmac_f32_e32 v28, v29, v28
	v_div_scale_f32 v29, vcc, 2.0, v26, 2.0
	v_mul_f32_e32 v30, v29, v28
	v_fma_f32 v31, -v27, v30, v29
	v_fmac_f32_e32 v30, v31, v28
	v_fma_f32 v27, -v27, v30, v29
	v_div_fmas_f32 v27, v27, v28, v30
	v_div_fixup_f32 v26, v27, v26, 2.0
	v_sub_f32_e32 v26, 1.0, v26
	v_add_f32_e32 v26, 1.0, v26
	v_mul_f32_e32 v6, v6, v26
	v_cvt_pk_bf16_f32 v6, v6, s0
	ds_write_b16 v231, v6 offset:36864
	v_add_f32_e32 v6, v7, v0
	v_mul_f32_e32 v7, 0x3d372713, v6
	v_mul_f32_e32 v7, v6, v7
	v_fma_f32 v7, v6, v7, v6
	v_mul_f32_e32 v7, 0x3f4c422a, v7
	v_add_f32_e32 v7, v7, v7
	v_mul_f32_e32 v7, 0x3fb8aa3b, v7
	v_exp_f32_e32 v7, v7
	v_mul_f32_e32 v6, 0.5, v6
	v_add_f32_e32 v7, 1.0, v7
	v_div_scale_f32 v26, s[18:19], v7, v7, 2.0
	v_rcp_f32_e32 v27, v26
	s_nop 0
	v_fma_f32 v28, -v26, v27, 1.0
	v_fmac_f32_e32 v27, v28, v27
	v_div_scale_f32 v28, vcc, 2.0, v7, 2.0
	v_mul_f32_e32 v29, v28, v27
	v_fma_f32 v30, -v26, v29, v28
	v_fmac_f32_e32 v29, v30, v27
	v_fma_f32 v26, -v26, v29, v28
	v_div_fmas_f32 v26, v26, v27, v29
	v_div_fixup_f32 v7, v26, v7, 2.0
	v_sub_f32_e32 v7, 1.0, v7
	v_add_f32_e32 v7, 1.0, v7
	v_mul_f32_e32 v6, v6, v7
	v_cvt_pk_bf16_f32 v6, v6, s0
	ds_write_b16 v231, v6 offset:37392
	v_add_f32_e32 v6, v8, v0
	v_mul_f32_e32 v7, 0x3d372713, v6
	v_mul_f32_e32 v7, v6, v7
	v_fma_f32 v7, v6, v7, v6
	v_mul_f32_e32 v7, 0x3f4c422a, v7
	v_add_f32_e32 v7, v7, v7
	v_mul_f32_e32 v7, 0x3fb8aa3b, v7
	v_exp_f32_e32 v7, v7
	v_mul_f32_e32 v6, 0.5, v6
	v_add_f32_e32 v0, v9, v0
	v_add_f32_e32 v7, 1.0, v7
	v_div_scale_f32 v8, s[18:19], v7, v7, 2.0
	v_rcp_f32_e32 v26, v8
	s_nop 0
	v_fma_f32 v27, -v8, v26, 1.0
	v_fmac_f32_e32 v26, v27, v26
	v_div_scale_f32 v27, vcc, 2.0, v7, 2.0
	v_mul_f32_e32 v28, v27, v26
	v_fma_f32 v29, -v8, v28, v27
	v_fmac_f32_e32 v28, v29, v26
	v_fma_f32 v8, -v8, v28, v27
	v_div_fmas_f32 v8, v8, v26, v28
	v_div_fixup_f32 v7, v8, v7, 2.0
	v_sub_f32_e32 v7, 1.0, v7
	v_add_f32_e32 v7, 1.0, v7
	v_mul_f32_e32 v6, v6, v7
	v_cvt_pk_bf16_f32 v6, v6, s0
	ds_write_b16 v231, v6 offset:37920
	v_mul_f32_e32 v6, 0x3d372713, v0
	v_mul_f32_e32 v6, v0, v6
	v_fma_f32 v6, v0, v6, v0
	v_mul_f32_e32 v6, 0x3f4c422a, v6
	v_add_f32_e32 v6, v6, v6
	v_mul_f32_e32 v6, 0x3fb8aa3b, v6
	v_exp_f32_e32 v6, v6
	v_mul_f32_e32 v0, 0.5, v0
	v_add_f32_e32 v6, 1.0, v6
	v_div_scale_f32 v7, s[18:19], v6, v6, 2.0
	v_rcp_f32_e32 v8, v7
	s_nop 0
	v_fma_f32 v9, -v7, v8, 1.0
	v_fmac_f32_e32 v8, v9, v8
	v_div_scale_f32 v9, vcc, 2.0, v6, 2.0
	v_mul_f32_e32 v26, v9, v8
	v_fma_f32 v27, -v7, v26, v9
	v_fmac_f32_e32 v26, v27, v8
	v_fma_f32 v7, -v7, v26, v9
	v_div_fmas_f32 v7, v7, v8, v26
	v_div_fixup_f32 v6, v7, v6, 2.0
	v_sub_f32_e32 v6, 1.0, v6
	v_add_f32_e32 v6, 1.0, v6
	v_mul_f32_e32 v0, v0, v6
	v_cvt_pk_bf16_f32 v0, v0, s0
	ds_write_b16 v231, v0 offset:38448
	s_waitcnt vmcnt(31)
	v_add_f32_e32 v0, 0, v82
	s_waitcnt vmcnt(30)
	v_add_f32_e32 v0, v0, v83
	s_waitcnt vmcnt(29)
	v_add_f32_e32 v0, v0, v84
	s_waitcnt vmcnt(28)
	v_add_f32_e32 v0, v0, v85
	s_waitcnt vmcnt(27)
	v_add_f32_e32 v0, v0, v86
	s_waitcnt vmcnt(26)
	v_add_f32_e32 v0, v0, v87
	s_waitcnt vmcnt(25)
	v_add_f32_e32 v0, v0, v88
	s_waitcnt vmcnt(24)
	v_add_f32_e32 v0, v0, v89
	s_waitcnt vmcnt(23)
	v_add_f32_e32 v0, v0, v90
	s_waitcnt vmcnt(22)
	v_add_f32_e32 v0, v0, v91
	s_waitcnt vmcnt(21)
	v_add_f32_e32 v0, v0, v92
	s_waitcnt vmcnt(20)
	v_add_f32_e32 v0, v0, v93
	s_waitcnt vmcnt(19)
	v_add_f32_e32 v0, v0, v94
	s_waitcnt vmcnt(18)
	v_add_f32_e32 v0, v0, v95
	s_waitcnt vmcnt(17)
	v_add_f32_e32 v0, v0, v96
	s_waitcnt vmcnt(16)
	v_add_f32_e32 v0, v0, v97
	s_waitcnt vmcnt(15)
	v_add_f32_e32 v0, v0, v98
	s_waitcnt vmcnt(14)
	v_add_f32_e32 v0, v0, v99
	s_waitcnt vmcnt(13)
	v_add_f32_e32 v0, v0, v100
	s_waitcnt vmcnt(12)
	v_add_f32_e32 v0, v0, v101
	s_waitcnt vmcnt(11)
	v_add_f32_e32 v0, v0, v102
	s_waitcnt vmcnt(10)
	v_add_f32_e32 v0, v0, v103
	s_waitcnt vmcnt(9)
	v_add_f32_e32 v0, v0, v104
	s_waitcnt vmcnt(8)
	v_add_f32_e32 v0, v0, v105
	s_waitcnt vmcnt(7)
	v_add_f32_e32 v0, v0, v106
	s_waitcnt vmcnt(6)
	v_add_f32_e32 v0, v0, v107
	s_waitcnt vmcnt(5)
	v_add_f32_e32 v0, v0, v108
	s_waitcnt vmcnt(4)
	v_add_f32_e32 v0, v0, v109
	s_waitcnt vmcnt(3)
	v_add_f32_e32 v0, v0, v110
	s_waitcnt vmcnt(2)
	v_add_f32_e32 v0, v0, v111
	s_waitcnt vmcnt(1)
	v_add_f32_e32 v0, v0, v112
	s_waitcnt vmcnt(0)
	v_add_f32_e32 v0, v0, v113
	v_add_f32_e32 v2, v2, v0
	v_mul_f32_e32 v6, 0x3d372713, v2
	v_mul_f32_e32 v6, v2, v6
	v_fma_f32 v6, v2, v6, v2
	v_mul_f32_e32 v6, 0x3f4c422a, v6
	v_add_f32_e32 v6, v6, v6
	v_mul_f32_e32 v6, 0x3fb8aa3b, v6
	v_exp_f32_e32 v6, v6
	v_mul_f32_e32 v2, 0.5, v2
	v_add_f32_e32 v6, 1.0, v6
	v_div_scale_f32 v7, s[18:19], v6, v6, 2.0
	v_rcp_f32_e32 v8, v7
	s_nop 0
	v_fma_f32 v9, -v7, v8, 1.0
	v_fmac_f32_e32 v8, v9, v8
	v_div_scale_f32 v9, vcc, 2.0, v6, 2.0
	v_mul_f32_e32 v10, v9, v8
	v_fma_f32 v11, -v7, v10, v9
	v_fmac_f32_e32 v10, v11, v8
	v_fma_f32 v7, -v7, v10, v9
	v_div_fmas_f32 v7, v7, v8, v10
	v_div_fixup_f32 v6, v7, v6, 2.0
	v_sub_f32_e32 v6, 1.0, v6
	v_add_f32_e32 v6, 1.0, v6
	v_mul_f32_e32 v2, v2, v6
	v_cvt_pk_bf16_f32 v2, v2, s0
	ds_write_b16 v231, v2 offset:36896
	v_add_f32_e32 v2, v3, v0
	v_mul_f32_e32 v3, 0x3d372713, v2
	v_mul_f32_e32 v3, v2, v3
	v_fma_f32 v3, v2, v3, v2
	v_mul_f32_e32 v3, 0x3f4c422a, v3
	v_add_f32_e32 v3, v3, v3
	v_mul_f32_e32 v3, 0x3fb8aa3b, v3
	v_exp_f32_e32 v3, v3
	v_mul_f32_e32 v2, 0.5, v2
	v_add_f32_e32 v3, 1.0, v3
	v_div_scale_f32 v6, s[18:19], v3, v3, 2.0
	v_rcp_f32_e32 v7, v6
	s_nop 0
	v_fma_f32 v8, -v6, v7, 1.0
	v_fmac_f32_e32 v7, v8, v7
	v_div_scale_f32 v8, vcc, 2.0, v3, 2.0
	v_mul_f32_e32 v9, v8, v7
	v_fma_f32 v10, -v6, v9, v8
	v_fmac_f32_e32 v9, v10, v7
	v_fma_f32 v6, -v6, v9, v8
	v_div_fmas_f32 v6, v6, v7, v9
	v_div_fixup_f32 v3, v6, v3, 2.0
	v_sub_f32_e32 v3, 1.0, v3
	v_add_f32_e32 v3, 1.0, v3
	v_mul_f32_e32 v2, v2, v3
	v_cvt_pk_bf16_f32 v2, v2, s0
	ds_write_b16 v231, v2 offset:37424
	v_add_f32_e32 v2, v4, v0
	v_mul_f32_e32 v3, 0x3d372713, v2
	v_mul_f32_e32 v3, v2, v3
	v_fma_f32 v3, v2, v3, v2
	v_mul_f32_e32 v3, 0x3f4c422a, v3
	v_add_f32_e32 v3, v3, v3
	v_mul_f32_e32 v3, 0x3fb8aa3b, v3
	v_exp_f32_e32 v3, v3
	v_mul_f32_e32 v2, 0.5, v2
	v_add_f32_e32 v0, v5, v0
	v_add_f32_e32 v3, 1.0, v3
	v_div_scale_f32 v4, s[18:19], v3, v3, 2.0
	v_rcp_f32_e32 v6, v4
	s_nop 0
	v_fma_f32 v7, -v4, v6, 1.0
	v_fmac_f32_e32 v6, v7, v6
	v_div_scale_f32 v7, vcc, 2.0, v3, 2.0
	v_mul_f32_e32 v8, v7, v6
	v_fma_f32 v9, -v4, v8, v7
	v_fmac_f32_e32 v8, v9, v6
	v_fma_f32 v4, -v4, v8, v7
	v_div_fmas_f32 v4, v4, v6, v8
	v_div_fixup_f32 v3, v4, v3, 2.0
	v_sub_f32_e32 v3, 1.0, v3
	v_add_f32_e32 v3, 1.0, v3
	v_mul_f32_e32 v2, v2, v3
	v_cvt_pk_bf16_f32 v2, v2, s0
	ds_write_b16 v231, v2 offset:37952
	v_mul_f32_e32 v2, 0x3d372713, v0
	v_mul_f32_e32 v2, v0, v2
	v_fma_f32 v2, v0, v2, v0
	v_mul_f32_e32 v2, 0x3f4c422a, v2
	v_add_f32_e32 v2, v2, v2
	v_mul_f32_e32 v2, 0x3fb8aa3b, v2
	v_exp_f32_e32 v2, v2
	v_mul_f32_e32 v0, 0.5, v0
	v_add_f32_e32 v2, 1.0, v2
	v_div_scale_f32 v3, s[18:19], v2, v2, 2.0
	v_rcp_f32_e32 v4, v3
	s_nop 0
	v_fma_f32 v5, -v3, v4, 1.0
	v_fmac_f32_e32 v4, v5, v4
	v_div_scale_f32 v5, vcc, 2.0, v2, 2.0
	v_mul_f32_e32 v6, v5, v4
	v_fma_f32 v7, -v3, v6, v5
	v_fmac_f32_e32 v6, v7, v4
	v_fma_f32 v3, -v3, v6, v5
	v_div_fmas_f32 v3, v3, v4, v6
	v_div_fixup_f32 v2, v3, v2, 2.0
	v_sub_f32_e32 v2, 1.0, v2
	v_add_f32_e32 v2, 1.0, v2
	v_mul_f32_e32 v0, v0, v2
	v_cvt_pk_bf16_f32 v0, v0, s0
	s_and_b64 vcc, exec, s[10:11]
	ds_write_b16 v231, v0 offset:38480
	s_waitcnt lgkmcnt(0)
	s_barrier
	s_cbranch_vccz .LBB0_274
	s_and_b64 s[18:19], s[20:21], exec
	s_mov_b32 s14, 0x5d00000
	s_cselect_b32 s16, s14, 0x5d10000
	v_lshl_add_u64 v[14:15], v[132:133], 0, s[16:17]
	global_load_dwordx4 v[18:21], v[14:15], off
	global_load_dwordx4 v[22:25], v[14:15], off offset:64
	global_load_dwordx4 v[26:29], v[14:15], off offset:128
	global_load_dwordx4 v[30:33], v[14:15], off offset:192
	global_load_dwordx4 v[34:37], v[14:15], off offset:256
	global_load_dwordx4 v[38:41], v[14:15], off offset:320
	global_load_dwordx4 v[42:45], v[14:15], off offset:384
	global_load_dwordx4 v[46:49], v[14:15], off offset:448
	ds_read_b128 v[50:53], v229 offset:36864
	ds_read_b128 v[54:57], v229 offset:36928
	ds_read_b128 v[58:61], v229 offset:36992
	ds_read_b128 v[62:65], v229 offset:37056
	ds_read_b128 v[66:69], v229 offset:37120
	ds_read_b128 v[70:73], v229 offset:37184
	ds_read_b128 v[74:77], v229 offset:37248
	ds_read_b128 v[78:81], v229 offset:37312
	s_mov_b32 s14, 0x5e00000
	s_cselect_b32 s20, s14, 0x5e40000
	s_mov_b32 s21, s17
	s_lshl_b32 s4, s4, 15
	s_waitcnt vmcnt(7) lgkmcnt(7)
	v_mfma_f32_16x16x32_bf16 v[2:5], v[50:53], v[18:21], 0
	s_waitcnt vmcnt(6) lgkmcnt(6)
	v_mfma_f32_16x16x32_bf16 v[2:5], v[54:57], v[22:25], v[2:5]
	s_waitcnt vmcnt(5) lgkmcnt(5)
	v_mfma_f32_16x16x32_bf16 v[2:5], v[58:61], v[26:29], v[2:5]
	s_waitcnt vmcnt(4) lgkmcnt(4)
	v_mfma_f32_16x16x32_bf16 v[2:5], v[62:65], v[30:33], v[2:5]
	s_waitcnt vmcnt(3) lgkmcnt(3)
	v_mfma_f32_16x16x32_bf16 v[2:5], v[66:69], v[34:37], v[2:5]
	s_waitcnt vmcnt(2) lgkmcnt(2)
	v_mfma_f32_16x16x32_bf16 v[2:5], v[70:73], v[38:41], v[2:5]
	s_waitcnt vmcnt(1) lgkmcnt(1)
	v_mfma_f32_16x16x32_bf16 v[2:5], v[74:77], v[42:45], v[2:5]
	s_waitcnt vmcnt(0) lgkmcnt(0)
	v_mfma_f32_16x16x32_bf16 v[2:5], v[78:81], v[46:49], v[2:5]
	v_lshl_or_b32 v8, s5, 4, v216
	v_lshl_add_u64 v[6:7], v[134:135], 0, s[20:21]
	v_lshl_or_b32 v0, v8, 7, s4
	v_lshl_add_u64 v[6:7], v[6:7], 0, v[0:1]
	s_nop 3
	v_cvt_pk_bf16_f32 v0, v3, s0
	global_store_short v[6:7], v0, off offset:128
	v_cvt_pk_bf16_f32 v0, v4, s0
	s_movk_i32 s4, 0xfc
	global_store_short v[6:7], v0, off offset:256
	v_cvt_pk_bf16_f32 v0, v5, s0
	v_cmp_ne_u32_e32 vcc, s4, v8
	v_cvt_pk_bf16_f32 v2, v2, s0
	global_store_short v[6:7], v2, off
	v_cndmask_b32_e32 v0, 0, v0, vcc
	global_store_short v[6:7], v0, off offset:384
